# GEMM k-loops: back edge rotated so the loop-back branch is taken before the barrier (barrier is the loop head; exit path has its own barrier copy)
# baseline (speedup 1.0000x reference)
; #define LAS __attribute__((address_space(3)))
; template <bool RSTD, bool SWAP>
; DI void gemm_tile(gacc_t& acc, const bf16_t* __restrict__ A, int lda, const bf16_t* __restrict__ Bt, int ldb, int K,
;                   char* lds, int tid, int wr, int wc, int lane, const float* ssq_row) {
; #pragma unroll
;     for (int m = 0; m < 8; ++m)
; #pragma unroll
;         for (int n = 0; n < 4; ++n)
; #pragma unroll
;             for (int j = 0; j < 4; ++j) acc[m][n][j] = 0.f;
;     const int nk = K / 64;
;     const int fr = lane & 15, fq = lane >> 4;
;     const int srow = tid >> 3, sch = tid & 7;
;     const int cl = sch ^ ((srow >> 1) & 7);
;     const int wv = __builtin_amdgcn_readfirstlane(tid >> 6);
;     const bf16_t* ap = A + (long)srow * lda + cl * 8;
;     const bf16_t* bp = Bt + (long)srow * ldb + cl * 8;
;     LAS char* l3 = (LAS char*)lds;
;     ...
;     GEMM_ISSUE(0, 0);
;     if (RSTD && tid < 256) {
;         const f32x4 q = *(const f32x4*)ssq_row;
;         ((float*)(lds + RSTD_OFF))[tid] = 1.0f / sqrtf(((q.x + q.y) + (q.z + q.w)) * (1.0f / 1024.0f) + 1e-6f);
;     }
;     asm volatile("s_waitcnt vmcnt(0)" ::: "memory");
;     __syncthreads();
;     for (int kt = 0; kt < nk; ++kt) {
;         const char* cur = lds + (kt & 1) * 65536;
;         if (kt + 1 < nk) GEMM_ISSUE(kt + 1, (kt + 1) & 1);
.LBB0_140:
	s_or_b64 exec, exec, s[34:35]
	s_sub_i32 s6, s37, s42
	s_sub_i32 s6, s6, s39
	s_sext_i32_i8 s6, s6
	s_waitcnt vmcnt(0)
	s_add_i32 s6, s38, s6
	s_ashr_i32 s7, s6, 31
	s_lshl_b64 s[6:7], s[6:7], 19
	v_mov_b32_e32 v0, 0
	s_lshl_b32 s17, s18, 24
	v_mov_b32_e32 v210, 0
	v_mov_b32_e32 v211, 0
	v_mov_b32_e32 v212, 0
	v_mov_b32_e32 v213, 0
	v_mov_b32_e32 v214, 0
	v_mov_b32_e32 v215, 0
	v_mov_b32_e32 v216, 0
	v_mov_b32_e32 v217, 0
	v_mov_b32_e32 v218, 0
	v_mov_b32_e32 v219, 0
	v_mov_b32_e32 v220, 0
	v_mov_b32_e32 v221, 0
	v_mov_b32_e32 v222, 0
	v_mov_b32_e32 v223, 0
	v_mov_b32_e32 v224, 0
	v_mov_b32_e32 v225, 0
	v_mov_b32_e32 v236, 0
	v_mov_b32_e32 v237, 0
	v_mov_b32_e32 v238, 0
	v_mov_b32_e32 v239, 0
	v_mov_b32_e32 v240, 0
	v_mov_b32_e32 v241, 0
	v_mov_b32_e32 v242, 0
	v_mov_b32_e32 v243, 0
	v_mov_b32_e32 v244, 0
	v_mov_b32_e32 v245, 0
	v_mov_b32_e32 v246, 0
	v_mov_b32_e32 v247, 0
	v_mov_b32_e32 v248, 0
	v_mov_b32_e32 v249, 0
	v_mov_b32_e32 v250, 0
	v_mov_b32_e32 v251, 0
	s_waitcnt vmcnt(0) lgkmcnt(0)
	v_lshl_add_u64 v[136:137], v[132:133], 0, s[30:31]
	v_lshl_add_u64 v[138:139], v[134:135], 0, s[6:7]
	s_mov_b64 s[6:7], 0
	s_mov_b32 s21, 0x10000
	v_mov_b32_e32 v1, v0
	v_mov_b32_e32 v2, v0
	v_mov_b32_e32 v3, v0
	v_mov_b32_e32 v4, v0
	v_mov_b32_e32 v5, v0
	v_mov_b32_e32 v6, v0
	v_mov_b32_e32 v7, v0
	v_mov_b32_e32 v8, v0
	v_mov_b32_e32 v9, v0
	v_mov_b32_e32 v10, v0
	v_mov_b32_e32 v11, v0
	v_mov_b32_e32 v12, v0
	v_mov_b32_e32 v13, v0
	v_mov_b32_e32 v14, v0
	v_mov_b32_e32 v15, v0
	v_mov_b32_e32 v16, v0
	v_mov_b32_e32 v17, v0
	v_mov_b32_e32 v18, v0
	v_mov_b32_e32 v19, v0
	v_mov_b32_e32 v20, v0
	v_mov_b32_e32 v21, v0
	v_mov_b32_e32 v22, v0
	v_mov_b32_e32 v23, v0
	v_mov_b32_e32 v24, v0
	v_mov_b32_e32 v25, v0
	v_mov_b32_e32 v26, v0
	v_mov_b32_e32 v27, v0
	v_mov_b32_e32 v28, v0
	v_mov_b32_e32 v29, v0
	v_mov_b32_e32 v30, v0
	v_mov_b32_e32 v31, v0
	v_mov_b32_e32 v32, v0
	v_mov_b32_e32 v33, v0
	v_mov_b32_e32 v34, v0
	v_mov_b32_e32 v35, v0
	v_mov_b32_e32 v36, v0
	v_mov_b32_e32 v37, v0
	v_mov_b32_e32 v38, v0
	v_mov_b32_e32 v39, v0
	v_mov_b32_e32 v40, v0
	v_mov_b32_e32 v41, v0
	v_mov_b32_e32 v42, v0
	v_mov_b32_e32 v43, v0
	v_mov_b32_e32 v44, v0
	v_mov_b32_e32 v45, v0
	v_mov_b32_e32 v46, v0
	v_mov_b32_e32 v47, v0
	v_mov_b32_e32 v48, v0
	v_mov_b32_e32 v49, v0
	v_mov_b32_e32 v50, v0
	v_mov_b32_e32 v51, v0
	v_mov_b32_e32 v52, v0
	v_mov_b32_e32 v53, v0
	v_mov_b32_e32 v54, v0
	v_mov_b32_e32 v55, v0
	v_mov_b32_e32 v56, v0
	v_mov_b32_e32 v57, v0
	v_mov_b32_e32 v58, v0
	v_mov_b32_e32 v59, v0
	v_mov_b32_e32 v60, v0
	v_mov_b32_e32 v61, v0
	v_mov_b32_e32 v62, v0
	v_mov_b32_e32 v63, v0
	v_mov_b32_e32 v64, v0
	v_mov_b32_e32 v65, v0
	v_mov_b32_e32 v66, v0
	v_mov_b32_e32 v67, v0
	v_mov_b32_e32 v68, v0
	v_mov_b32_e32 v69, v0
	v_mov_b32_e32 v70, v0
	v_mov_b32_e32 v71, v0
	v_mov_b32_e32 v72, v0
	v_mov_b32_e32 v73, v0
	v_mov_b32_e32 v74, v0
	v_mov_b32_e32 v75, v0
	v_mov_b32_e32 v76, v0
	v_mov_b32_e32 v77, v0
	v_mov_b32_e32 v78, v0
	v_mov_b32_e32 v79, v0
	v_mov_b32_e32 v80, v0
	v_mov_b32_e32 v81, v0
	v_mov_b32_e32 v82, v0
	v_mov_b32_e32 v83, v0
	v_mov_b32_e32 v84, v0
	v_mov_b32_e32 v85, v0
	v_mov_b32_e32 v86, v0
	v_mov_b32_e32 v87, v0
	v_mov_b32_e32 v88, v0
	v_mov_b32_e32 v89, v0
	v_mov_b32_e32 v90, v0
	v_mov_b32_e32 v91, v0
	v_mov_b32_e32 v92, v0
	v_mov_b32_e32 v93, v0
	v_mov_b32_e32 v94, v0
	v_mov_b32_e32 v95, v0
	v_mov_b32_e32 v96, v0
	v_mov_b32_e32 v97, v0
	v_mov_b32_e32 v98, v0
	v_mov_b32_e32 v99, v0
	v_mov_b32_e32 v100, v0
	v_mov_b32_e32 v101, v0
	v_mov_b32_e32 v102, v0
	v_mov_b32_e32 v103, v0
	v_mov_b32_e32 v104, v0
	v_mov_b32_e32 v105, v0
	v_mov_b32_e32 v106, v0
	v_mov_b32_e32 v107, v0
	v_mov_b32_e32 v108, v0
	v_mov_b32_e32 v109, v0
	v_mov_b32_e32 v110, v0
	v_mov_b32_e32 v111, v0
	v_mov_b32_e32 v112, v0
	v_mov_b32_e32 v113, v0
	v_mov_b32_e32 v114, v0
	v_mov_b32_e32 v115, v0
	v_mov_b32_e32 v116, v0
	v_mov_b32_e32 v117, v0
	v_mov_b32_e32 v118, v0
	v_mov_b32_e32 v119, v0
	v_mov_b32_e32 v120, v0
	v_mov_b32_e32 v121, v0
	v_mov_b32_e32 v122, v0
	v_mov_b32_e32 v123, v0
	v_mov_b32_e32 v124, v0
	v_mov_b32_e32 v125, v0
	v_mov_b32_e32 v126, v0
	v_mov_b32_e32 v127, v0
.Lkhead_141:
	s_barrier
.LBB0_141:
	s_add_i32 s30, s21, 0xffff0000
	s_and_b32 s31, s21, 0x10000
	v_lshl_add_u64 v[164:165], v[136:137], 0, s[6:7]
	s_and_b32 s34, s30, 0x10000
	s_add_i32 s35, s19, s31
	s_mov_b64 s[30:31], 0xc80080
	v_lshl_add_u64 v[172:173], v[164:165], 0, s[30:31]
	s_mov_b64 s[30:31], 0xca0080
	v_lshl_add_u64 v[176:177], v[164:165], 0, s[30:31]
	s_mov_b64 s[30:31], 0xcc0080
	v_lshl_add_u64 v[162:163], v[138:139], 0, s[6:7]
	v_lshl_add_u64 v[180:181], v[164:165], 0, s[30:31]
	s_mov_b64 s[30:31], 0xce0080
	v_lshl_add_u64 v[166:167], v[162:163], 0, s[94:95]
	v_lshl_add_u64 v[164:165], v[164:165], 0, s[30:31]
	s_add_i32 s31, s35, 0x8000
	s_mov_b32 m0, s35
	v_lshl_add_u64 v[174:175], v[162:163], 0, s[96:97]
	global_load_lds_dwordx4 v[166:167], off
	v_mfma_f32_16x16x32_bf16 v[60:63], v[210:213], v[236:239], v[60:63]
	s_mov_b32 m0, s31
	v_lshl_add_u64 v[178:179], v[162:163], 0, s[80:81]
	global_load_lds_dwordx4 v[172:173], off
	v_mfma_f32_16x16x32_bf16 v[56:59], v[214:217], v[236:239], v[56:59]
	s_add_i32 m0, s35, 0x2000
	v_lshl_add_u64 v[162:163], v[162:163], 0, s[82:83]
	global_load_lds_dwordx4 v[174:175], off
	v_mfma_f32_16x16x32_bf16 v[52:55], v[218:221], v[236:239], v[52:55]
	s_add_i32 m0, s35, 0xa000
	s_add_i32 s30, s34, 0
	global_load_lds_dwordx4 v[176:177], off
	v_mfma_f32_16x16x32_bf16 v[48:51], v[222:225], v[236:239], v[48:51]
	s_add_i32 m0, s35, 0x4000
	v_add_u32_e32 v146, s30, v143
	global_load_lds_dwordx4 v[178:179], off
	v_mfma_f32_16x16x32_bf16 v[44:47], v[210:213], v[240:243], v[44:47]
	s_add_i32 m0, s35, 0xc000
	v_add3_u32 v161, v146, v149, v150
	global_load_lds_dwordx4 v[180:181], off
	v_mfma_f32_16x16x32_bf16 v[40:43], v[214:217], v[240:243], v[40:43]
	s_add_i32 m0, s35, 0x6000
	v_add_u32_e32 v166, v146, v145
	global_load_lds_dwordx4 v[162:163], off
	v_mfma_f32_16x16x32_bf16 v[36:39], v[218:221], v[240:243], v[36:39]
	s_add_i32 m0, s35, 0xe000
	s_nop 0
	global_load_lds_dwordx4 v[164:165], off
	v_mfma_f32_16x16x32_bf16 v[32:35], v[222:225], v[240:243], v[32:35]
	ds_read_b128 v[162:165], v161 offset:32768
	ds_read_b128 v[186:189], v161 offset:34816
	ds_read_b128 v[194:197], v161 offset:36864
	ds_read_b128 v[198:201], v161 offset:38912
	ds_read_b128 v[190:193], v166
	ds_read_b128 v[202:205], v166 offset:2048
	v_add_u32_e32 v161, v146, v151
	ds_read_b128 v[206:209], v166 offset:4096
	v_mfma_f32_16x16x32_bf16 v[28:31], v[210:213], v[244:247], v[28:31]
	v_mfma_f32_16x16x32_bf16 v[24:27], v[214:217], v[244:247], v[24:27]
	v_mfma_f32_16x16x32_bf16 v[20:23], v[218:221], v[244:247], v[20:23]
	v_mfma_f32_16x16x32_bf16 v[16:19], v[222:225], v[244:247], v[16:19]
	v_mfma_f32_16x16x32_bf16 v[12:15], v[210:213], v[248:251], v[12:15]
	v_mfma_f32_16x16x32_bf16 v[8:11], v[214:217], v[248:251], v[8:11]
	v_mfma_f32_16x16x32_bf16 v[4:7], v[218:221], v[248:251], v[4:7]
	v_mfma_f32_16x16x32_bf16 v[0:3], v[222:225], v[248:251], v[0:3]
	s_waitcnt lgkmcnt(2)
; #define MFMA16(a, b, c) __builtin_amdgcn_mfma_f32_16x16x32_bf16((a), (b), (c), 0, 0, 0)
; DI bf16x8 ldfrag(const char* lds, int row, int chunk) { return *(const bf16x8*)(lds + swz(row, chunk)); }
; #define GEMM_SG1() do { __builtin_amdgcn_sched_group_barrier(0x100, 1, 0); __builtin_amdgcn_sched_group_barrier(0x008, 4, 0); } while (0)
; #define GEMM_SG2() do { __builtin_amdgcn_sched_group_barrier(0x100, 2, 0); __builtin_amdgcn_sched_group_barrier(0x008, 4, 0); } while (0)
; template <bool RSTD, bool SWAP>
; DI void gemm_tile(gacc_t& acc, const bf16_t* __restrict__ A, int lda, const bf16_t* __restrict__ Bt, int ldb, int K,
;                   char* lds, int tid, int wr, int wc, int lane, const float* ssq_row) {
;     ...
;         for (int n = 0; n < 4; ++n) bfr[0][n] = ldfrag(cur + 32768, wc * 64 + n * 16 + fr, fq);
;         afr[0] = ldfrag(cur, wr * 128 + fr, fq);
;         afr[1] = ldfrag(cur, wr * 128 + 16 + fr, fq);
; #pragma unroll
;         for (int idx = 0; idx < 16; ++idx) {
;             const int ks = idx >> 3, m = idx & 7;
;             if (idx < 14) afr[(idx + 2) % 3] = ldfrag(cur, wr * 128 + ((idx + 2) & 7) * 16 + fr, ((idx + 2) >> 3) * 4 + fq);
;             if (ks == 0 && m >= 2 && m < 6) bfr[1][m - 2] = ldfrag(cur + 32768, wc * 64 + (m - 2) * 16 + fr, 4 + fq);
; #pragma unroll
;             for (int n = 0; n < 4; ++n) acc[m][n] = SWAP ? MFMA16(bfr[ks][n], afr[idx % 3], acc[m][n]) : MFMA16(afr[idx % 3], bfr[ks][n], acc[m][n]);
;         }
;         __builtin_amdgcn_sched_group_barrier(0x100, 6, 0);
;     ...
;         GEMM_SG1(); GEMM_SG1(); GEMM_SG2(); GEMM_SG2(); GEMM_SG2(); GEMM_SG2(); GEMM_SG1(); GEMM_SG1();
;         GEMM_SG1(); GEMM_SG1(); GEMM_SG1(); GEMM_SG1(); GEMM_SG1(); GEMM_SG1();
;         __builtin_amdgcn_sched_group_barrier(0x008, 8, 0);
;         __builtin_amdgcn_sched_barrier(0);
;         asm volatile("s_waitcnt vmcnt(0)" ::: "memory");
;         __syncthreads();
	v_mfma_f32_16x16x32_bf16 v[124:127], v[162:165], v[190:193], v[124:127]
	v_add_u32_e32 v146, v146, v153
	v_mfma_f32_16x16x32_bf16 v[120:123], v[186:189], v[190:193], v[120:123]
	v_mfma_f32_16x16x32_bf16 v[116:119], v[194:197], v[190:193], v[116:119]
	v_mfma_f32_16x16x32_bf16 v[112:115], v[198:201], v[190:193], v[112:115]
	ds_read_b128 v[190:193], v161
	v_add_u32_e32 v161, s30, v148
	v_add_u32_e32 v167, v161, v152
	s_waitcnt lgkmcnt(2)
	v_mfma_f32_16x16x32_bf16 v[108:111], v[162:165], v[202:205], v[108:111]
	v_mfma_f32_16x16x32_bf16 v[104:107], v[186:189], v[202:205], v[104:107]
	v_mfma_f32_16x16x32_bf16 v[100:103], v[194:197], v[202:205], v[100:103]
	v_mfma_f32_16x16x32_bf16 v[96:99], v[198:201], v[202:205], v[96:99]
	ds_read_b128 v[202:205], v166 offset:8192
	ds_read_b128 v[210:213], v167 offset:32768
	s_waitcnt lgkmcnt(3)
	v_mfma_f32_16x16x32_bf16 v[92:95], v[162:165], v[206:209], v[92:95]
	v_mfma_f32_16x16x32_bf16 v[88:91], v[186:189], v[206:209], v[88:91]
	v_mfma_f32_16x16x32_bf16 v[84:87], v[194:197], v[206:209], v[84:87]
	v_mfma_f32_16x16x32_bf16 v[80:83], v[198:201], v[206:209], v[80:83]
	ds_read_b128 v[206:209], v166 offset:10240
	ds_read_b128 v[214:217], v167 offset:34816
	s_waitcnt lgkmcnt(4)
	v_mfma_f32_16x16x32_bf16 v[76:79], v[162:165], v[190:193], v[76:79]
	v_mfma_f32_16x16x32_bf16 v[72:75], v[186:189], v[190:193], v[72:75]
	v_mfma_f32_16x16x32_bf16 v[68:71], v[194:197], v[190:193], v[68:71]
	v_mfma_f32_16x16x32_bf16 v[64:67], v[198:201], v[190:193], v[64:67]
	ds_read_b128 v[190:193], v166 offset:12288
	v_add_u32_e32 v166, v161, v154
	ds_read_b128 v[218:221], v167 offset:36864
	s_waitcnt lgkmcnt(5)
	v_mfma_f32_16x16x32_bf16 v[60:63], v[162:165], v[202:205], v[60:63]
	v_mfma_f32_16x16x32_bf16 v[56:59], v[186:189], v[202:205], v[56:59]
	v_mfma_f32_16x16x32_bf16 v[52:55], v[194:197], v[202:205], v[52:55]
	v_mfma_f32_16x16x32_bf16 v[48:51], v[198:201], v[202:205], v[48:51]
	ds_read_b128 v[222:225], v166 offset:38912
	ds_read_b128 v[202:205], v146
	v_add_u32_e32 v146, v161, v145
	s_waitcnt lgkmcnt(5)
	v_mfma_f32_16x16x32_bf16 v[44:47], v[162:165], v[206:209], v[44:47]
	v_add_u32_e32 v166, v161, v151
	v_mfma_f32_16x16x32_bf16 v[40:43], v[186:189], v[206:209], v[40:43]
	v_mfma_f32_16x16x32_bf16 v[36:39], v[194:197], v[206:209], v[36:39]
	v_mfma_f32_16x16x32_bf16 v[32:35], v[198:201], v[206:209], v[32:35]
	ds_read_b128 v[206:209], v146
	s_waitcnt lgkmcnt(4)
	v_mfma_f32_16x16x32_bf16 v[28:31], v[162:165], v[190:193], v[28:31]
	v_mfma_f32_16x16x32_bf16 v[24:27], v[186:189], v[190:193], v[24:27]
	v_mfma_f32_16x16x32_bf16 v[20:23], v[194:197], v[190:193], v[20:23]
	v_mfma_f32_16x16x32_bf16 v[16:19], v[198:201], v[190:193], v[16:19]
	ds_read_b128 v[190:193], v146 offset:2048
	s_waitcnt lgkmcnt(2)
	v_mfma_f32_16x16x32_bf16 v[12:15], v[162:165], v[202:205], v[12:15]
	v_mfma_f32_16x16x32_bf16 v[8:11], v[186:189], v[202:205], v[8:11]
	v_mfma_f32_16x16x32_bf16 v[4:7], v[194:197], v[202:205], v[4:7]
	v_mfma_f32_16x16x32_bf16 v[0:3], v[198:201], v[202:205], v[0:3]
	ds_read_b128 v[162:165], v146 offset:4096
	s_waitcnt lgkmcnt(2)
	v_mfma_f32_16x16x32_bf16 v[124:127], v[210:213], v[206:209], v[124:127]
	v_mfma_f32_16x16x32_bf16 v[120:123], v[214:217], v[206:209], v[120:123]
	v_mfma_f32_16x16x32_bf16 v[116:119], v[218:221], v[206:209], v[116:119]
	v_mfma_f32_16x16x32_bf16 v[112:115], v[222:225], v[206:209], v[112:115]
	ds_read_b128 v[186:189], v166
	s_waitcnt lgkmcnt(2)
	v_mfma_f32_16x16x32_bf16 v[108:111], v[210:213], v[190:193], v[108:111]
	v_mfma_f32_16x16x32_bf16 v[104:107], v[214:217], v[190:193], v[104:107]
	v_mfma_f32_16x16x32_bf16 v[100:103], v[218:221], v[190:193], v[100:103]
	v_mfma_f32_16x16x32_bf16 v[96:99], v[222:225], v[190:193], v[96:99]
	ds_read_b128 v[236:239], v146 offset:8192
	s_waitcnt lgkmcnt(2)
	v_mfma_f32_16x16x32_bf16 v[92:95], v[210:213], v[162:165], v[92:95]
	v_mfma_f32_16x16x32_bf16 v[88:91], v[214:217], v[162:165], v[88:91]
	v_mfma_f32_16x16x32_bf16 v[84:87], v[218:221], v[162:165], v[84:87]
	v_mfma_f32_16x16x32_bf16 v[80:83], v[222:225], v[162:165], v[80:83]
	ds_read_b128 v[240:243], v146 offset:10240
	ds_read_b128 v[244:247], v146 offset:12288
	v_add_u32_e32 v146, v161, v153
	ds_read_b128 v[248:251], v146
	s_waitcnt lgkmcnt(4)
	v_mfma_f32_16x16x32_bf16 v[76:79], v[210:213], v[186:189], v[76:79]
	v_mfma_f32_16x16x32_bf16 v[72:75], v[214:217], v[186:189], v[72:75]
	v_mfma_f32_16x16x32_bf16 v[68:71], v[218:221], v[186:189], v[68:71]
	v_mfma_f32_16x16x32_bf16 v[64:67], v[222:225], v[186:189], v[64:67]
	s_waitcnt lgkmcnt(0)
	s_waitcnt vmcnt(0)
	s_add_u32 s6, s6, 0x80
	s_addc_u32 s7, s7, 0
	s_add_i32 s21, s21, 0x10000
	s_cmpk_lg_i32 s6, 0x780
	s_waitcnt vmcnt(0)
	s_cbranch_scc1 .Lkhead_141
	s_barrier
; #define MFMA16(a, b, c) __builtin_amdgcn_mfma_f32_16x16x32_bf16((a), (b), (c), 0, 0, 0)
; DI bf16x8 ldfrag(const char* lds, int row, int chunk) { return *(const bf16x8*)(lds + swz(row, chunk)); }
; template <bool RSTD, bool SWAP>
; DI void gemm_tile(gacc_t& acc, const bf16_t* __restrict__ A, int lda, const bf16_t* __restrict__ Bt, int ldb, int K,
;                   char* lds, int tid, int wr, int wc, int lane, const float* ssq_row) {
;     ...
;         for (int n = 0; n < 4; ++n) bfr[0][n] = ldfrag(cur + 32768, wc * 64 + n * 16 + fr, fq);
;         afr[0] = ldfrag(cur, wr * 128 + fr, fq);
;         afr[1] = ldfrag(cur, wr * 128 + 16 + fr, fq);
; #pragma unroll
;         for (int idx = 0; idx < 16; ++idx) {
;             const int ks = idx >> 3, m = idx & 7;
;             if (idx < 14) afr[(idx + 2) % 3] = ldfrag(cur, wr * 128 + ((idx + 2) & 7) * 16 + fr, ((idx + 2) >> 3) * 4 + fq);
;             if (ks == 0 && m >= 2 && m < 6) bfr[1][m - 2] = ldfrag(cur + 32768, wc * 64 + (m - 2) * 16 + fr, 4 + fq);
; #pragma unroll
;             for (int n = 0; n < 4; ++n) acc[m][n] = SWAP ? MFMA16(bfr[ks][n], afr[idx % 3], acc[m][n]) : MFMA16(afr[idx % 3], bfr[ks][n], acc[m][n]);
	v_mfma_f32_16x16x32_bf16 v[60:63], v[210:213], v[236:239], v[60:63]
	v_mfma_f32_16x16x32_bf16 v[56:59], v[214:217], v[236:239], v[56:59]
	v_mfma_f32_16x16x32_bf16 v[52:55], v[218:221], v[236:239], v[52:55]
	v_mfma_f32_16x16x32_bf16 v[48:51], v[222:225], v[236:239], v[48:51]
	v_mfma_f32_16x16x32_bf16 v[44:47], v[210:213], v[240:243], v[44:47]
	v_mfma_f32_16x16x32_bf16 v[40:43], v[214:217], v[240:243], v[40:43]
	v_mfma_f32_16x16x32_bf16 v[36:39], v[218:221], v[240:243], v[36:39]
	v_mfma_f32_16x16x32_bf16 v[32:35], v[222:225], v[240:243], v[32:35]
	v_mfma_f32_16x16x32_bf16 v[28:31], v[210:213], v[244:247], v[28:31]
	v_mfma_f32_16x16x32_bf16 v[24:27], v[214:217], v[244:247], v[24:27]
	v_mfma_f32_16x16x32_bf16 v[20:23], v[218:221], v[244:247], v[20:23]
	v_mfma_f32_16x16x32_bf16 v[16:19], v[222:225], v[244:247], v[16:19]
	v_mfma_f32_16x16x32_bf16 v[12:15], v[210:213], v[248:251], v[12:15]
	v_mfma_f32_16x16x32_bf16 v[8:11], v[214:217], v[248:251], v[8:11]
	v_mfma_f32_16x16x32_bf16 v[4:7], v[218:221], v[248:251], v[4:7]
	v_mfma_f32_16x16x32_bf16 v[0:3], v[222:225], v[248:251], v[0:3]
	ds_read_b128 v[136:139], v160
	ds_read_b128 v[162:165], v160 offset:2048
	ds_read_b128 v[190:193], v160 offset:4096
	ds_read_b128 v[194:197], v160 offset:6144
	v_add_u32_e32 v146, v155, v145
	ds_read_b128 v[186:189], v146
	ds_read_b128 v[198:201], v146 offset:2048
	ds_read_b128 v[202:205], v146 offset:4096
	s_waitcnt lgkmcnt(2)
	v_mfma_f32_16x16x32_bf16 v[124:127], v[136:139], v[186:189], v[124:127]
	v_mfma_f32_16x16x32_bf16 v[206:209], v[162:165], v[186:189], v[120:123]
	v_mfma_f32_16x16x32_bf16 v[116:119], v[190:193], v[186:189], v[116:119]
	v_mfma_f32_16x16x32_bf16 v[186:189], v[194:197], v[186:189], v[112:115]
	s_nop 2
	v_add_u32_e32 v112, v155, v151
	ds_read_b128 v[112:115], v112
	s_waitcnt lgkmcnt(2)
	v_mfma_f32_16x16x32_bf16 v[108:111], v[136:139], v[198:201], v[108:111]
	v_mfma_f32_16x16x32_bf16 v[210:213], v[162:165], v[198:201], v[104:107]
	v_mfma_f32_16x16x32_bf16 v[100:103], v[190:193], v[198:201], v[100:103]
	s_nop 1
	v_add_u32_e32 v104, v156, v152
	v_mfma_f32_16x16x32_bf16 v[198:201], v[194:197], v[198:201], v[96:99]
	ds_read_b128 v[214:217], v104
	s_nop 1
	ds_read_b128 v[96:99], v146 offset:8192
	s_waitcnt lgkmcnt(3)
	v_mfma_f32_16x16x32_bf16 v[92:95], v[136:139], v[202:205], v[92:95]
	v_mfma_f32_16x16x32_bf16 v[218:221], v[162:165], v[202:205], v[88:91]
	v_mfma_f32_16x16x32_bf16 v[84:87], v[190:193], v[202:205], v[84:87]
	v_mfma_f32_16x16x32_bf16 v[202:205], v[194:197], v[202:205], v[80:83]
	ds_read_b128 v[222:225], v104 offset:2048
	s_nop 1
	ds_read_b128 v[80:83], v146 offset:10240
	s_waitcnt lgkmcnt(4)
	v_mfma_f32_16x16x32_bf16 v[76:79], v[136:139], v[112:115], v[76:79]
	v_mfma_f32_16x16x32_bf16 v[226:229], v[162:165], v[112:115], v[72:75]
	v_mfma_f32_16x16x32_bf16 v[68:71], v[190:193], v[112:115], v[68:71]
	v_mfma_f32_16x16x32_bf16 v[230:233], v[194:197], v[112:115], v[64:67]
	ds_read_b128 v[234:237], v104 offset:4096
	s_nop 1
	ds_read_b128 v[64:67], v146 offset:12288
	s_waitcnt lgkmcnt(4)
	v_mfma_f32_16x16x32_bf16 v[238:241], v[162:165], v[96:99], v[56:59]
	v_mfma_f32_16x16x32_bf16 v[60:63], v[136:139], v[96:99], v[60:63]
	s_nop 1
	v_add_u32_e32 v56, v156, v154
	v_mfma_f32_16x16x32_bf16 v[52:55], v[190:193], v[96:99], v[52:55]
	v_mfma_f32_16x16x32_bf16 v[242:245], v[194:197], v[96:99], v[48:51]
	ds_read_b128 v[246:249], v56 offset:6144
	s_nop 1
	v_add_u32_e32 v48, v155, v153
	ds_read_b128 v[48:51], v48
	s_waitcnt lgkmcnt(4)
	v_mfma_f32_16x16x32_bf16 v[250:253], v[162:165], v[80:83], v[40:43]
	v_mfma_f32_16x16x32_bf16 v[44:47], v[136:139], v[80:83], v[44:47]
	s_nop 1
	v_add_u32_e32 v40, v157, v145
	v_mfma_f32_16x16x32_bf16 v[36:39], v[190:193], v[80:83], v[36:39]
	v_mfma_f32_16x16x32_bf16 v[172:175], v[194:197], v[80:83], v[32:35]
	s_nop 2
	ds_read_b128 v[32:35], v40
	s_waitcnt lgkmcnt(3)
	v_mfma_f32_16x16x32_bf16 v[28:31], v[136:139], v[64:67], v[28:31]
	v_mfma_f32_16x16x32_bf16 v[176:179], v[162:165], v[64:67], v[24:27]
	v_mfma_f32_16x16x32_bf16 v[20:23], v[190:193], v[64:67], v[20:23]
	v_mfma_f32_16x16x32_bf16 v[180:183], v[194:197], v[64:67], v[16:19]
	s_nop 2
	ds_read_b128 v[16:19], v40 offset:2048
	s_waitcnt lgkmcnt(2)
	v_mfma_f32_16x16x32_bf16 v[12:15], v[136:139], v[48:51], v[12:15]
	v_mfma_f32_16x16x32_bf16 v[136:139], v[162:165], v[48:51], v[8:11]
	s_nop 2
	v_add_u32_e32 v8, v157, v151
	v_mfma_f32_16x16x32_bf16 v[4:7], v[190:193], v[48:51], v[4:7]
	v_mfma_f32_16x16x32_bf16 v[162:165], v[194:197], v[48:51], v[0:3]
	s_nop 2
	ds_read_b128 v[0:3], v40 offset:4096
	s_waitcnt lgkmcnt(2)
	v_mfma_f32_16x16x32_bf16 v[120:123], v[214:217], v[32:35], v[124:127]
	v_mfma_f32_16x16x32_bf16 v[112:115], v[222:225], v[32:35], v[206:209]
	v_mfma_f32_16x16x32_bf16 v[124:127], v[234:237], v[32:35], v[116:119]
	v_mfma_f32_16x16x32_bf16 v[116:119], v[246:249], v[32:35], v[186:189]
	ds_read_b128 v[8:11], v8
	s_waitcnt lgkmcnt(2)
	v_mfma_f32_16x16x32_bf16 v[104:107], v[214:217], v[16:19], v[108:111]
	v_mfma_f32_16x16x32_bf16 v[96:99], v[222:225], v[16:19], v[210:213]
	v_mfma_f32_16x16x32_bf16 v[108:111], v[234:237], v[16:19], v[100:103]
	v_mfma_f32_16x16x32_bf16 v[100:103], v[246:249], v[16:19], v[198:201]
	ds_read_b128 v[16:19], v40 offset:8192
	s_waitcnt lgkmcnt(2)
	v_mfma_f32_16x16x32_bf16 v[88:91], v[214:217], v[0:3], v[92:95]
	v_mfma_f32_16x16x32_bf16 v[80:83], v[222:225], v[0:3], v[218:221]
	v_mfma_f32_16x16x32_bf16 v[92:95], v[234:237], v[0:3], v[84:87]
	v_mfma_f32_16x16x32_bf16 v[84:87], v[246:249], v[0:3], v[202:205]
	ds_read_b128 v[0:3], v40 offset:10240
	s_waitcnt lgkmcnt(2)
; template <bool RSTD, bool SWAP>
; DI void gemm_tile(gacc_t& acc, const bf16_t* __restrict__ A, int lda, const bf16_t* __restrict__ Bt, int ldb, int K,
;                   char* lds, int tid, int wr, int wc, int lane, const float* ssq_row) {
;     ...
;         for (int idx = 0; idx < 16; ++idx) {
;             const int ks = idx >> 3, m = idx & 7;
;             if (idx < 14) afr[(idx + 2) % 3] = ldfrag(cur, wr * 128 + ((idx + 2) & 7) * 16 + fr, ((idx + 2) >> 3) * 4 + fq);
;             if (ks == 0 && m >= 2 && m < 6) bfr[1][m - 2] = ldfrag(cur + 32768, wc * 64 + (m - 2) * 16 + fr, 4 + fq);
; #pragma unroll
;             for (int n = 0; n < 4; ++n) acc[m][n] = SWAP ? MFMA16(bfr[ks][n], afr[idx % 3], acc[m][n]) : MFMA16(afr[idx % 3], bfr[ks][n], acc[m][n]);
;         }
;         __builtin_amdgcn_sched_group_barrier(0x100, 6, 0);
;     ...
;         GEMM_SG1(); GEMM_SG1(); GEMM_SG2(); GEMM_SG2(); GEMM_SG2(); GEMM_SG2(); GEMM_SG1(); GEMM_SG1();
;         GEMM_SG1(); GEMM_SG1(); GEMM_SG1(); GEMM_SG1(); GEMM_SG1(); GEMM_SG1();
;         __builtin_amdgcn_sched_group_barrier(0x008, 8, 0);
;         __builtin_amdgcn_sched_barrier(0);
;         asm volatile("s_waitcnt vmcnt(0)" ::: "memory");
;         __syncthreads();
;     DI void operator()(gacc_t& acc, int pm, int pn, char* lds, int tid, int wr, int wc, int lane) const {
;         asm volatile("" : "+v"(tid), "+v"(lane));
;         const int fr = lane & 15, fq = lane >> 4;
;         const int R0 = pm * 256;
;         const int t0 = R0 < TP ? (R0 & ~4095) : TP + ((R0 - TP) & ~8191);
;         const int S = R0 < TP ? 4096 : 8192;
;         char* lbase = lds + (wr * 128 + fr) * 528 + (wc * 64 + 4 * fq) * 2;
;         const float* rlt = (const float*)(lds + RSTD_OFF) + wr * 128 + fr;
;         if (pn < 8) {
;             const float sc = pn < 4 ? 0.18033688011112042f : 1.0f;
;             const f32x2* rbase = rope + (R0 - t0 + wr * 128 + fr) * 32 + 4 * fq;
; #pragma unroll
;             for (int m = 0; m < 8; ++m) {
;                 const float rs = rlt[m * 16] * sc;
; #pragma unroll
;                 for (int n = 0; n < 2; ++n) {
;                     const f32x4 c01 = *(const f32x4*)(rbase + m * 16 * 32 + n * 16), c23 = *(const f32x4*)(rbase + m * 16 * 32 + n * 16 + 2);
;                     const float cs_[4] = {c01.x, c01.z, c23.x, c23.z}, sn_[4] = {c01.y, c01.w, c23.y, c23.w};
;                     float o1[4], o2[4];
	v_mfma_f32_16x16x32_bf16 v[72:75], v[214:217], v[8:11], v[76:79]
	v_mfma_f32_16x16x32_bf16 v[64:67], v[222:225], v[8:11], v[226:229]
	v_mfma_f32_16x16x32_bf16 v[76:79], v[234:237], v[8:11], v[68:71]
	v_mfma_f32_16x16x32_bf16 v[68:71], v[246:249], v[8:11], v[230:233]
	ds_read_b128 v[8:11], v40 offset:12288
	s_waitcnt lgkmcnt(2)
	v_mfma_f32_16x16x32_bf16 v[56:59], v[214:217], v[16:19], v[60:63]
	v_mfma_f32_16x16x32_bf16 v[48:51], v[222:225], v[16:19], v[238:241]
	v_mfma_f32_16x16x32_bf16 v[60:63], v[234:237], v[16:19], v[52:55]
	v_mfma_f32_16x16x32_bf16 v[52:55], v[246:249], v[16:19], v[242:245]
	v_add_u32_e32 v16, v157, v153
	ds_read_b128 v[186:189], v16
	s_waitcnt lgkmcnt(2)
	v_mfma_f32_16x16x32_bf16 v[40:43], v[214:217], v[0:3], v[44:47]
	v_mfma_f32_16x16x32_bf16 v[32:35], v[222:225], v[0:3], v[250:253]
	v_mfma_f32_16x16x32_bf16 v[44:47], v[234:237], v[0:3], v[36:39]
	v_mfma_f32_16x16x32_bf16 v[36:39], v[246:249], v[0:3], v[172:175]
	s_waitcnt lgkmcnt(1)
	v_mfma_f32_16x16x32_bf16 v[24:27], v[214:217], v[8:11], v[28:31]
	v_mfma_f32_16x16x32_bf16 v[16:19], v[222:225], v[8:11], v[176:179]
	v_mfma_f32_16x16x32_bf16 v[28:31], v[234:237], v[8:11], v[20:23]
	v_mfma_f32_16x16x32_bf16 v[20:23], v[246:249], v[8:11], v[180:183]
	s_waitcnt lgkmcnt(0)
	v_mfma_f32_16x16x32_bf16 v[8:11], v[214:217], v[186:189], v[12:15]
	v_mfma_f32_16x16x32_bf16 v[0:3], v[222:225], v[186:189], v[136:139]
	v_mfma_f32_16x16x32_bf16 v[12:15], v[234:237], v[186:189], v[4:7]
	v_mfma_f32_16x16x32_bf16 v[4:7], v[246:249], v[186:189], v[162:165]
	s_nop 0
	v_mov_b32_e32 v138, v140
	v_mov_b32_e32 v136, v141
	s_cmp_lt_i32 s20, 64
	s_waitcnt vmcnt(0)
	s_barrier
	s_cselect_b64 s[6:7], -1, 0
	v_and_b32_e32 v137, 15, v136
	s_and_b64 s[20:21], s[6:7], exec
	s_movk_i32 s19, 0xf000
	v_ashrrev_i32_e32 v136, 2, v136
	s_cselect_b32 s19, s19, 0x7fffe000
	v_or_b32_e32 v139, v137, v144
	v_and_b32_e32 v136, -4, v136
	s_ashr_i32 s17, s17, 24
	v_mul_lo_u32 v139, v139, s3
	v_lshlrev_b32_e32 v146, 1, v136
	s_cmp_gt_i32 s17, 7
	v_add3_u32 v139, v158, v139, v146
	v_lshl_add_u32 v146, v137, 2, v159
	s_cselect_b64 s[20:21], -1, 0
	s_cmp_lt_i32 s17, 8
	s_mov_b64 s[30:31], -1
	s_cbranch_scc1 .LBB0_144
	ds_read_b32 v162, v146
	v_add_u32_e32 v161, 0x2000, v139
	s_mov_b64 s[30:31], 0
	s_waitcnt lgkmcnt(0)
	v_pk_mul_f32 v[164:165], v[120:121], v[162:163] op_sel_hi:[1,0]
	v_pk_mul_f32 v[166:167], v[122:123], v[162:163] op_sel_hi:[1,0]
	v_cvt_pk_bf16_f32 v164, v164, v165
	v_cvt_pk_bf16_f32 v165, v166, v167
	v_pk_mul_f32 v[166:167], v[112:113], v[162:163] op_sel_hi:[1,0]
	v_pk_mul_f32 v[172:173], v[114:115], v[162:163] op_sel_hi:[1,0]
	v_cvt_pk_bf16_f32 v166, v166, v167
	v_cvt_pk_bf16_f32 v167, v172, v173
	ds_write2_b64 v139, v[164:165], v[166:167] offset1:4
	v_pk_mul_f32 v[164:165], v[124:125], v[162:163] op_sel_hi:[1,0]
	v_pk_mul_f32 v[166:167], v[126:127], v[162:163] op_sel_hi:[1,0]
	v_cvt_pk_bf16_f32 v164, v164, v165
	v_cvt_pk_bf16_f32 v165, v166, v167
	v_pk_mul_f32 v[166:167], v[116:117], v[162:163] op_sel_hi:[1,0]
	v_pk_mul_f32 v[162:163], v[118:119], v[162:163] op_sel_hi:[1,0]
	v_cvt_pk_bf16_f32 v166, v166, v167
	v_cvt_pk_bf16_f32 v167, v162, v163
	ds_write2_b64 v139, v[164:165], v[166:167] offset0:8 offset1:12
	ds_read_b32 v162, v146 offset:64
	s_waitcnt lgkmcnt(0)
	v_pk_mul_f32 v[164:165], v[104:105], v[162:163] op_sel_hi:[1,0]
	v_pk_mul_f32 v[166:167], v[106:107], v[162:163] op_sel_hi:[1,0]
	v_cvt_pk_bf16_f32 v164, v164, v165
	v_cvt_pk_bf16_f32 v165, v166, v167
	v_pk_mul_f32 v[166:167], v[96:97], v[162:163] op_sel_hi:[1,0]
	v_pk_mul_f32 v[172:173], v[98:99], v[162:163] op_sel_hi:[1,0]
	v_cvt_pk_bf16_f32 v166, v166, v167
	v_cvt_pk_bf16_f32 v167, v172, v173
	ds_write2_b64 v161, v[164:165], v[166:167] offset0:32 offset1:36
	v_pk_mul_f32 v[164:165], v[108:109], v[162:163] op_sel_hi:[1,0]
	v_pk_mul_f32 v[166:167], v[110:111], v[162:163] op_sel_hi:[1,0]
	v_cvt_pk_bf16_f32 v164, v164, v165
	v_cvt_pk_bf16_f32 v165, v166, v167
	v_pk_mul_f32 v[166:167], v[100:101], v[162:163] op_sel_hi:[1,0]
	v_pk_mul_f32 v[162:163], v[102:103], v[162:163] op_sel_hi:[1,0]
	v_cvt_pk_bf16_f32 v166, v166, v167
	v_cvt_pk_bf16_f32 v167, v162, v163
	ds_write2_b64 v161, v[164:165], v[166:167] offset0:40 offset1:44
	ds_read_b32 v162, v146 offset:128
	v_add_u32_e32 v161, 0x4000, v139
	s_waitcnt lgkmcnt(0)
	v_pk_mul_f32 v[164:165], v[88:89], v[162:163] op_sel_hi:[1,0]
	v_pk_mul_f32 v[166:167], v[90:91], v[162:163] op_sel_hi:[1,0]
	v_cvt_pk_bf16_f32 v164, v164, v165
	v_cvt_pk_bf16_f32 v165, v166, v167
	v_pk_mul_f32 v[166:167], v[80:81], v[162:163] op_sel_hi:[1,0]
	v_pk_mul_f32 v[172:173], v[82:83], v[162:163] op_sel_hi:[1,0]
	v_cvt_pk_bf16_f32 v166, v166, v167
	v_cvt_pk_bf16_f32 v167, v172, v173
	ds_write2_b64 v161, v[164:165], v[166:167] offset0:64 offset1:68
	v_pk_mul_f32 v[164:165], v[92:93], v[162:163] op_sel_hi:[1,0]
	v_pk_mul_f32 v[166:167], v[94:95], v[162:163] op_sel_hi:[1,0]
	v_cvt_pk_bf16_f32 v164, v164, v165
	v_cvt_pk_bf16_f32 v165, v166, v167
	v_pk_mul_f32 v[166:167], v[84:85], v[162:163] op_sel_hi:[1,0]
	v_pk_mul_f32 v[162:163], v[86:87], v[162:163] op_sel_hi:[1,0]
	v_cvt_pk_bf16_f32 v166, v166, v167
	v_cvt_pk_bf16_f32 v167, v162, v163
	ds_write2_b64 v161, v[164:165], v[166:167] offset0:72 offset1:76
	ds_read_b32 v162, v146 offset:192
	v_add_u32_e32 v161, 0x6000, v139
	s_waitcnt lgkmcnt(0)
; DI unsigned pk2(float a, float b) { f32x2 v = {a, b}; bf16x2_t r = __builtin_convertvector(v, bf16x2_t); return __builtin_bit_cast(unsigned, r); }
;     DI void operator()(gacc_t& acc, int pm, int pn, char* lds, int tid, int wr, int wc, int lane) const {
;     ...
; #pragma unroll
;             for (int m = 0; m < 8; ++m) {
;                 const float r = rlt[m * 16];
; #pragma unroll
;                 for (int n = 0; n < 4; ++n) { u32x2 w; w.x = pk2(acc[m][n][0] * r, acc[m][n][1] * r); w.y = pk2(acc[m][n][2] * r, acc[m][n][3] * r); *(u32x2*)(lbase + m * 16 * 528 + n * 32) = w; }
;             }
	v_pk_mul_f32 v[164:165], v[72:73], v[162:163] op_sel_hi:[1,0]
	v_pk_mul_f32 v[166:167], v[74:75], v[162:163] op_sel_hi:[1,0]
	v_cvt_pk_bf16_f32 v164, v164, v165
	v_cvt_pk_bf16_f32 v165, v166, v167
	v_pk_mul_f32 v[166:167], v[64:65], v[162:163] op_sel_hi:[1,0]
	v_pk_mul_f32 v[172:173], v[66:67], v[162:163] op_sel_hi:[1,0]
	v_cvt_pk_bf16_f32 v166, v166, v167
	v_cvt_pk_bf16_f32 v167, v172, v173
	ds_write2_b64 v161, v[164:165], v[166:167] offset0:96 offset1:100
	v_pk_mul_f32 v[164:165], v[76:77], v[162:163] op_sel_hi:[1,0]
	v_pk_mul_f32 v[166:167], v[78:79], v[162:163] op_sel_hi:[1,0]
	v_cvt_pk_bf16_f32 v164, v164, v165
	v_cvt_pk_bf16_f32 v165, v166, v167
	v_pk_mul_f32 v[166:167], v[68:69], v[162:163] op_sel_hi:[1,0]
	v_pk_mul_f32 v[162:163], v[70:71], v[162:163] op_sel_hi:[1,0]
	v_cvt_pk_bf16_f32 v166, v166, v167
	v_cvt_pk_bf16_f32 v167, v162, v163
	ds_write2_b64 v161, v[164:165], v[166:167] offset0:104 offset1:108
	ds_read_b32 v162, v146 offset:256
	v_add_u32_e32 v161, 0x8000, v139
	s_waitcnt lgkmcnt(0)
	v_pk_mul_f32 v[164:165], v[56:57], v[162:163] op_sel_hi:[1,0]
	v_pk_mul_f32 v[166:167], v[58:59], v[162:163] op_sel_hi:[1,0]
	v_cvt_pk_bf16_f32 v164, v164, v165
	v_cvt_pk_bf16_f32 v165, v166, v167
	v_pk_mul_f32 v[166:167], v[48:49], v[162:163] op_sel_hi:[1,0]
	v_pk_mul_f32 v[172:173], v[50:51], v[162:163] op_sel_hi:[1,0]
	v_cvt_pk_bf16_f32 v166, v166, v167
	v_cvt_pk_bf16_f32 v167, v172, v173
	ds_write2_b64 v161, v[164:165], v[166:167] offset0:128 offset1:132
	v_pk_mul_f32 v[164:165], v[60:61], v[162:163] op_sel_hi:[1,0]
	v_pk_mul_f32 v[166:167], v[62:63], v[162:163] op_sel_hi:[1,0]
	v_cvt_pk_bf16_f32 v164, v164, v165
	v_cvt_pk_bf16_f32 v165, v166, v167
	v_pk_mul_f32 v[166:167], v[52:53], v[162:163] op_sel_hi:[1,0]
	v_pk_mul_f32 v[162:163], v[54:55], v[162:163] op_sel_hi:[1,0]
	v_cvt_pk_bf16_f32 v166, v166, v167
	v_cvt_pk_bf16_f32 v167, v162, v163
	ds_write2_b64 v161, v[164:165], v[166:167] offset0:136 offset1:140
	ds_read_b32 v162, v146 offset:320
	v_add_u32_e32 v161, 0xa000, v139
	s_waitcnt lgkmcnt(0)
	v_pk_mul_f32 v[164:165], v[40:41], v[162:163] op_sel_hi:[1,0]
	v_pk_mul_f32 v[166:167], v[42:43], v[162:163] op_sel_hi:[1,0]
	v_cvt_pk_bf16_f32 v164, v164, v165
	v_cvt_pk_bf16_f32 v165, v166, v167
	v_pk_mul_f32 v[166:167], v[32:33], v[162:163] op_sel_hi:[1,0]
	v_pk_mul_f32 v[172:173], v[34:35], v[162:163] op_sel_hi:[1,0]
	v_cvt_pk_bf16_f32 v166, v166, v167
	v_cvt_pk_bf16_f32 v167, v172, v173
	ds_write2_b64 v161, v[164:165], v[166:167] offset0:160 offset1:164
	v_pk_mul_f32 v[164:165], v[44:45], v[162:163] op_sel_hi:[1,0]
	v_pk_mul_f32 v[166:167], v[46:47], v[162:163] op_sel_hi:[1,0]
	v_cvt_pk_bf16_f32 v164, v164, v165
	v_cvt_pk_bf16_f32 v165, v166, v167
	v_pk_mul_f32 v[166:167], v[36:37], v[162:163] op_sel_hi:[1,0]
	v_pk_mul_f32 v[162:163], v[38:39], v[162:163] op_sel_hi:[1,0]
	v_cvt_pk_bf16_f32 v166, v166, v167
	v_cvt_pk_bf16_f32 v167, v162, v163
	ds_write2_b64 v161, v[164:165], v[166:167] offset0:168 offset1:172
	ds_read_b32 v162, v146 offset:384
	v_add_u32_e32 v161, 0xc000, v139
	s_waitcnt lgkmcnt(0)
	v_pk_mul_f32 v[164:165], v[24:25], v[162:163] op_sel_hi:[1,0]
	v_pk_mul_f32 v[166:167], v[26:27], v[162:163] op_sel_hi:[1,0]
	v_cvt_pk_bf16_f32 v164, v164, v165
	v_cvt_pk_bf16_f32 v165, v166, v167
	v_pk_mul_f32 v[166:167], v[16:17], v[162:163] op_sel_hi:[1,0]
	v_pk_mul_f32 v[172:173], v[18:19], v[162:163] op_sel_hi:[1,0]
	v_cvt_pk_bf16_f32 v166, v166, v167
	v_cvt_pk_bf16_f32 v167, v172, v173
	ds_write2_b64 v161, v[164:165], v[166:167] offset0:192 offset1:196
	v_pk_mul_f32 v[164:165], v[28:29], v[162:163] op_sel_hi:[1,0]
	v_pk_mul_f32 v[166:167], v[30:31], v[162:163] op_sel_hi:[1,0]
	v_cvt_pk_bf16_f32 v164, v164, v165
	v_cvt_pk_bf16_f32 v165, v166, v167
	v_pk_mul_f32 v[166:167], v[20:21], v[162:163] op_sel_hi:[1,0]
	v_pk_mul_f32 v[162:163], v[22:23], v[162:163] op_sel_hi:[1,0]
	v_cvt_pk_bf16_f32 v166, v166, v167
	v_cvt_pk_bf16_f32 v167, v162, v163
	ds_write2_b64 v161, v[164:165], v[166:167] offset0:200 offset1:204
	ds_read_b32 v162, v146 offset:448
	v_add_u32_e32 v161, 0xe000, v139
	s_waitcnt lgkmcnt(0)
	v_pk_mul_f32 v[164:165], v[8:9], v[162:163] op_sel_hi:[1,0]
	v_pk_mul_f32 v[166:167], v[10:11], v[162:163] op_sel_hi:[1,0]
	v_cvt_pk_bf16_f32 v164, v164, v165
	v_cvt_pk_bf16_f32 v165, v166, v167
	v_pk_mul_f32 v[166:167], v[0:1], v[162:163] op_sel_hi:[1,0]
	v_pk_mul_f32 v[172:173], v[2:3], v[162:163] op_sel_hi:[1,0]
	v_cvt_pk_bf16_f32 v166, v166, v167
	v_cvt_pk_bf16_f32 v167, v172, v173
	ds_write2_b64 v161, v[164:165], v[166:167] offset0:224 offset1:228
	v_pk_mul_f32 v[164:165], v[12:13], v[162:163] op_sel_hi:[1,0]
	v_pk_mul_f32 v[166:167], v[14:15], v[162:163] op_sel_hi:[1,0]
	v_cvt_pk_bf16_f32 v164, v164, v165
	v_cvt_pk_bf16_f32 v165, v166, v167
	v_pk_mul_f32 v[166:167], v[4:5], v[162:163] op_sel_hi:[1,0]
	v_pk_mul_f32 v[162:163], v[6:7], v[162:163] op_sel_hi:[1,0]
	v_cvt_pk_bf16_f32 v166, v166, v167
	v_cvt_pk_bf16_f32 v167, v162, v163
	ds_write2_b64 v161, v[164:165], v[166:167] offset0:232 offset1:236

; #define MFMA16(a, b, c) __builtin_amdgcn_mfma_f32_16x16x32_bf16((a), (b), (c), 0, 0, 0)
; DI bf16x8 ldfrag(const char* lds, int row, int chunk) { return *(const bf16x8*)(lds + swz(row, chunk)); }
; template <bool RSTD, bool SWAP>
; DI void gemm_tile(gacc_t& acc, const bf16_t* __restrict__ A, int lda, const bf16_t* __restrict__ Bt, int ldb, int K,
;                   char* lds, int tid, int wr, int wc, int lane, const float* ssq_row) {
;     ...
;     GEMM_ISSUE(0, 0);
;     if (RSTD && tid < 256) {
;         const f32x4 q = *(const f32x4*)ssq_row;
;         ((float*)(lds + RSTD_OFF))[tid] = 1.0f / sqrtf(((q.x + q.y) + (q.z + q.w)) * (1.0f / 1024.0f) + 1e-6f);
;     }
;     asm volatile("s_waitcnt vmcnt(0)" ::: "memory");
;     __syncthreads();
;     for (int kt = 0; kt < nk; ++kt) {
;         const char* cur = lds + (kt & 1) * 65536;
;         if (kt + 1 < nk) GEMM_ISSUE(kt + 1, (kt + 1) & 1);
;         bf16x8 bfr[2][4], afr[3];
; #pragma unroll
;         for (int n = 0; n < 4; ++n) bfr[0][n] = ldfrag(cur + 32768, wc * 64 + n * 16 + fr, fq);
;         afr[0] = ldfrag(cur, wr * 128 + fr, fq);
;         afr[1] = ldfrag(cur, wr * 128 + 16 + fr, fq);
; #pragma unroll
;         for (int idx = 0; idx < 16; ++idx) {
;             const int ks = idx >> 3, m = idx & 7;
;             if (idx < 14) afr[(idx + 2) % 3] = ldfrag(cur, wr * 128 + ((idx + 2) & 7) * 16 + fr, ((idx + 2) >> 3) * 4 + fq);
;             if (ks == 0 && m >= 2 && m < 6) bfr[1][m - 2] = ldfrag(cur + 32768, wc * 64 + (m - 2) * 16 + fr, 4 + fq);
; #pragma unroll
;             for (int n = 0; n < 4; ++n) acc[m][n] = SWAP ? MFMA16(bfr[ks][n], afr[idx % 3], acc[m][n]) : MFMA16(afr[idx % 3], bfr[ks][n], acc[m][n]);
.LBB0_281:
	v_lshl_add_u64 v[158:159], v[136:137], 0, s[4:5]
	s_mov_b64 s[20:21], 0x1880080
	v_lshl_add_u64 v[162:163], v[158:159], 0, s[20:21]
	s_mov_b64 s[20:21], 0x18a0080
	s_add_i32 s18, s17, 0xffff0000
	s_and_b32 s19, s17, 0x10000
	v_lshl_add_u64 v[166:167], v[158:159], 0, s[20:21]
	s_mov_b64 s[20:21], 0x18c0080
	s_and_b32 s23, s18, 0x10000
	s_add_i32 s18, s19, 0
	v_lshl_add_u64 v[174:175], v[158:159], 0, s[20:21]
	s_mov_b64 s[20:21], 0x18e0080
	v_lshl_add_u64 v[156:157], v[138:139], 0, s[4:5]
	v_lshl_add_u64 v[158:159], v[158:159], 0, s[20:21]
	s_add_i32 s20, s18, s16
	v_lshl_add_u64 v[160:161], v[156:157], 0, s[14:15]
	s_add_i32 s21, s20, 0x8000
	s_mov_b32 m0, s20
	v_lshl_add_u64 v[164:165], v[156:157], 0, s[72:73]
	global_load_lds_dwordx4 v[160:161], off
	v_mfma_f32_16x16x32_bf16 v[60:63], v[194:197], v[236:239], v[60:63]
	s_mov_b32 m0, s21
	v_lshl_add_u64 v[172:173], v[156:157], 0, s[76:77]
	global_load_lds_dwordx4 v[162:163], off
	v_mfma_f32_16x16x32_bf16 v[56:59], v[198:201], v[236:239], v[56:59]
	s_add_i32 m0, s20, 0x2000
	v_lshl_add_u64 v[156:157], v[156:157], 0, s[0:1]
	global_load_lds_dwordx4 v[164:165], off
	v_mfma_f32_16x16x32_bf16 v[52:55], v[202:205], v[236:239], v[52:55]
	s_add_i32 m0, s20, 0xa000
	s_add_i32 s19, s23, 0
	global_load_lds_dwordx4 v[166:167], off
	v_mfma_f32_16x16x32_bf16 v[48:51], v[206:209], v[236:239], v[48:51]
	s_add_i32 m0, s20, 0x4000
	v_add_u32_e32 v146, s19, v142
	global_load_lds_dwordx4 v[172:173], off
	v_mfma_f32_16x16x32_bf16 v[44:47], v[194:197], v[240:243], v[44:47]
	s_add_i32 m0, s20, 0xc000
	v_add3_u32 v155, v146, v148, v149
	global_load_lds_dwordx4 v[174:175], off
	v_mfma_f32_16x16x32_bf16 v[40:43], v[198:201], v[240:243], v[40:43]
	s_add_i32 m0, s20, 0x6000
	v_add_u32_e32 v252, v146, v144
	global_load_lds_dwordx4 v[156:157], off
	v_mfma_f32_16x16x32_bf16 v[36:39], v[202:205], v[240:243], v[36:39]
	s_add_i32 m0, s20, 0xe000
	s_nop 0
	global_load_lds_dwordx4 v[158:159], off
	v_mfma_f32_16x16x32_bf16 v[32:35], v[206:209], v[240:243], v[32:35]
	ds_read_b128 v[156:159], v155 offset:32768
	ds_read_b128 v[160:163], v155 offset:34816
	ds_read_b128 v[172:175], v155 offset:36864
	ds_read_b128 v[176:179], v155 offset:38912
	ds_read_b128 v[164:167], v252
	ds_read_b128 v[180:183], v252 offset:2048
	ds_read_b128 v[190:193], v252 offset:4096
	v_add_u32_e32 v155, v146, v150
	v_mfma_f32_16x16x32_bf16 v[28:31], v[194:197], v[244:247], v[28:31]
	v_mfma_f32_16x16x32_bf16 v[24:27], v[198:201], v[244:247], v[24:27]
	v_mfma_f32_16x16x32_bf16 v[20:23], v[202:205], v[244:247], v[20:23]
	v_mfma_f32_16x16x32_bf16 v[16:19], v[206:209], v[244:247], v[16:19]
	v_mfma_f32_16x16x32_bf16 v[12:15], v[194:197], v[248:251], v[12:15]
	v_mfma_f32_16x16x32_bf16 v[8:11], v[198:201], v[248:251], v[8:11]
	v_mfma_f32_16x16x32_bf16 v[4:7], v[202:205], v[248:251], v[4:7]
	v_mfma_f32_16x16x32_bf16 v[0:3], v[206:209], v[248:251], v[0:3]
	s_waitcnt lgkmcnt(2)
	v_mfma_f32_16x16x32_bf16 v[124:127], v[156:159], v[164:167], v[124:127]
	v_add_u32_e32 v146, v146, v152
	v_mfma_f32_16x16x32_bf16 v[120:123], v[160:163], v[164:167], v[120:123]
	v_mfma_f32_16x16x32_bf16 v[116:119], v[172:175], v[164:167], v[116:119]
	v_mfma_f32_16x16x32_bf16 v[112:115], v[176:179], v[164:167], v[112:115]
	ds_read_b128 v[164:167], v155
	v_add_u32_e32 v155, s19, v145
	v_add_u32_e32 v203, v155, v151
	s_waitcnt lgkmcnt(2)
	v_mfma_f32_16x16x32_bf16 v[108:111], v[156:159], v[180:183], v[108:111]
	v_add_u32_e32 v206, v155, v153
	v_mfma_f32_16x16x32_bf16 v[104:107], v[160:163], v[180:183], v[104:107]
	v_mfma_f32_16x16x32_bf16 v[100:103], v[172:175], v[180:183], v[100:103]
	v_mfma_f32_16x16x32_bf16 v[96:99], v[176:179], v[180:183], v[96:99]
	ds_read_b128 v[180:183], v252 offset:8192
	ds_read_b128 v[194:197], v203 offset:32768
	s_waitcnt lgkmcnt(3)
	v_mfma_f32_16x16x32_bf16 v[92:95], v[156:159], v[190:193], v[92:95]
	v_mfma_f32_16x16x32_bf16 v[88:91], v[160:163], v[190:193], v[88:91]
	v_mfma_f32_16x16x32_bf16 v[84:87], v[172:175], v[190:193], v[84:87]
	v_mfma_f32_16x16x32_bf16 v[80:83], v[176:179], v[190:193], v[80:83]
	ds_read_b128 v[190:193], v252 offset:10240
	ds_read_b128 v[198:201], v203 offset:34816
	s_waitcnt lgkmcnt(4)
	v_mfma_f32_16x16x32_bf16 v[76:79], v[156:159], v[164:167], v[76:79]
	v_mfma_f32_16x16x32_bf16 v[72:75], v[160:163], v[164:167], v[72:75]
	v_mfma_f32_16x16x32_bf16 v[68:71], v[172:175], v[164:167], v[68:71]
	v_mfma_f32_16x16x32_bf16 v[64:67], v[176:179], v[164:167], v[64:67]
	ds_read_b128 v[164:167], v252 offset:12288
	ds_read_b128 v[202:205], v203 offset:36864
	s_waitcnt lgkmcnt(5)
	v_mfma_f32_16x16x32_bf16 v[60:63], v[156:159], v[180:183], v[60:63]
	v_mfma_f32_16x16x32_bf16 v[56:59], v[160:163], v[180:183], v[56:59]
	v_mfma_f32_16x16x32_bf16 v[52:55], v[172:175], v[180:183], v[52:55]
	v_mfma_f32_16x16x32_bf16 v[48:51], v[176:179], v[180:183], v[48:51]
	ds_read_b128 v[206:209], v206 offset:38912
	ds_read_b128 v[180:183], v146
	v_add_u32_e32 v146, v155, v144
	s_waitcnt lgkmcnt(5)
	v_mfma_f32_16x16x32_bf16 v[44:47], v[156:159], v[190:193], v[44:47]
	v_mfma_f32_16x16x32_bf16 v[40:43], v[160:163], v[190:193], v[40:43]
	v_mfma_f32_16x16x32_bf16 v[36:39], v[172:175], v[190:193], v[36:39]
	v_mfma_f32_16x16x32_bf16 v[32:35], v[176:179], v[190:193], v[32:35]
	ds_read_b128 v[190:193], v146
	s_waitcnt lgkmcnt(4)
	v_mfma_f32_16x16x32_bf16 v[28:31], v[156:159], v[164:167], v[28:31]
	v_mfma_f32_16x16x32_bf16 v[24:27], v[160:163], v[164:167], v[24:27]
	v_mfma_f32_16x16x32_bf16 v[20:23], v[172:175], v[164:167], v[20:23]
	v_mfma_f32_16x16x32_bf16 v[16:19], v[176:179], v[164:167], v[16:19]
	ds_read_b128 v[164:167], v146 offset:2048
	s_waitcnt lgkmcnt(2)
; #define MFMA16(a, b, c) __builtin_amdgcn_mfma_f32_16x16x32_bf16((a), (b), (c), 0, 0, 0)
; DI bf16x8 ldfrag(const char* lds, int row, int chunk) { return *(const bf16x8*)(lds + swz(row, chunk)); }
; #define GEMM_SG1() do { __builtin_amdgcn_sched_group_barrier(0x100, 1, 0); __builtin_amdgcn_sched_group_barrier(0x008, 4, 0); } while (0)
; #define GEMM_SG2() do { __builtin_amdgcn_sched_group_barrier(0x100, 2, 0); __builtin_amdgcn_sched_group_barrier(0x008, 4, 0); } while (0)
; template <bool RSTD, bool SWAP>
; DI void gemm_tile(gacc_t& acc, const bf16_t* __restrict__ A, int lda, const bf16_t* __restrict__ Bt, int ldb, int K,
;                   char* lds, int tid, int wr, int wc, int lane, const float* ssq_row) {
;     ...
;     for (int kt = 0; kt < nk; ++kt) {
;         const char* cur = lds + (kt & 1) * 65536;
;         if (kt + 1 < nk) GEMM_ISSUE(kt + 1, (kt + 1) & 1);
;         bf16x8 bfr[2][4], afr[3];
; #pragma unroll
;         for (int n = 0; n < 4; ++n) bfr[0][n] = ldfrag(cur + 32768, wc * 64 + n * 16 + fr, fq);
;         afr[0] = ldfrag(cur, wr * 128 + fr, fq);
;         afr[1] = ldfrag(cur, wr * 128 + 16 + fr, fq);
; #pragma unroll
;         for (int idx = 0; idx < 16; ++idx) {
;             const int ks = idx >> 3, m = idx & 7;
;             if (idx < 14) afr[(idx + 2) % 3] = ldfrag(cur, wr * 128 + ((idx + 2) & 7) * 16 + fr, ((idx + 2) >> 3) * 4 + fq);
;             if (ks == 0 && m >= 2 && m < 6) bfr[1][m - 2] = ldfrag(cur + 32768, wc * 64 + (m - 2) * 16 + fr, 4 + fq);
; #pragma unroll
;             for (int n = 0; n < 4; ++n) acc[m][n] = SWAP ? MFMA16(bfr[ks][n], afr[idx % 3], acc[m][n]) : MFMA16(afr[idx % 3], bfr[ks][n], acc[m][n]);
;         }
;         __builtin_amdgcn_sched_group_barrier(0x100, 6, 0);
;     ...
;         GEMM_SG1(); GEMM_SG1(); GEMM_SG2(); GEMM_SG2(); GEMM_SG2(); GEMM_SG2(); GEMM_SG1(); GEMM_SG1();
;         GEMM_SG1(); GEMM_SG1(); GEMM_SG1(); GEMM_SG1(); GEMM_SG1(); GEMM_SG1();
;         __builtin_amdgcn_sched_group_barrier(0x008, 8, 0);
;         __builtin_amdgcn_sched_barrier(0);
;         asm volatile("s_waitcnt vmcnt(0)" ::: "memory");
;         __syncthreads();
	v_mfma_f32_16x16x32_bf16 v[8:11], v[160:163], v[180:183], v[8:11]
	v_add_u32_e32 v160, v155, v150
	v_mfma_f32_16x16x32_bf16 v[12:15], v[156:159], v[180:183], v[12:15]
	v_mfma_f32_16x16x32_bf16 v[4:7], v[172:175], v[180:183], v[4:7]
	v_mfma_f32_16x16x32_bf16 v[0:3], v[176:179], v[180:183], v[0:3]
	ds_read_b128 v[156:159], v146 offset:4096
	s_waitcnt lgkmcnt(2)
	v_mfma_f32_16x16x32_bf16 v[124:127], v[194:197], v[190:193], v[124:127]
	v_mfma_f32_16x16x32_bf16 v[120:123], v[198:201], v[190:193], v[120:123]
	v_mfma_f32_16x16x32_bf16 v[116:119], v[202:205], v[190:193], v[116:119]
	v_mfma_f32_16x16x32_bf16 v[112:115], v[206:209], v[190:193], v[112:115]
	ds_read_b128 v[160:163], v160
	s_waitcnt lgkmcnt(2)
	v_mfma_f32_16x16x32_bf16 v[108:111], v[194:197], v[164:167], v[108:111]
	v_mfma_f32_16x16x32_bf16 v[104:107], v[198:201], v[164:167], v[104:107]
	v_mfma_f32_16x16x32_bf16 v[100:103], v[202:205], v[164:167], v[100:103]
	v_mfma_f32_16x16x32_bf16 v[96:99], v[206:209], v[164:167], v[96:99]
	ds_read_b128 v[236:239], v146 offset:8192
	s_waitcnt lgkmcnt(2)
	v_mfma_f32_16x16x32_bf16 v[92:95], v[194:197], v[156:159], v[92:95]
	v_mfma_f32_16x16x32_bf16 v[88:91], v[198:201], v[156:159], v[88:91]
	v_mfma_f32_16x16x32_bf16 v[84:87], v[202:205], v[156:159], v[84:87]
	v_mfma_f32_16x16x32_bf16 v[80:83], v[206:209], v[156:159], v[80:83]
	ds_read_b128 v[240:243], v146 offset:10240
	ds_read_b128 v[244:247], v146 offset:12288
	v_add_u32_e32 v146, v155, v152
	ds_read_b128 v[248:251], v146
	s_waitcnt lgkmcnt(4)
	v_mfma_f32_16x16x32_bf16 v[76:79], v[194:197], v[160:163], v[76:79]
	v_mfma_f32_16x16x32_bf16 v[72:75], v[198:201], v[160:163], v[72:75]
	v_mfma_f32_16x16x32_bf16 v[68:71], v[202:205], v[160:163], v[68:71]
	v_mfma_f32_16x16x32_bf16 v[64:67], v[206:209], v[160:163], v[64:67]
	s_waitcnt lgkmcnt(0)
	s_waitcnt vmcnt(0)
	s_add_u32 s4, s4, 0x80
	s_addc_u32 s5, s5, 0
	s_add_i32 s17, s17, 0x10000
	s_cmpk_eq_i32 s4, 0x780
	s_waitcnt vmcnt(0)
	s_cbranch_scc0 .Lkhead_281
	s_barrier
	v_mfma_f32_16x16x32_bf16 v[60:63], v[194:197], v[236:239], v[60:63]
	v_mfma_f32_16x16x32_bf16 v[56:59], v[198:201], v[236:239], v[56:59]
	v_mfma_f32_16x16x32_bf16 v[52:55], v[202:205], v[236:239], v[52:55]
	v_mfma_f32_16x16x32_bf16 v[48:51], v[206:209], v[236:239], v[48:51]
	v_mfma_f32_16x16x32_bf16 v[44:47], v[194:197], v[240:243], v[44:47]
	v_mfma_f32_16x16x32_bf16 v[40:43], v[198:201], v[240:243], v[40:43]
	v_mfma_f32_16x16x32_bf16 v[36:39], v[202:205], v[240:243], v[36:39]
	v_mfma_f32_16x16x32_bf16 v[32:35], v[206:209], v[240:243], v[32:35]
	v_mfma_f32_16x16x32_bf16 v[28:31], v[194:197], v[244:247], v[28:31]
	v_mfma_f32_16x16x32_bf16 v[24:27], v[198:201], v[244:247], v[24:27]
	v_mfma_f32_16x16x32_bf16 v[20:23], v[202:205], v[244:247], v[20:23]
	v_mfma_f32_16x16x32_bf16 v[16:19], v[206:209], v[244:247], v[16:19]
	v_mfma_f32_16x16x32_bf16 v[12:15], v[194:197], v[248:251], v[12:15]
	v_mfma_f32_16x16x32_bf16 v[8:11], v[198:201], v[248:251], v[8:11]
	v_mfma_f32_16x16x32_bf16 v[4:7], v[202:205], v[248:251], v[4:7]
	v_mfma_f32_16x16x32_bf16 v[0:3], v[206:209], v[248:251], v[0:3]
	v_add_u32_e32 v146, s18, v142
	v_add3_u32 v155, v146, v148, v149
	ds_read_b128 v[136:139], v155 offset:32768
	ds_read_b128 v[156:159], v155 offset:34816
	ds_read_b128 v[164:167], v155 offset:36864
	ds_read_b128 v[172:175], v155 offset:38912
	v_add_u32_e32 v198, v146, v144
	ds_read_b128 v[160:163], v198
	ds_read_b128 v[176:179], v198 offset:2048
	v_add_u32_e32 v155, v146, v150
	ds_read_b128 v[180:183], v198 offset:4096
	s_waitcnt lgkmcnt(2)
	v_mfma_f32_16x16x32_bf16 v[124:127], v[136:139], v[160:163], v[124:127]
	v_add_u32_e32 v146, v146, v152
	s_lshl_b64 s[16:17], s[8:9], 8
	v_mfma_f32_16x16x32_bf16 v[120:123], v[156:159], v[160:163], v[120:123]
	v_mfma_f32_16x16x32_bf16 v[116:119], v[164:167], v[160:163], v[116:119]
	v_mfma_f32_16x16x32_bf16 v[112:115], v[172:175], v[160:163], v[112:115]
	ds_read_b128 v[160:163], v155
	v_add_u32_e32 v155, s18, v145
	v_add_u32_e32 v199, v155, v151
	s_waitcnt lgkmcnt(2)
	v_mfma_f32_16x16x32_bf16 v[108:111], v[136:139], v[176:179], v[108:111]
	v_mfma_f32_16x16x32_bf16 v[104:107], v[156:159], v[176:179], v[104:107]
	v_mfma_f32_16x16x32_bf16 v[100:103], v[164:167], v[176:179], v[100:103]
	v_mfma_f32_16x16x32_bf16 v[96:99], v[172:175], v[176:179], v[96:99]
	ds_read_b128 v[176:179], v198 offset:8192
	ds_read_b128 v[190:193], v199 offset:32768
	s_waitcnt lgkmcnt(3)
	v_mfma_f32_16x16x32_bf16 v[92:95], v[136:139], v[180:183], v[92:95]
	v_mfma_f32_16x16x32_bf16 v[88:91], v[156:159], v[180:183], v[88:91]
	v_mfma_f32_16x16x32_bf16 v[84:87], v[164:167], v[180:183], v[84:87]
	v_mfma_f32_16x16x32_bf16 v[80:83], v[172:175], v[180:183], v[80:83]
	ds_read_b128 v[180:183], v198 offset:10240
	ds_read_b128 v[194:197], v199 offset:34816
	s_waitcnt lgkmcnt(4)
	v_mfma_f32_16x16x32_bf16 v[76:79], v[136:139], v[160:163], v[76:79]
	v_mfma_f32_16x16x32_bf16 v[72:75], v[156:159], v[160:163], v[72:75]
	v_mfma_f32_16x16x32_bf16 v[68:71], v[164:167], v[160:163], v[68:71]
	v_mfma_f32_16x16x32_bf16 v[64:67], v[172:175], v[160:163], v[64:67]
	ds_read_b128 v[160:163], v198 offset:12288
	ds_read_b128 v[198:201], v199 offset:36864
	s_waitcnt lgkmcnt(5)
	v_mfma_f32_16x16x32_bf16 v[60:63], v[136:139], v[176:179], v[60:63]
	v_mfma_f32_16x16x32_bf16 v[56:59], v[156:159], v[176:179], v[56:59]
	v_mfma_f32_16x16x32_bf16 v[52:55], v[164:167], v[176:179], v[52:55]
	v_mfma_f32_16x16x32_bf16 v[48:51], v[172:175], v[176:179], v[48:51]
	ds_read_b128 v[176:179], v146
	v_add_u32_e32 v146, v155, v153
	ds_read_b128 v[202:205], v146 offset:38912
	v_add_u32_e32 v146, v155, v144
	s_waitcnt lgkmcnt(5)
; #define MFMA16(a, b, c) __builtin_amdgcn_mfma_f32_16x16x32_bf16((a), (b), (c), 0, 0, 0)
; DI unsigned pk2(float a, float b) { f32x2 v = {a, b}; bf16x2_t r = __builtin_convertvector(v, bf16x2_t); return __builtin_bit_cast(unsigned, r); }
; DI bf16x8 ldfrag(const char* lds, int row, int chunk) { return *(const bf16x8*)(lds + swz(row, chunk)); }
; #define GEMM_SG1() do { __builtin_amdgcn_sched_group_barrier(0x100, 1, 0); __builtin_amdgcn_sched_group_barrier(0x008, 4, 0); } while (0)
; template <bool RSTD, bool SWAP>
; DI void gemm_tile(gacc_t& acc, const bf16_t* __restrict__ A, int lda, const bf16_t* __restrict__ Bt, int ldb, int K,
;                   char* lds, int tid, int wr, int wc, int lane, const float* ssq_row) {
;     ...
;         for (int idx = 0; idx < 16; ++idx) {
;             const int ks = idx >> 3, m = idx & 7;
;             if (idx < 14) afr[(idx + 2) % 3] = ldfrag(cur, wr * 128 + ((idx + 2) & 7) * 16 + fr, ((idx + 2) >> 3) * 4 + fq);
;             if (ks == 0 && m >= 2 && m < 6) bfr[1][m - 2] = ldfrag(cur + 32768, wc * 64 + (m - 2) * 16 + fr, 4 + fq);
; #pragma unroll
;             for (int n = 0; n < 4; ++n) acc[m][n] = SWAP ? MFMA16(bfr[ks][n], afr[idx % 3], acc[m][n]) : MFMA16(afr[idx % 3], bfr[ks][n], acc[m][n]);
;         }
;         __builtin_amdgcn_sched_group_barrier(0x100, 6, 0);
;     ...
;         GEMM_SG1(); GEMM_SG1(); GEMM_SG2(); GEMM_SG2(); GEMM_SG2(); GEMM_SG2(); GEMM_SG1(); GEMM_SG1();
;         GEMM_SG1(); GEMM_SG1(); GEMM_SG1(); GEMM_SG1(); GEMM_SG1(); GEMM_SG1();
;         __builtin_amdgcn_sched_group_barrier(0x008, 8, 0);
;         __builtin_amdgcn_sched_barrier(0);
;         asm volatile("s_waitcnt vmcnt(0)" ::: "memory");
;         __syncthreads();
;     DI void operator()(gacc_t& acc, int pm, int pn, char* lds, int tid, int wr, int wc, int lane) const {
;         asm volatile("" : "+v"(tid), "+v"(lane));
;         const int fr = lane & 15, fq = lane >> 4, wid = tid >> 6;
;         char* lbase = lds + (wr * 128 + fr) * 528 + (wc * 64 + 4 * fq) * 2;
; #pragma unroll
;         for (int m = 0; m < 8; ++m)
; #pragma unroll
;             for (int n = 0; n < 4; ++n) { u32x2 w; w.x = pk2(acc[m][n][0], acc[m][n][1]); w.y = pk2(acc[m][n][2], acc[m][n][3]); *(u32x2*)(lbase + m * 16 * 528 + n * 32) = w; }
;         __builtin_amdgcn_sched_barrier(0);
	v_mfma_f32_16x16x32_bf16 v[44:47], v[136:139], v[180:183], v[44:47]
	v_mfma_f32_16x16x32_bf16 v[40:43], v[156:159], v[180:183], v[40:43]
	v_mfma_f32_16x16x32_bf16 v[36:39], v[164:167], v[180:183], v[36:39]
	v_mfma_f32_16x16x32_bf16 v[32:35], v[172:175], v[180:183], v[32:35]
	ds_read_b128 v[180:183], v146
	s_waitcnt lgkmcnt(4)
	v_mfma_f32_16x16x32_bf16 v[28:31], v[136:139], v[160:163], v[28:31]
	v_mfma_f32_16x16x32_bf16 v[24:27], v[156:159], v[160:163], v[24:27]
	v_mfma_f32_16x16x32_bf16 v[20:23], v[164:167], v[160:163], v[20:23]
	v_mfma_f32_16x16x32_bf16 v[16:19], v[172:175], v[160:163], v[16:19]
	ds_read_b128 v[160:163], v146 offset:2048
	s_waitcnt lgkmcnt(3)
	v_mfma_f32_16x16x32_bf16 v[8:11], v[156:159], v[176:179], v[8:11]
	v_add_u32_e32 v156, v155, v150
	v_mfma_f32_16x16x32_bf16 v[12:15], v[136:139], v[176:179], v[12:15]
	v_mfma_f32_16x16x32_bf16 v[4:7], v[164:167], v[176:179], v[4:7]
	v_mfma_f32_16x16x32_bf16 v[0:3], v[172:175], v[176:179], v[0:3]
	ds_read_b128 v[136:139], v146 offset:4096
	s_waitcnt lgkmcnt(2)
	v_mfma_f32_16x16x32_bf16 v[124:127], v[190:193], v[180:183], v[124:127]
	v_mfma_f32_16x16x32_bf16 v[120:123], v[194:197], v[180:183], v[120:123]
	v_mfma_f32_16x16x32_bf16 v[116:119], v[198:201], v[180:183], v[116:119]
	v_mfma_f32_16x16x32_bf16 v[112:115], v[202:205], v[180:183], v[112:115]
	ds_read_b128 v[156:159], v156
	s_waitcnt lgkmcnt(2)
	v_mfma_f32_16x16x32_bf16 v[108:111], v[190:193], v[160:163], v[108:111]
	v_mfma_f32_16x16x32_bf16 v[104:107], v[194:197], v[160:163], v[104:107]
	v_mfma_f32_16x16x32_bf16 v[100:103], v[198:201], v[160:163], v[100:103]
	v_mfma_f32_16x16x32_bf16 v[96:99], v[202:205], v[160:163], v[96:99]
	ds_read_b128 v[160:163], v146 offset:8192
	s_waitcnt lgkmcnt(2)
	v_mfma_f32_16x16x32_bf16 v[92:95], v[190:193], v[136:139], v[92:95]
	v_mfma_f32_16x16x32_bf16 v[88:91], v[194:197], v[136:139], v[88:91]
	v_mfma_f32_16x16x32_bf16 v[84:87], v[198:201], v[136:139], v[84:87]
	v_mfma_f32_16x16x32_bf16 v[80:83], v[202:205], v[136:139], v[80:83]
	ds_read_b128 v[136:139], v146 offset:10240
	s_waitcnt lgkmcnt(2)
	v_mfma_f32_16x16x32_bf16 v[76:79], v[190:193], v[156:159], v[76:79]
	v_mfma_f32_16x16x32_bf16 v[72:75], v[194:197], v[156:159], v[72:75]
	v_mfma_f32_16x16x32_bf16 v[68:71], v[198:201], v[156:159], v[68:71]
	v_mfma_f32_16x16x32_bf16 v[64:67], v[202:205], v[156:159], v[64:67]
	ds_read_b128 v[156:159], v146 offset:12288
	v_add_u32_e32 v146, v155, v152
	s_waitcnt lgkmcnt(2)
	v_mfma_f32_16x16x32_bf16 v[60:63], v[190:193], v[160:163], v[60:63]
	v_mfma_f32_16x16x32_bf16 v[56:59], v[194:197], v[160:163], v[56:59]
	v_mfma_f32_16x16x32_bf16 v[52:55], v[198:201], v[160:163], v[52:55]
	v_mfma_f32_16x16x32_bf16 v[48:51], v[202:205], v[160:163], v[48:51]
	ds_read_b128 v[160:163], v146
	s_waitcnt lgkmcnt(2)
	v_mfma_f32_16x16x32_bf16 v[44:47], v[190:193], v[136:139], v[44:47]
	v_mfma_f32_16x16x32_bf16 v[40:43], v[194:197], v[136:139], v[40:43]
	v_mfma_f32_16x16x32_bf16 v[36:39], v[198:201], v[136:139], v[36:39]
	v_mfma_f32_16x16x32_bf16 v[32:35], v[202:205], v[136:139], v[32:35]
	s_waitcnt lgkmcnt(1)
	v_mfma_f32_16x16x32_bf16 v[24:27], v[194:197], v[156:159], v[24:27]
	v_mfma_f32_16x16x32_bf16 v[20:23], v[198:201], v[156:159], v[20:23]
	v_mfma_f32_16x16x32_bf16 v[16:19], v[202:205], v[156:159], v[16:19]
	s_waitcnt lgkmcnt(0)
	v_mfma_f32_16x16x32_bf16 v[12:15], v[190:193], v[160:163], v[12:15]
	v_mfma_f32_16x16x32_bf16 v[8:11], v[194:197], v[160:163], v[8:11]
	v_mfma_f32_16x16x32_bf16 v[4:7], v[198:201], v[160:163], v[4:7]
	v_mfma_f32_16x16x32_bf16 v[0:3], v[202:205], v[160:163], v[0:3]
	v_mfma_f32_16x16x32_bf16 v[28:31], v[190:193], v[156:159], v[28:31]
	v_mov_b32_e32 v136, v141
	v_mov_b32_e32 v137, v140
	s_waitcnt vmcnt(0)
	s_barrier
	v_cvt_pk_bf16_f32 v124, v124, v125
	v_and_or_b32 v138, v136, 15, v143
	v_ashrrev_i32_e32 v139, 1, v136
	v_mul_lo_u32 v138, v138, s3
	v_and_b32_e32 v139, -8, v139
	v_add3_u32 v138, v154, v138, v139
	v_cvt_pk_bf16_f32 v125, v126, v127
	v_cvt_pk_bf16_f32 v120, v120, v121
	v_cvt_pk_bf16_f32 v121, v122, v123
	v_cvt_pk_bf16_f32 v116, v116, v117
	v_cvt_pk_bf16_f32 v117, v118, v119
	v_cvt_pk_bf16_f32 v112, v112, v113
	v_cvt_pk_bf16_f32 v113, v114, v115
	v_cvt_pk_bf16_f32 v108, v108, v109
	v_cvt_pk_bf16_f32 v109, v110, v111
	v_cvt_pk_bf16_f32 v104, v104, v105
	v_cvt_pk_bf16_f32 v105, v106, v107
	v_add_u32_e32 v106, 0x2000, v138
	v_cvt_pk_bf16_f32 v100, v100, v101
	v_cvt_pk_bf16_f32 v101, v102, v103
	v_cvt_pk_bf16_f32 v96, v96, v97
	v_cvt_pk_bf16_f32 v97, v98, v99
	v_cvt_pk_bf16_f32 v92, v92, v93
	v_cvt_pk_bf16_f32 v93, v94, v95
	v_cvt_pk_bf16_f32 v88, v88, v89
	v_cvt_pk_bf16_f32 v89, v90, v91
	v_add_u32_e32 v90, 0x4000, v138
	v_cvt_pk_bf16_f32 v84, v84, v85
	v_cvt_pk_bf16_f32 v85, v86, v87
	v_cvt_pk_bf16_f32 v80, v80, v81
	v_cvt_pk_bf16_f32 v81, v82, v83
	v_cvt_pk_bf16_f32 v76, v76, v77
	v_cvt_pk_bf16_f32 v77, v78, v79
	v_cvt_pk_bf16_f32 v72, v72, v73
	v_cvt_pk_bf16_f32 v73, v74, v75
	v_add_u32_e32 v74, 0x6000, v138
	v_cvt_pk_bf16_f32 v68, v68, v69
	v_cvt_pk_bf16_f32 v69, v70, v71
	v_cvt_pk_bf16_f32 v64, v64, v65
	v_cvt_pk_bf16_f32 v65, v66, v67
	v_cvt_pk_bf16_f32 v60, v60, v61
	v_cvt_pk_bf16_f32 v61, v62, v63
	v_cvt_pk_bf16_f32 v56, v56, v57
	v_cvt_pk_bf16_f32 v57, v58, v59
	v_add_u32_e32 v58, 0x8000, v138
	v_cvt_pk_bf16_f32 v52, v52, v53
	v_cvt_pk_bf16_f32 v53, v54, v55
	v_cvt_pk_bf16_f32 v48, v48, v49
	v_cvt_pk_bf16_f32 v49, v50, v51
	v_cvt_pk_bf16_f32 v44, v44, v45
	v_cvt_pk_bf16_f32 v45, v46, v47
	v_cvt_pk_bf16_f32 v40, v40, v41
; DI unsigned pk2(float a, float b) { f32x2 v = {a, b}; bf16x2_t r = __builtin_convertvector(v, bf16x2_t); return __builtin_bit_cast(unsigned, r); }
; DI float bflo(unsigned w) { return __uint_as_float(w << 16); }
; DI float bfhi(unsigned w) { return __uint_as_float(w & 0xffff0000u); }
;     DI void operator()(gacc_t& acc, int pm, int pn, char* lds, int tid, int wr, int wc, int lane) const {
;     ...
;             for (int n = 0; n < 4; ++n) { u32x2 w; w.x = pk2(acc[m][n][0], acc[m][n][1]); w.y = pk2(acc[m][n][2], acc[m][n][3]); *(u32x2*)(lbase + m * 16 * 528 + n * 32) = w; }
;         __builtin_amdgcn_sched_barrier(0);
;         __syncthreads();
;         __builtin_amdgcn_sched_barrier(0);
;         const int g = lane >> 5, j32 = lane & 31;
; #pragma unroll
;         for (int ib = 0; ib < 4; ++ib) {
;             __builtin_amdgcn_sched_barrier(0);
;             u32x4 xv[4];
; #pragma unroll
;             for (int u = 0; u < 4; ++u) {
;                 const long row = (long)pm * 256 + (ib * 4 + u) * 16 + wid * 2 + g;
;                 xv[u] = *(const u32x4*)(xold + row * 1024 + pn * 256 + j32 * 8);
;             }
; #pragma unroll
;             for (int u = 0; u < 4; ++u) {
;                 const int rloc = (ib * 4 + u) * 16 + wid * 2 + g;
;                 const long row = (long)pm * 256 + rloc;
;                 const u32x4 a = *(const u32x4*)(lds + rloc * 528 + j32 * 16);
;                 u32x4 w; float ss = 0.f;
; #pragma unroll
;                 for (int e = 0; e < 4; ++e) {
;                     w[e] = pk2(bflo(xv[u][e]) + bflo(a[e]), bfhi(xv[u][e]) + bfhi(a[e]));
;                     const float b0 = bflo(w[e]), b1 = bfhi(w[e]);
;                     ss += b0 * b0 + b1 * b1;
;                 }
;                 *(u32x4*)(xnew + row * 1024 + pn * 256 + j32 * 8) = w;
; #pragma unroll
;                 for (int o = 1; o < 32; o <<= 1) ss += __shfl_xor(ss, o);
;                 if (j32 == 0) ssq[row * 4 + pn] = ss;
	v_cvt_pk_bf16_f32 v41, v42, v43
	v_add_u32_e32 v42, 0xa000, v138
	v_cvt_pk_bf16_f32 v36, v36, v37
	v_cvt_pk_bf16_f32 v37, v38, v39
	v_cvt_pk_bf16_f32 v32, v32, v33
	v_cvt_pk_bf16_f32 v33, v34, v35
	v_cvt_pk_bf16_f32 v28, v28, v29
	v_cvt_pk_bf16_f32 v29, v30, v31
	v_cvt_pk_bf16_f32 v24, v24, v25
	v_cvt_pk_bf16_f32 v25, v26, v27
	v_add_u32_e32 v26, 0xc000, v138
	v_cvt_pk_bf16_f32 v20, v20, v21
	v_cvt_pk_bf16_f32 v21, v22, v23
	v_cvt_pk_bf16_f32 v16, v16, v17
	v_cvt_pk_bf16_f32 v17, v18, v19
	v_cvt_pk_bf16_f32 v12, v12, v13
	v_cvt_pk_bf16_f32 v13, v14, v15
	v_cvt_pk_bf16_f32 v8, v8, v9
	v_cvt_pk_bf16_f32 v9, v10, v11
	v_add_u32_e32 v10, 0xe000, v138
	v_cvt_pk_bf16_f32 v4, v4, v5
	v_cvt_pk_bf16_f32 v5, v6, v7
	v_cvt_pk_bf16_f32 v0, v0, v1
	v_cvt_pk_bf16_f32 v1, v2, v3
	ds_write2_b64 v138, v[124:125], v[120:121] offset1:4
	ds_write2_b64 v138, v[116:117], v[112:113] offset0:8 offset1:12
	ds_write2_b64 v106, v[108:109], v[104:105] offset0:32 offset1:36
	ds_write2_b64 v106, v[100:101], v[96:97] offset0:40 offset1:44
	ds_write2_b64 v90, v[92:93], v[88:89] offset0:64 offset1:68
	ds_write2_b64 v90, v[84:85], v[80:81] offset0:72 offset1:76
	ds_write2_b64 v74, v[76:77], v[72:73] offset0:96 offset1:100
	ds_write2_b64 v74, v[68:69], v[64:65] offset0:104 offset1:108
	ds_write2_b64 v58, v[60:61], v[56:57] offset0:128 offset1:132
	ds_write2_b64 v58, v[52:53], v[48:49] offset0:136 offset1:140
	ds_write2_b64 v42, v[44:45], v[40:41] offset0:160 offset1:164
	ds_write2_b64 v42, v[36:37], v[32:33] offset0:168 offset1:172
	ds_write2_b64 v26, v[28:29], v[24:25] offset0:192 offset1:196
	ds_write2_b64 v26, v[20:21], v[16:17] offset0:200 offset1:204
	ds_write2_b64 v10, v[12:13], v[8:9] offset0:224 offset1:228
	ds_write2_b64 v10, v[4:5], v[0:1] offset0:232 offset1:236
	s_waitcnt lgkmcnt(0)
	s_barrier
	v_ashrrev_i32_e32 v0, 5, v136
	v_ashrrev_i32_e32 v1, 5, v137
	v_and_b32_e32 v23, 31, v136
	v_and_b32_e32 v2, -2, v1
	v_ashrrev_i32_e32 v1, 31, v0
	v_ashrrev_i32_e32 v3, 31, v2
	v_lshl_add_u64 v[4:5], s[16:17], 0, v[0:1]
	s_lshl_b32 s18, s6, 8
	v_lshlrev_b32_e32 v146, 4, v23
	v_lshl_add_u64 v[4:5], v[4:5], 0, v[2:3]
	s_ashr_i32 s19, s18, 31
	v_add_u32_e32 v16, v2, v0
	v_add_u32_e32 v22, 0, v146
	v_cmp_eq_u32_e64 s[4:5], 0, v23
	v_cmp_eq_u32_e64 s[98:99], 16, v23
	s_lshl_b64 s[20:21], s[18:19], 1
	s_add_u32 s30, s10, s20
	s_addc_u32 s31, s11, s21
	v_lshl_add_u64 v[0:1], s[30:31], 0, v[146:147]
	v_lshlrev_b64 v[2:3], 11, v[4:5]
	v_lshl_add_u64 v[18:19], v[0:1], 0, v[2:3]
	flat_load_dwordx4 v[12:15], v[18:19]
	v_add_co_u32_e32 v0, vcc, s49, v18
	v_mul_lo_u32 v24, v16, s3
	s_nop 0
	v_addc_co_u32_e32 v1, vcc, 0, v19, vcc
	flat_load_dwordx4 v[8:11], v[0:1]
	v_add_co_u32_e32 v0, vcc, s48, v18
	v_add_u32_e32 v20, v22, v24
	s_nop 0
	v_addc_co_u32_e32 v1, vcc, 0, v19, vcc
	flat_load_dwordx4 v[4:7], v[0:1]
	v_add_co_u32_e32 v0, vcc, s47, v18
	ds_read_b128 v[26:29], v20
	s_nop 0
	v_addc_co_u32_e32 v1, vcc, 0, v19, vcc
	flat_load_dwordx4 v[0:3], v[0:1]
	v_ashrrev_i32_e32 v17, 31, v16
	s_waitcnt lgkmcnt(0)
	v_lshlrev_b32_e32 v30, 16, v26
	v_and_b32_e32 v31, 0xffff0000, v26
	v_lshlrev_b32_e32 v26, 16, v27
	v_and_b32_e32 v27, 0xffff0000, v27
	s_waitcnt vmcnt(0)
	v_lshlrev_b32_e32 v20, 16, v12
	v_and_b32_e32 v21, 0xffff0000, v12
	v_pk_add_f32 v[20:21], v[20:21], v[30:31]
	s_nop 0
	v_cvt_pk_bf16_f32 v12, v20, v21
	v_and_b32_e32 v21, 0xffff0000, v12
	v_lshlrev_b32_e32 v20, 16, v12
	v_mul_f32_e32 v25, v21, v21
	v_fmac_f32_e32 v25, v20, v20
	v_lshlrev_b32_e32 v20, 16, v13
	v_and_b32_e32 v21, 0xffff0000, v13
	v_pk_add_f32 v[20:21], v[20:21], v[26:27]
	v_lshlrev_b32_e32 v26, 16, v28
	v_cvt_pk_bf16_f32 v13, v20, v21
	v_and_b32_e32 v21, 0xffff0000, v13
	v_lshlrev_b32_e32 v20, 16, v13
	v_mul_f32_e32 v21, v21, v21
	v_fmac_f32_e32 v21, v20, v20
	v_add_f32_e32 v25, v25, v21
	v_lshlrev_b32_e32 v20, 16, v14
	v_and_b32_e32 v21, 0xffff0000, v14
	v_and_b32_e32 v27, 0xffff0000, v28
	v_pk_add_f32 v[20:21], v[20:21], v[26:27]
	v_lshlrev_b32_e32 v26, 16, v29
	v_cvt_pk_bf16_f32 v14, v20, v21
	v_and_b32_e32 v21, 0xffff0000, v14
	v_lshlrev_b32_e32 v20, 16, v14
	v_mul_f32_e32 v21, v21, v21
	v_fmac_f32_e32 v21, v20, v20
	v_add_f32_e32 v25, v21, v25
	v_lshlrev_b32_e32 v20, 16, v15
	v_and_b32_e32 v21, 0xffff0000, v15
	v_and_b32_e32 v27, 0xffff0000, v29
	v_pk_add_f32 v[20:21], v[20:21], v[26:27]
	s_nop 0
	v_cvt_pk_bf16_f32 v15, v20, v21
	v_and_b32_e32 v21, 0xffff0000, v15
	v_lshlrev_b32_e32 v20, 16, v15
	v_mul_f32_e32 v21, v21, v21
	v_fmac_f32_e32 v21, v20, v20
	v_add_f32_e32 v25, v21, v25
	v_lshl_add_u64 v[20:21], s[16:17], 0, v[16:17]
	v_lshlrev_b64 v[26:27], 11, v[20:21]
	v_lshl_add_u64 v[26:27], s[68:69], 0, v[26:27]
	v_lshl_add_u64 v[26:27], v[26:27], 0, s[20:21]
	v_lshl_add_u64 v[26:27], v[26:27], 0, v[146:147]
	flat_store_dwordx4 v[26:27], v[12:15]
	s_nop 1
	v_add_f32_dpp v86, v25, v25 quad_perm:[1,0,3,2] row_mask:0xf bank_mask:0xf
	s_nop 1
	v_add_f32_dpp v86, v86, v86 quad_perm:[2,3,0,1] row_mask:0xf bank_mask:0xf
	s_nop 1
	v_add_f32_dpp v86, v86, v86 row_half_mirror row_mask:0xf bank_mask:0xf
	s_nop 1
	v_add_f32_dpp v86, v86, v86 row_mirror row_mask:0xf bank_mask:0xf
	s_nop 1
	v_add_f32_dpp v86, v86, v86 row_bcast:15 row_mask:0xa bank_mask:0xf
	s_waitcnt lgkmcnt(0)
	s_waitcnt lgkmcnt(0)
	s_waitcnt lgkmcnt(0)
	s_waitcnt lgkmcnt(0)
	s_and_saveexec_b64 s[20:21], s[98:99]
	s_cbranch_execz .LBB0_284
	v_lshl_add_u64 v[14:15], v[20:21], 4, s[78:79]
	v_lshl_add_u64 v[14:15], s[6:7], 2, v[14:15]
	s_waitcnt lgkmcnt(0)
	v_mov_b32_e32 v12, v86
	flat_store_dword v[14:15], v12

; #define MFMA16(a, b, c) __builtin_amdgcn_mfma_f32_16x16x32_bf16((a), (b), (c), 0, 0, 0)
; DI bf16x8 ldfrag(const char* lds, int row, int chunk) { return *(const bf16x8*)(lds + swz(row, chunk)); }
; template <bool RSTD, bool SWAP>
; DI void gemm_tile(gacc_t& acc, const bf16_t* __restrict__ A, int lda, const bf16_t* __restrict__ Bt, int ldb, int K,
;                   char* lds, int tid, int wr, int wc, int lane, const float* ssq_row) {
;     ...
;     GEMM_ISSUE(0, 0);
;     if (RSTD && tid < 256) {
;         const f32x4 q = *(const f32x4*)ssq_row;
;         ((float*)(lds + RSTD_OFF))[tid] = 1.0f / sqrtf(((q.x + q.y) + (q.z + q.w)) * (1.0f / 1024.0f) + 1e-6f);
;     }
;     asm volatile("s_waitcnt vmcnt(0)" ::: "memory");
;     __syncthreads();
;     for (int kt = 0; kt < nk; ++kt) {
;         const char* cur = lds + (kt & 1) * 65536;
;         if (kt + 1 < nk) GEMM_ISSUE(kt + 1, (kt + 1) & 1);
;         bf16x8 bfr[2][4], afr[3];
; #pragma unroll
;         for (int n = 0; n < 4; ++n) bfr[0][n] = ldfrag(cur + 32768, wc * 64 + n * 16 + fr, fq);
;         afr[0] = ldfrag(cur, wr * 128 + fr, fq);
;         afr[1] = ldfrag(cur, wr * 128 + 16 + fr, fq);
; #pragma unroll
;         for (int idx = 0; idx < 16; ++idx) {
;             const int ks = idx >> 3, m = idx & 7;
;             if (idx < 14) afr[(idx + 2) % 3] = ldfrag(cur, wr * 128 + ((idx + 2) & 7) * 16 + fr, ((idx + 2) >> 3) * 4 + fq);
;             if (ks == 0 && m >= 2 && m < 6) bfr[1][m - 2] = ldfrag(cur + 32768, wc * 64 + (m - 2) * 16 + fr, 4 + fq);
; #pragma unroll
;             for (int n = 0; n < 4; ++n) acc[m][n] = SWAP ? MFMA16(bfr[ks][n], afr[idx % 3], acc[m][n]) : MFMA16(afr[idx % 3], bfr[ks][n], acc[m][n]);
.LBB0_373:
	s_and_b32 s20, s18, 0x10000
	v_lshl_add_u64 v[162:163], v[138:139], 0, s[6:7]
	s_add_i32 s20, s22, s20
	v_lshl_add_u64 v[164:165], v[136:137], 0, s[6:7]
	v_lshl_add_u64 v[166:167], v[162:163], 0, s[94:95]
	s_add_i32 s21, s20, 0x8000
	s_mov_b32 m0, s20
	v_lshl_add_u64 v[172:173], v[164:165], 0, s[14:15]
	global_load_lds_dwordx4 v[166:167], off
	v_mfma_f32_16x16x32_bf16 v[60:63], v[210:213], v[236:239], v[60:63]
	s_mov_b32 m0, s21
	v_lshl_add_u64 v[174:175], v[162:163], 0, s[96:97]
	global_load_lds_dwordx4 v[172:173], off
	v_mfma_f32_16x16x32_bf16 v[56:59], v[214:217], v[236:239], v[56:59]
	s_add_i32 m0, s20, 0x2000
	v_lshl_add_u64 v[176:177], v[164:165], 0, s[72:73]
	global_load_lds_dwordx4 v[174:175], off
	v_mfma_f32_16x16x32_bf16 v[52:55], v[218:221], v[236:239], v[52:55]
	s_add_i32 m0, s20, 0xa000
	v_lshl_add_u64 v[178:179], v[162:163], 0, s[80:81]
	global_load_lds_dwordx4 v[176:177], off
	v_mfma_f32_16x16x32_bf16 v[48:51], v[222:225], v[236:239], v[48:51]
	s_add_i32 m0, s20, 0x4000
	v_lshl_add_u64 v[180:181], v[164:165], 0, s[76:77]
	global_load_lds_dwordx4 v[178:179], off
	v_mfma_f32_16x16x32_bf16 v[44:47], v[210:213], v[240:243], v[44:47]
	s_add_i32 m0, s20, 0xc000
	v_lshl_add_u64 v[162:163], v[162:163], 0, s[82:83]
	global_load_lds_dwordx4 v[180:181], off
	v_mfma_f32_16x16x32_bf16 v[40:43], v[214:217], v[240:243], v[40:43]
	s_add_i32 m0, s20, 0x6000
	v_lshl_add_u64 v[164:165], v[164:165], 0, s[0:1]
	global_load_lds_dwordx4 v[162:163], off
	v_mfma_f32_16x16x32_bf16 v[36:39], v[218:221], v[240:243], v[36:39]
	s_add_i32 m0, s20, 0xe000
	s_add_i32 s19, s18, 0xffff0000
	global_load_lds_dwordx4 v[164:165], off
	v_mfma_f32_16x16x32_bf16 v[32:35], v[222:225], v[240:243], v[32:35]
	s_and_b32 s19, s19, 0x10000
	s_add_i32 s19, s19, 0
	v_add_u32_e32 v146, s19, v144
	v_add3_u32 v166, v146, v150, v151
	ds_read_b128 v[162:165], v166 offset:32768
	ds_read_b128 v[186:189], v166 offset:34816
	ds_read_b128 v[194:197], v166 offset:36864
	ds_read_b128 v[198:201], v166 offset:38912
	v_add_u32_e32 v167, v146, v148
	ds_read_b128 v[190:193], v167
	ds_read_b128 v[202:205], v167 offset:2048
	v_add_u32_e32 v166, v146, v152
	ds_read_b128 v[206:209], v167 offset:4096
	v_mfma_f32_16x16x32_bf16 v[28:31], v[210:213], v[244:247], v[28:31]
	v_mfma_f32_16x16x32_bf16 v[24:27], v[214:217], v[244:247], v[24:27]
	v_mfma_f32_16x16x32_bf16 v[20:23], v[218:221], v[244:247], v[20:23]
	v_mfma_f32_16x16x32_bf16 v[16:19], v[222:225], v[244:247], v[16:19]
	v_mfma_f32_16x16x32_bf16 v[12:15], v[210:213], v[248:251], v[12:15]
	v_mfma_f32_16x16x32_bf16 v[8:11], v[214:217], v[248:251], v[8:11]
	v_mfma_f32_16x16x32_bf16 v[4:7], v[218:221], v[248:251], v[4:7]
	v_mfma_f32_16x16x32_bf16 v[0:3], v[222:225], v[248:251], v[0:3]
	s_waitcnt lgkmcnt(2)
	v_mfma_f32_16x16x32_bf16 v[124:127], v[162:165], v[190:193], v[124:127]
	v_add_u32_e32 v146, v146, v154
	v_mfma_f32_16x16x32_bf16 v[120:123], v[186:189], v[190:193], v[120:123]
	v_mfma_f32_16x16x32_bf16 v[116:119], v[194:197], v[190:193], v[116:119]
	v_mfma_f32_16x16x32_bf16 v[112:115], v[198:201], v[190:193], v[112:115]
	ds_read_b128 v[190:193], v166
	v_add_u32_e32 v166, s19, v149
	v_add_u32_e32 v172, v166, v153
	s_waitcnt lgkmcnt(2)
	v_mfma_f32_16x16x32_bf16 v[108:111], v[162:165], v[202:205], v[108:111]
	v_mfma_f32_16x16x32_bf16 v[104:107], v[186:189], v[202:205], v[104:107]
	v_mfma_f32_16x16x32_bf16 v[100:103], v[194:197], v[202:205], v[100:103]
	v_mfma_f32_16x16x32_bf16 v[96:99], v[198:201], v[202:205], v[96:99]
	ds_read_b128 v[202:205], v167 offset:8192
	ds_read_b128 v[210:213], v172 offset:32768
	s_waitcnt lgkmcnt(3)
	v_mfma_f32_16x16x32_bf16 v[92:95], v[162:165], v[206:209], v[92:95]
	v_mfma_f32_16x16x32_bf16 v[88:91], v[186:189], v[206:209], v[88:91]
	v_mfma_f32_16x16x32_bf16 v[84:87], v[194:197], v[206:209], v[84:87]
	v_mfma_f32_16x16x32_bf16 v[80:83], v[198:201], v[206:209], v[80:83]
	ds_read_b128 v[206:209], v167 offset:10240
	ds_read_b128 v[214:217], v172 offset:34816
	s_waitcnt lgkmcnt(4)
	v_mfma_f32_16x16x32_bf16 v[76:79], v[162:165], v[190:193], v[76:79]
	v_mfma_f32_16x16x32_bf16 v[72:75], v[186:189], v[190:193], v[72:75]
	v_mfma_f32_16x16x32_bf16 v[68:71], v[194:197], v[190:193], v[68:71]
	v_mfma_f32_16x16x32_bf16 v[64:67], v[198:201], v[190:193], v[64:67]
	ds_read_b128 v[190:193], v167 offset:12288
	v_add_u32_e32 v167, v166, v155
	ds_read_b128 v[218:221], v172 offset:36864
	s_waitcnt lgkmcnt(5)
	v_mfma_f32_16x16x32_bf16 v[60:63], v[162:165], v[202:205], v[60:63]
	v_mfma_f32_16x16x32_bf16 v[56:59], v[186:189], v[202:205], v[56:59]
	v_mfma_f32_16x16x32_bf16 v[52:55], v[194:197], v[202:205], v[52:55]
	v_mfma_f32_16x16x32_bf16 v[48:51], v[198:201], v[202:205], v[48:51]
	ds_read_b128 v[222:225], v167 offset:38912
	ds_read_b128 v[202:205], v146
	v_add_u32_e32 v146, v166, v148
	s_waitcnt lgkmcnt(5)
	v_mfma_f32_16x16x32_bf16 v[44:47], v[162:165], v[206:209], v[44:47]
	v_add_u32_e32 v167, v166, v152
	v_mfma_f32_16x16x32_bf16 v[40:43], v[186:189], v[206:209], v[40:43]
	v_mfma_f32_16x16x32_bf16 v[36:39], v[194:197], v[206:209], v[36:39]
	v_mfma_f32_16x16x32_bf16 v[32:35], v[198:201], v[206:209], v[32:35]
	ds_read_b128 v[206:209], v146
	s_waitcnt lgkmcnt(4)
	v_mfma_f32_16x16x32_bf16 v[28:31], v[162:165], v[190:193], v[28:31]
	v_mfma_f32_16x16x32_bf16 v[24:27], v[186:189], v[190:193], v[24:27]
	v_mfma_f32_16x16x32_bf16 v[20:23], v[194:197], v[190:193], v[20:23]
	v_mfma_f32_16x16x32_bf16 v[16:19], v[198:201], v[190:193], v[16:19]
	ds_read_b128 v[190:193], v146 offset:2048
	s_waitcnt lgkmcnt(2)
; #define MFMA16(a, b, c) __builtin_amdgcn_mfma_f32_16x16x32_bf16((a), (b), (c), 0, 0, 0)
; DI bf16x8 ldfrag(const char* lds, int row, int chunk) { return *(const bf16x8*)(lds + swz(row, chunk)); }
; #define GEMM_SG1() do { __builtin_amdgcn_sched_group_barrier(0x100, 1, 0); __builtin_amdgcn_sched_group_barrier(0x008, 4, 0); } while (0)
; #define GEMM_SG2() do { __builtin_amdgcn_sched_group_barrier(0x100, 2, 0); __builtin_amdgcn_sched_group_barrier(0x008, 4, 0); } while (0)
; template <bool RSTD, bool SWAP>
; DI void gemm_tile(gacc_t& acc, const bf16_t* __restrict__ A, int lda, const bf16_t* __restrict__ Bt, int ldb, int K,
;                   char* lds, int tid, int wr, int wc, int lane, const float* ssq_row) {
;     ...
;     for (int kt = 0; kt < nk; ++kt) {
;         const char* cur = lds + (kt & 1) * 65536;
;         if (kt + 1 < nk) GEMM_ISSUE(kt + 1, (kt + 1) & 1);
;         bf16x8 bfr[2][4], afr[3];
; #pragma unroll
;         for (int n = 0; n < 4; ++n) bfr[0][n] = ldfrag(cur + 32768, wc * 64 + n * 16 + fr, fq);
;         afr[0] = ldfrag(cur, wr * 128 + fr, fq);
;         afr[1] = ldfrag(cur, wr * 128 + 16 + fr, fq);
; #pragma unroll
;         for (int idx = 0; idx < 16; ++idx) {
;             const int ks = idx >> 3, m = idx & 7;
;             if (idx < 14) afr[(idx + 2) % 3] = ldfrag(cur, wr * 128 + ((idx + 2) & 7) * 16 + fr, ((idx + 2) >> 3) * 4 + fq);
;             if (ks == 0 && m >= 2 && m < 6) bfr[1][m - 2] = ldfrag(cur + 32768, wc * 64 + (m - 2) * 16 + fr, 4 + fq);
; #pragma unroll
;             for (int n = 0; n < 4; ++n) acc[m][n] = SWAP ? MFMA16(bfr[ks][n], afr[idx % 3], acc[m][n]) : MFMA16(afr[idx % 3], bfr[ks][n], acc[m][n]);
;         }
;         __builtin_amdgcn_sched_group_barrier(0x100, 6, 0);
;     ...
;         GEMM_SG1(); GEMM_SG1(); GEMM_SG2(); GEMM_SG2(); GEMM_SG2(); GEMM_SG2(); GEMM_SG1(); GEMM_SG1();
;         GEMM_SG1(); GEMM_SG1(); GEMM_SG1(); GEMM_SG1(); GEMM_SG1(); GEMM_SG1();
;         __builtin_amdgcn_sched_group_barrier(0x008, 8, 0);
;         __builtin_amdgcn_sched_barrier(0);
;         asm volatile("s_waitcnt vmcnt(0)" ::: "memory");
;         __syncthreads();
	v_mfma_f32_16x16x32_bf16 v[12:15], v[162:165], v[202:205], v[12:15]
	v_mfma_f32_16x16x32_bf16 v[8:11], v[186:189], v[202:205], v[8:11]
	v_mfma_f32_16x16x32_bf16 v[4:7], v[194:197], v[202:205], v[4:7]
	v_mfma_f32_16x16x32_bf16 v[0:3], v[198:201], v[202:205], v[0:3]
	ds_read_b128 v[162:165], v146 offset:4096
	s_waitcnt lgkmcnt(2)
	v_mfma_f32_16x16x32_bf16 v[124:127], v[210:213], v[206:209], v[124:127]
	v_mfma_f32_16x16x32_bf16 v[120:123], v[214:217], v[206:209], v[120:123]
	v_mfma_f32_16x16x32_bf16 v[116:119], v[218:221], v[206:209], v[116:119]
	v_mfma_f32_16x16x32_bf16 v[112:115], v[222:225], v[206:209], v[112:115]
	ds_read_b128 v[186:189], v167
	s_waitcnt lgkmcnt(2)
	v_mfma_f32_16x16x32_bf16 v[108:111], v[210:213], v[190:193], v[108:111]
	v_mfma_f32_16x16x32_bf16 v[104:107], v[214:217], v[190:193], v[104:107]
	v_mfma_f32_16x16x32_bf16 v[100:103], v[218:221], v[190:193], v[100:103]
	v_mfma_f32_16x16x32_bf16 v[96:99], v[222:225], v[190:193], v[96:99]
	ds_read_b128 v[236:239], v146 offset:8192
	s_waitcnt lgkmcnt(2)
	v_mfma_f32_16x16x32_bf16 v[92:95], v[210:213], v[162:165], v[92:95]
	v_mfma_f32_16x16x32_bf16 v[88:91], v[214:217], v[162:165], v[88:91]
	v_mfma_f32_16x16x32_bf16 v[84:87], v[218:221], v[162:165], v[84:87]
	v_mfma_f32_16x16x32_bf16 v[80:83], v[222:225], v[162:165], v[80:83]
	ds_read_b128 v[240:243], v146 offset:10240
	ds_read_b128 v[244:247], v146 offset:12288
	v_add_u32_e32 v146, v166, v154
	ds_read_b128 v[248:251], v146
	s_waitcnt lgkmcnt(4)
	v_mfma_f32_16x16x32_bf16 v[76:79], v[210:213], v[186:189], v[76:79]
	v_mfma_f32_16x16x32_bf16 v[72:75], v[214:217], v[186:189], v[72:75]
	v_mfma_f32_16x16x32_bf16 v[68:71], v[218:221], v[186:189], v[68:71]
	v_mfma_f32_16x16x32_bf16 v[64:67], v[222:225], v[186:189], v[64:67]
	s_waitcnt lgkmcnt(0)
	s_waitcnt vmcnt(0)
	s_add_u32 s6, s6, 0x80
	s_addc_u32 s7, s7, 0
	s_add_i32 s18, s18, 0x10000
	s_cmpk_lg_i32 s6, 0x780
	s_waitcnt vmcnt(0)
	s_cbranch_scc1 .Lkhead_373
	s_barrier
	v_mfma_f32_16x16x32_bf16 v[60:63], v[210:213], v[236:239], v[60:63]
	v_mfma_f32_16x16x32_bf16 v[56:59], v[214:217], v[236:239], v[56:59]
	v_mfma_f32_16x16x32_bf16 v[52:55], v[218:221], v[236:239], v[52:55]
	v_mfma_f32_16x16x32_bf16 v[48:51], v[222:225], v[236:239], v[48:51]
	v_mfma_f32_16x16x32_bf16 v[44:47], v[210:213], v[240:243], v[44:47]
	v_mfma_f32_16x16x32_bf16 v[40:43], v[214:217], v[240:243], v[40:43]
	v_mfma_f32_16x16x32_bf16 v[36:39], v[218:221], v[240:243], v[36:39]
	v_mfma_f32_16x16x32_bf16 v[32:35], v[222:225], v[240:243], v[32:35]
	v_mfma_f32_16x16x32_bf16 v[28:31], v[210:213], v[244:247], v[28:31]
	v_mfma_f32_16x16x32_bf16 v[24:27], v[214:217], v[244:247], v[24:27]
	v_mfma_f32_16x16x32_bf16 v[20:23], v[218:221], v[244:247], v[20:23]
	v_mfma_f32_16x16x32_bf16 v[16:19], v[222:225], v[244:247], v[16:19]
	v_mfma_f32_16x16x32_bf16 v[12:15], v[210:213], v[248:251], v[12:15]
	v_mfma_f32_16x16x32_bf16 v[8:11], v[214:217], v[248:251], v[8:11]
	v_mfma_f32_16x16x32_bf16 v[4:7], v[218:221], v[248:251], v[4:7]
	v_mfma_f32_16x16x32_bf16 v[0:3], v[222:225], v[248:251], v[0:3]
	ds_read_b128 v[136:139], v161
	ds_read_b128 v[162:165], v161 offset:2048
	ds_read_b128 v[190:193], v161 offset:4096
	ds_read_b128 v[194:197], v161 offset:6144
	v_add_u32_e32 v146, v156, v148
	ds_read_b128 v[186:189], v146
	ds_read_b128 v[198:201], v146 offset:2048
	v_add_u32_e32 v166, v156, v152
	ds_read_b128 v[202:205], v146 offset:4096
	s_waitcnt lgkmcnt(2)
	v_mfma_f32_16x16x32_bf16 v[124:127], v[136:139], v[186:189], v[124:127]
	s_sext_i32_i8 s6, s16
	v_mfma_f32_16x16x32_bf16 v[120:123], v[162:165], v[186:189], v[120:123]
	v_mfma_f32_16x16x32_bf16 v[116:119], v[190:193], v[186:189], v[116:119]
	v_mfma_f32_16x16x32_bf16 v[112:115], v[194:197], v[186:189], v[112:115]
	ds_read_b128 v[186:189], v166
	v_add_u32_e32 v166, v157, v153
	s_waitcnt lgkmcnt(2)
	v_mfma_f32_16x16x32_bf16 v[108:111], v[136:139], v[198:201], v[108:111]
	v_mfma_f32_16x16x32_bf16 v[104:107], v[162:165], v[198:201], v[104:107]
	v_mfma_f32_16x16x32_bf16 v[100:103], v[190:193], v[198:201], v[100:103]
	v_mfma_f32_16x16x32_bf16 v[96:99], v[194:197], v[198:201], v[96:99]
	ds_read_b128 v[198:201], v146 offset:8192
	ds_read_b128 v[206:209], v166
	s_waitcnt lgkmcnt(3)
	v_mfma_f32_16x16x32_bf16 v[92:95], v[136:139], v[202:205], v[92:95]
	v_mfma_f32_16x16x32_bf16 v[88:91], v[162:165], v[202:205], v[88:91]
	v_mfma_f32_16x16x32_bf16 v[84:87], v[190:193], v[202:205], v[84:87]
	v_mfma_f32_16x16x32_bf16 v[80:83], v[194:197], v[202:205], v[80:83]
	ds_read_b128 v[202:205], v146 offset:10240
	ds_read_b128 v[210:213], v166 offset:2048
	s_waitcnt lgkmcnt(4)
	v_mfma_f32_16x16x32_bf16 v[76:79], v[136:139], v[186:189], v[76:79]
	v_mfma_f32_16x16x32_bf16 v[72:75], v[162:165], v[186:189], v[72:75]
	v_mfma_f32_16x16x32_bf16 v[68:71], v[190:193], v[186:189], v[68:71]
	v_mfma_f32_16x16x32_bf16 v[64:67], v[194:197], v[186:189], v[64:67]
	ds_read_b128 v[186:189], v146 offset:12288
	v_add_u32_e32 v146, v156, v154
	ds_read_b128 v[214:217], v166 offset:4096
	s_waitcnt lgkmcnt(5)
	v_mfma_f32_16x16x32_bf16 v[60:63], v[136:139], v[198:201], v[60:63]
	v_mfma_f32_16x16x32_bf16 v[56:59], v[162:165], v[198:201], v[56:59]
	v_mfma_f32_16x16x32_bf16 v[52:55], v[190:193], v[198:201], v[52:55]
	v_mfma_f32_16x16x32_bf16 v[48:51], v[194:197], v[198:201], v[48:51]
	ds_read_b128 v[198:201], v146
	v_add_u32_e32 v146, v157, v155
	ds_read_b128 v[218:221], v146 offset:6144
	v_add_u32_e32 v146, v158, v148
	s_waitcnt lgkmcnt(5)
	v_mfma_f32_16x16x32_bf16 v[44:47], v[136:139], v[202:205], v[44:47]
	v_mfma_f32_16x16x32_bf16 v[40:43], v[162:165], v[202:205], v[40:43]
	v_mfma_f32_16x16x32_bf16 v[36:39], v[190:193], v[202:205], v[36:39]
	v_mfma_f32_16x16x32_bf16 v[32:35], v[194:197], v[202:205], v[32:35]
	ds_read_b128 v[202:205], v146
	s_waitcnt lgkmcnt(4)
; #define MFMA16(a, b, c) __builtin_amdgcn_mfma_f32_16x16x32_bf16((a), (b), (c), 0, 0, 0)
; DI bf16x8 ldfrag(const char* lds, int row, int chunk) { return *(const bf16x8*)(lds + swz(row, chunk)); }
; template <bool RSTD, bool SWAP>
; DI void gemm_tile(gacc_t& acc, const bf16_t* __restrict__ A, int lda, const bf16_t* __restrict__ Bt, int ldb, int K,
;                   char* lds, int tid, int wr, int wc, int lane, const float* ssq_row) {
;     ...
;         for (int idx = 0; idx < 16; ++idx) {
;             const int ks = idx >> 3, m = idx & 7;
;             if (idx < 14) afr[(idx + 2) % 3] = ldfrag(cur, wr * 128 + ((idx + 2) & 7) * 16 + fr, ((idx + 2) >> 3) * 4 + fq);
;             if (ks == 0 && m >= 2 && m < 6) bfr[1][m - 2] = ldfrag(cur + 32768, wc * 64 + (m - 2) * 16 + fr, 4 + fq);
; #pragma unroll
;             for (int n = 0; n < 4; ++n) acc[m][n] = SWAP ? MFMA16(bfr[ks][n], afr[idx % 3], acc[m][n]) : MFMA16(afr[idx % 3], bfr[ks][n], acc[m][n]);
;         }
;         __builtin_amdgcn_sched_group_barrier(0x100, 6, 0);
;     ...
;         GEMM_SG1(); GEMM_SG1(); GEMM_SG2(); GEMM_SG2(); GEMM_SG2(); GEMM_SG2(); GEMM_SG1(); GEMM_SG1();
;         GEMM_SG1(); GEMM_SG1(); GEMM_SG1(); GEMM_SG1(); GEMM_SG1(); GEMM_SG1();
;         __builtin_amdgcn_sched_group_barrier(0x008, 8, 0);
;         __builtin_amdgcn_sched_barrier(0);
;         asm volatile("s_waitcnt vmcnt(0)" ::: "memory");
;         __syncthreads();
;     DI void operator()(gacc_t& acc, int pm, int pn, char* lds, int tid, int wr, int wc, int lane) const {
;         asm volatile("" : "+v"(tid), "+v"(lane));
;         const int fr = lane & 15, fq = lane >> 4;
;         char* lbase = lds + (wr * 128 + fr) * 528 + (wc * 64 + 4 * fq) * 2;
;         const float* rl = (const float*)(lds + RSTD_OFF) + wr * 128 + fr;
; #pragma unroll
;         for (int m = 0; m < 8; ++m) {
;             const float r = rl[m * 16];
; #pragma unroll
;             for (int n = 0; n < 4; ++n) {
;                 float g[4];
; #pragma unroll
;                 for (int j = 0; j < 4; ++j) {
;                     const float x = acc[m][n][j] * r;
;                     const float u = 0.7978845608028654f * (x + 0.044715f * x * x * x);
;                     const float e = __builtin_amdgcn_exp2f(-2.885390081777927f * u);
;                     g[j] = x * __builtin_amdgcn_rcpf(1.0f + e);
;                 }
	v_mfma_f32_16x16x32_bf16 v[28:31], v[136:139], v[186:189], v[28:31]
	v_mfma_f32_16x16x32_bf16 v[24:27], v[162:165], v[186:189], v[24:27]
	v_mfma_f32_16x16x32_bf16 v[20:23], v[190:193], v[186:189], v[20:23]
	v_mfma_f32_16x16x32_bf16 v[16:19], v[194:197], v[186:189], v[16:19]
	ds_read_b128 v[186:189], v146 offset:2048
	s_waitcnt lgkmcnt(3)
	v_mfma_f32_16x16x32_bf16 v[12:15], v[136:139], v[198:201], v[12:15]
	v_mfma_f32_16x16x32_bf16 v[8:11], v[162:165], v[198:201], v[8:11]
	v_mfma_f32_16x16x32_bf16 v[4:7], v[190:193], v[198:201], v[4:7]
	v_mfma_f32_16x16x32_bf16 v[0:3], v[194:197], v[198:201], v[0:3]
	ds_read_b128 v[136:139], v146 offset:4096
	s_waitcnt lgkmcnt(2)
	v_mfma_f32_16x16x32_bf16 v[162:165], v[206:209], v[202:205], v[124:127]
	s_nop 2
	v_add_u32_e32 v124, v158, v152
	v_mfma_f32_16x16x32_bf16 v[120:123], v[210:213], v[202:205], v[120:123]
	v_mfma_f32_16x16x32_bf16 v[116:119], v[214:217], v[202:205], v[116:119]
	v_mfma_f32_16x16x32_bf16 v[112:115], v[218:221], v[202:205], v[112:115]
	ds_read_b128 v[124:127], v124
	s_waitcnt lgkmcnt(2)
	v_mfma_f32_16x16x32_bf16 v[108:111], v[206:209], v[186:189], v[108:111]
	v_mfma_f32_16x16x32_bf16 v[104:107], v[210:213], v[186:189], v[104:107]
	v_mfma_f32_16x16x32_bf16 v[100:103], v[214:217], v[186:189], v[100:103]
	v_mfma_f32_16x16x32_bf16 v[96:99], v[218:221], v[186:189], v[96:99]
	ds_read_b128 v[186:189], v146 offset:8192
	s_waitcnt lgkmcnt(2)
	v_mfma_f32_16x16x32_bf16 v[92:95], v[206:209], v[136:139], v[92:95]
	v_mfma_f32_16x16x32_bf16 v[88:91], v[210:213], v[136:139], v[88:91]
	v_mfma_f32_16x16x32_bf16 v[84:87], v[214:217], v[136:139], v[84:87]
	v_mfma_f32_16x16x32_bf16 v[80:83], v[218:221], v[136:139], v[80:83]
	ds_read_b128 v[136:139], v146 offset:10240
	s_waitcnt lgkmcnt(2)
	v_mfma_f32_16x16x32_bf16 v[76:79], v[206:209], v[124:127], v[76:79]
	v_mfma_f32_16x16x32_bf16 v[72:75], v[210:213], v[124:127], v[72:75]
	v_mfma_f32_16x16x32_bf16 v[68:71], v[214:217], v[124:127], v[68:71]
	v_mfma_f32_16x16x32_bf16 v[64:67], v[218:221], v[124:127], v[64:67]
	ds_read_b128 v[124:127], v146 offset:12288
	v_add_u32_e32 v146, v158, v154
	s_waitcnt lgkmcnt(2)
	v_mfma_f32_16x16x32_bf16 v[60:63], v[206:209], v[186:189], v[60:63]
	v_mfma_f32_16x16x32_bf16 v[56:59], v[210:213], v[186:189], v[56:59]
	v_mfma_f32_16x16x32_bf16 v[52:55], v[214:217], v[186:189], v[52:55]
	v_mfma_f32_16x16x32_bf16 v[48:51], v[218:221], v[186:189], v[48:51]
	ds_read_b128 v[186:189], v146
	s_waitcnt lgkmcnt(2)
	v_mfma_f32_16x16x32_bf16 v[44:47], v[206:209], v[136:139], v[44:47]
	v_mfma_f32_16x16x32_bf16 v[40:43], v[210:213], v[136:139], v[40:43]
	v_mfma_f32_16x16x32_bf16 v[36:39], v[214:217], v[136:139], v[36:39]
	v_mfma_f32_16x16x32_bf16 v[32:35], v[218:221], v[136:139], v[32:35]
	s_waitcnt lgkmcnt(1)
	v_mfma_f32_16x16x32_bf16 v[28:31], v[206:209], v[124:127], v[28:31]
	v_mfma_f32_16x16x32_bf16 v[24:27], v[210:213], v[124:127], v[24:27]
	v_mfma_f32_16x16x32_bf16 v[20:23], v[214:217], v[124:127], v[20:23]
	v_mfma_f32_16x16x32_bf16 v[16:19], v[218:221], v[124:127], v[16:19]
	s_waitcnt lgkmcnt(0)
	v_mfma_f32_16x16x32_bf16 v[12:15], v[206:209], v[186:189], v[12:15]
	v_mfma_f32_16x16x32_bf16 v[8:11], v[210:213], v[186:189], v[8:11]
	v_mfma_f32_16x16x32_bf16 v[4:7], v[214:217], v[186:189], v[4:7]
	v_mfma_f32_16x16x32_bf16 v[0:3], v[218:221], v[186:189], v[0:3]
	v_mov_b32_e32 v124, v141
	v_mov_b32_e32 v125, v140
	s_waitcnt vmcnt(0)
	s_barrier
	s_nop 0
	v_and_b32_e32 v127, 15, v124
	v_or_b32_e32 v126, v127, v145
	v_ashrrev_i32_e32 v124, 1, v124
	v_mul_lo_u32 v126, v126, s3
	v_and_b32_e32 v124, -8, v124
	v_lshl_add_u32 v127, v127, 2, v160
	v_add3_u32 v126, v159, v126, v124
	ds_read_b32 v124, v127
	s_waitcnt lgkmcnt(0)
	v_pk_mul_f32 v[136:137], v[162:163], v[124:125] op_sel_hi:[1,0]
	s_nop 0
	v_mul_f32_e32 v138, 0x3d372713, v136
	v_mul_f32_e32 v139, 0x3d372713, v137
	v_mul_f32_e32 v138, v136, v138
	v_mul_f32_e32 v139, v137, v139
	v_fma_f32 v138, v136, v138, v136
	v_fma_f32 v139, v137, v139, v137
	v_mul_f32_e32 v138, 0x3f4c422a, v138
	v_mul_f32_e32 v139, 0x3f4c422a, v139
	v_mul_f32_e32 v138, 0xc038aa3b, v138
	v_mul_f32_e32 v139, 0xc038aa3b, v139
	v_exp_f32_e32 v138, v138
	v_exp_f32_e32 v139, v139
	v_pk_mul_f32 v[120:121], v[120:121], v[124:125] op_sel_hi:[1,0]
	v_pk_mul_f32 v[122:123], v[122:123], v[124:125] op_sel_hi:[1,0]
	v_add_f32_e32 v138, 1.0, v138
	v_add_f32_e32 v139, 1.0, v139
	v_rcp_f32_e32 v138, v138
	v_rcp_f32_e32 v139, v139
	v_pk_mul_f32 v[116:117], v[116:117], v[124:125] op_sel_hi:[1,0]
	v_pk_mul_f32 v[118:119], v[118:119], v[124:125] op_sel_hi:[1,0]
	v_pk_mul_f32 v[112:113], v[112:113], v[124:125] op_sel_hi:[1,0]
	v_pk_mul_f32 v[136:137], v[136:137], v[138:139]
	v_pk_mul_f32 v[138:139], v[164:165], v[124:125] op_sel_hi:[1,0]
	v_cvt_pk_bf16_f32 v136, v136, v137
	v_mul_f32_e32 v146, 0x3d372713, v138
	v_mul_f32_e32 v146, v138, v146
	v_fma_f32 v146, v138, v146, v138
	v_mul_f32_e32 v146, 0x3f4c422a, v146
	v_mul_f32_e32 v146, 0xc038aa3b, v146
	v_exp_f32_e32 v146, v146
	v_pk_mul_f32 v[114:115], v[114:115], v[124:125] op_sel_hi:[1,0]
	v_add_f32_e32 v146, 1.0, v146
	v_rcp_f32_e32 v162, v146
	v_mul_f32_e32 v146, 0x3d372713, v139
	v_mul_f32_e32 v146, v139, v146
	v_fma_f32 v146, v139, v146, v139
	v_mul_f32_e32 v146, 0x3f4c422a, v146
	v_mul_f32_e32 v146, 0xc038aa3b, v146
	v_exp_f32_e32 v146, v146
	s_nop 0
	v_add_f32_e32 v146, 1.0, v146
	v_rcp_f32_e32 v163, v146
	s_nop 0
	v_pk_mul_f32 v[138:139], v[138:139], v[162:163]
	s_nop 0
	v_cvt_pk_bf16_f32 v137, v138, v139
	v_mul_f32_e32 v138, 0x3d372713, v120
	v_mul_f32_e32 v139, 0x3d372713, v121
	v_mul_f32_e32 v138, v120, v138
	v_mul_f32_e32 v139, v121, v139
	v_fma_f32 v138, v120, v138, v120
; DI unsigned pk2(float a, float b) { f32x2 v = {a, b}; bf16x2_t r = __builtin_convertvector(v, bf16x2_t); return __builtin_bit_cast(unsigned, r); }
;     DI void operator()(gacc_t& acc, int pm, int pn, char* lds, int tid, int wr, int wc, int lane) const {
;     ...
;         for (int m = 0; m < 8; ++m) {
;             const float r = rl[m * 16];
; #pragma unroll
;             for (int n = 0; n < 4; ++n) {
;                 float g[4];
; #pragma unroll
;                 for (int j = 0; j < 4; ++j) {
;                     const float x = acc[m][n][j] * r;
;                     const float u = 0.7978845608028654f * (x + 0.044715f * x * x * x);
;                     const float e = __builtin_amdgcn_exp2f(-2.885390081777927f * u);
;                     g[j] = x * __builtin_amdgcn_rcpf(1.0f + e);
;                 }
;                 u32x2 w; w.x = pk2(g[0], g[1]); w.y = pk2(g[2], g[3]);
;                 *(u32x2*)(lbase + m * 16 * 528 + n * 32) = w;
;             }
	v_fma_f32 v139, v121, v139, v121
	v_mul_f32_e32 v138, 0x3f4c422a, v138
	v_mul_f32_e32 v139, 0x3f4c422a, v139
	v_mul_f32_e32 v138, 0xc038aa3b, v138
	v_mul_f32_e32 v139, 0xc038aa3b, v139
	v_exp_f32_e32 v138, v138
	v_exp_f32_e32 v139, v139
	v_add_f32_e32 v138, 1.0, v138
	v_add_f32_e32 v139, 1.0, v139
	v_rcp_f32_e32 v138, v138
	v_rcp_f32_e32 v139, v139
	s_nop 0
	v_pk_mul_f32 v[120:121], v[120:121], v[138:139]
	v_mul_f32_e32 v138, 0x3d372713, v122
	v_mul_f32_e32 v139, 0x3d372713, v123
	v_mul_f32_e32 v138, v122, v138
	v_mul_f32_e32 v139, v123, v139
	v_fma_f32 v138, v122, v138, v122
	v_fma_f32 v139, v123, v139, v123
	v_mul_f32_e32 v138, 0x3f4c422a, v138
	v_mul_f32_e32 v139, 0x3f4c422a, v139
	v_mul_f32_e32 v138, 0xc038aa3b, v138
	v_mul_f32_e32 v139, 0xc038aa3b, v139
	v_exp_f32_e32 v138, v138
	v_exp_f32_e32 v139, v139
	v_cvt_pk_bf16_f32 v120, v120, v121
	v_add_f32_e32 v138, 1.0, v138
	v_add_f32_e32 v139, 1.0, v139
	v_rcp_f32_e32 v138, v138
	v_rcp_f32_e32 v139, v139
	s_nop 0
	v_pk_mul_f32 v[122:123], v[122:123], v[138:139]
	s_nop 0
	v_cvt_pk_bf16_f32 v121, v122, v123
	ds_write2_b64 v126, v[136:137], v[120:121] offset1:4
	v_mul_f32_e32 v120, 0x3d372713, v116
	v_mul_f32_e32 v121, 0x3d372713, v117
	v_mul_f32_e32 v120, v116, v120
	v_mul_f32_e32 v121, v117, v121
	v_fma_f32 v120, v116, v120, v116
	v_fma_f32 v121, v117, v121, v117
	v_mul_f32_e32 v120, 0x3f4c422a, v120
	v_mul_f32_e32 v121, 0x3f4c422a, v121
	v_mul_f32_e32 v120, 0xc038aa3b, v120
	v_mul_f32_e32 v121, 0xc038aa3b, v121
	v_exp_f32_e32 v120, v120
	v_exp_f32_e32 v121, v121
	v_add_f32_e32 v120, 1.0, v120
	v_add_f32_e32 v121, 1.0, v121
	v_rcp_f32_e32 v120, v120
	v_rcp_f32_e32 v121, v121
	s_nop 0
	v_pk_mul_f32 v[116:117], v[116:117], v[120:121]
	v_mul_f32_e32 v120, 0x3d372713, v118
	v_mul_f32_e32 v121, 0x3d372713, v119
	v_mul_f32_e32 v120, v118, v120
	v_mul_f32_e32 v121, v119, v121
	v_fma_f32 v120, v118, v120, v118
	v_fma_f32 v121, v119, v121, v119
	v_mul_f32_e32 v120, 0x3f4c422a, v120
	v_mul_f32_e32 v121, 0x3f4c422a, v121
	v_mul_f32_e32 v120, 0xc038aa3b, v120
	v_mul_f32_e32 v121, 0xc038aa3b, v121
	v_exp_f32_e32 v120, v120
	v_exp_f32_e32 v121, v121
	v_cvt_pk_bf16_f32 v116, v116, v117
	v_add_f32_e32 v120, 1.0, v120
	v_add_f32_e32 v121, 1.0, v121
	v_rcp_f32_e32 v120, v120
	v_rcp_f32_e32 v121, v121
	s_nop 0
	v_pk_mul_f32 v[118:119], v[118:119], v[120:121]
	s_nop 0
	v_cvt_pk_bf16_f32 v117, v118, v119
	v_mul_f32_e32 v118, 0x3d372713, v112
	v_mul_f32_e32 v119, 0x3d372713, v113
	v_mul_f32_e32 v118, v112, v118
	v_mul_f32_e32 v119, v113, v119
	v_fma_f32 v118, v112, v118, v112
	v_fma_f32 v119, v113, v119, v113
	v_mul_f32_e32 v118, 0x3f4c422a, v118
	v_mul_f32_e32 v119, 0x3f4c422a, v119
	v_mul_f32_e32 v118, 0xc038aa3b, v118
	v_mul_f32_e32 v119, 0xc038aa3b, v119
	v_exp_f32_e32 v118, v118
	v_exp_f32_e32 v119, v119
	v_add_f32_e32 v118, 1.0, v118
	v_add_f32_e32 v119, 1.0, v119
	v_rcp_f32_e32 v118, v118
	v_rcp_f32_e32 v119, v119
	s_nop 0
	v_pk_mul_f32 v[112:113], v[112:113], v[118:119]
	v_mul_f32_e32 v118, 0x3d372713, v114
	v_mul_f32_e32 v119, 0x3d372713, v115
	v_mul_f32_e32 v118, v114, v118
	v_mul_f32_e32 v119, v115, v119
	v_fma_f32 v118, v114, v118, v114
	v_fma_f32 v119, v115, v119, v115
	v_mul_f32_e32 v118, 0x3f4c422a, v118
	v_mul_f32_e32 v119, 0x3f4c422a, v119
	v_mul_f32_e32 v118, 0xc038aa3b, v118
	v_mul_f32_e32 v119, 0xc038aa3b, v119
	v_exp_f32_e32 v118, v118
	v_exp_f32_e32 v119, v119
	v_cvt_pk_bf16_f32 v112, v112, v113
	v_add_f32_e32 v118, 1.0, v118
	v_add_f32_e32 v119, 1.0, v119
	v_rcp_f32_e32 v118, v118
	v_rcp_f32_e32 v119, v119
	s_nop 0
	v_pk_mul_f32 v[114:115], v[114:115], v[118:119]
	s_nop 0
	v_cvt_pk_bf16_f32 v113, v114, v115
	ds_write2_b64 v126, v[116:117], v[112:113] offset0:8 offset1:12
	ds_read_b32 v112, v127 offset:64
	s_waitcnt lgkmcnt(0)
	v_pk_mul_f32 v[108:109], v[108:109], v[112:113] op_sel_hi:[1,0]
	s_nop 0
	v_mul_f32_e32 v113, 0x3d372713, v108
	v_mul_f32_e32 v113, v108, v113
	v_fma_f32 v113, v108, v113, v108
	v_mul_f32_e32 v113, 0x3f4c422a, v113
	v_mul_f32_e32 v113, 0xc038aa3b, v113
	v_exp_f32_e32 v113, v113
	s_nop 0
	v_add_f32_e32 v113, 1.0, v113
	v_rcp_f32_e32 v114, v113
	v_mul_f32_e32 v113, 0x3d372713, v109
	v_mul_f32_e32 v113, v109, v113
	v_fma_f32 v113, v109, v113, v109
	v_mul_f32_e32 v113, 0x3f4c422a, v113
	v_mul_f32_e32 v113, 0xc038aa3b, v113
	v_exp_f32_e32 v113, v113
	s_nop 0
	v_add_f32_e32 v113, 1.0, v113
	v_pk_mul_f32 v[110:111], v[110:111], v[112:113] op_sel_hi:[1,0]
	v_rcp_f32_e32 v115, v113
	v_mul_f32_e32 v113, 0x3d372713, v110
	v_mul_f32_e32 v113, v110, v113
	v_fma_f32 v113, v110, v113, v110
	v_mul_f32_e32 v113, 0x3f4c422a, v113
	v_mul_f32_e32 v113, 0xc038aa3b, v113
	v_exp_f32_e32 v113, v113
	v_pk_mul_f32 v[108:109], v[108:109], v[114:115]
	v_add_f32_e32 v113, 1.0, v113
	v_rcp_f32_e32 v114, v113
	v_mul_f32_e32 v113, 0x3d372713, v111
	v_mul_f32_e32 v113, v111, v113
	v_fma_f32 v113, v111, v113, v111
	v_mul_f32_e32 v113, 0x3f4c422a, v113
	v_mul_f32_e32 v113, 0xc038aa3b, v113
	v_exp_f32_e32 v113, v113
	v_cvt_pk_bf16_f32 v108, v108, v109
	v_add_f32_e32 v113, 1.0, v113
	v_rcp_f32_e32 v115, v113
	v_pk_mul_f32 v[104:105], v[104:105], v[112:113] op_sel_hi:[1,0]
	v_pk_mul_f32 v[106:107], v[106:107], v[112:113] op_sel_hi:[1,0]
	v_pk_mul_f32 v[100:101], v[100:101], v[112:113] op_sel_hi:[1,0]
	v_pk_mul_f32 v[110:111], v[110:111], v[114:115]
	v_pk_mul_f32 v[102:103], v[102:103], v[112:113] op_sel_hi:[1,0]
	v_cvt_pk_bf16_f32 v109, v110, v111
	v_mul_f32_e32 v110, 0x3d372713, v104
	v_mul_f32_e32 v111, 0x3d372713, v105
	v_mul_f32_e32 v110, v104, v110
	v_mul_f32_e32 v111, v105, v111
	v_fma_f32 v110, v104, v110, v104
	v_fma_f32 v111, v105, v111, v105
	v_mul_f32_e32 v110, 0x3f4c422a, v110
; DI unsigned pk2(float a, float b) { f32x2 v = {a, b}; bf16x2_t r = __builtin_convertvector(v, bf16x2_t); return __builtin_bit_cast(unsigned, r); }
;     DI void operator()(gacc_t& acc, int pm, int pn, char* lds, int tid, int wr, int wc, int lane) const {
;     ...
;         for (int m = 0; m < 8; ++m) {
;             const float r = rl[m * 16];
; #pragma unroll
;             for (int n = 0; n < 4; ++n) {
;                 float g[4];
; #pragma unroll
;                 for (int j = 0; j < 4; ++j) {
;                     const float x = acc[m][n][j] * r;
;                     const float u = 0.7978845608028654f * (x + 0.044715f * x * x * x);
;                     const float e = __builtin_amdgcn_exp2f(-2.885390081777927f * u);
;                     g[j] = x * __builtin_amdgcn_rcpf(1.0f + e);
;                 }
;                 u32x2 w; w.x = pk2(g[0], g[1]); w.y = pk2(g[2], g[3]);
;                 *(u32x2*)(lbase + m * 16 * 528 + n * 32) = w;
;             }
	v_mul_f32_e32 v111, 0x3f4c422a, v111
	v_mul_f32_e32 v110, 0xc038aa3b, v110
	v_mul_f32_e32 v111, 0xc038aa3b, v111
	v_exp_f32_e32 v110, v110
	v_exp_f32_e32 v111, v111
	v_pk_mul_f32 v[96:97], v[96:97], v[112:113] op_sel_hi:[1,0]
	v_pk_mul_f32 v[98:99], v[98:99], v[112:113] op_sel_hi:[1,0]
	v_add_f32_e32 v110, 1.0, v110
	v_add_f32_e32 v111, 1.0, v111
	v_rcp_f32_e32 v110, v110
	v_rcp_f32_e32 v111, v111
	s_nop 0
	v_pk_mul_f32 v[104:105], v[104:105], v[110:111]
	v_mul_f32_e32 v110, 0x3d372713, v106
	v_mul_f32_e32 v111, 0x3d372713, v107
	v_mul_f32_e32 v110, v106, v110
	v_mul_f32_e32 v111, v107, v111
	v_fma_f32 v110, v106, v110, v106
	v_fma_f32 v111, v107, v111, v107
	v_mul_f32_e32 v110, 0x3f4c422a, v110
	v_mul_f32_e32 v111, 0x3f4c422a, v111
	v_mul_f32_e32 v110, 0xc038aa3b, v110
	v_mul_f32_e32 v111, 0xc038aa3b, v111
	v_exp_f32_e32 v110, v110
	v_exp_f32_e32 v111, v111
	v_cvt_pk_bf16_f32 v104, v104, v105
	v_add_f32_e32 v110, 1.0, v110
	v_add_f32_e32 v111, 1.0, v111
	v_rcp_f32_e32 v110, v110
	v_rcp_f32_e32 v111, v111
	s_nop 0
	v_pk_mul_f32 v[106:107], v[106:107], v[110:111]
	s_nop 0
	v_cvt_pk_bf16_f32 v105, v106, v107
	v_add_u32_e32 v106, 0x2000, v126
	ds_write2_b64 v106, v[108:109], v[104:105] offset0:32 offset1:36
	v_mul_f32_e32 v104, 0x3d372713, v100
	v_mul_f32_e32 v105, 0x3d372713, v101
	v_mul_f32_e32 v104, v100, v104
	v_mul_f32_e32 v105, v101, v105
	v_fma_f32 v104, v100, v104, v100
	v_fma_f32 v105, v101, v105, v101
	v_mul_f32_e32 v104, 0x3f4c422a, v104
	v_mul_f32_e32 v105, 0x3f4c422a, v105
	v_mul_f32_e32 v104, 0xc038aa3b, v104
	v_mul_f32_e32 v105, 0xc038aa3b, v105
	v_exp_f32_e32 v104, v104
	v_exp_f32_e32 v105, v105
	v_add_f32_e32 v104, 1.0, v104
	v_add_f32_e32 v105, 1.0, v105
	v_rcp_f32_e32 v104, v104
	v_rcp_f32_e32 v105, v105
	s_nop 0
	v_pk_mul_f32 v[100:101], v[100:101], v[104:105]
	v_mul_f32_e32 v104, 0x3d372713, v102
	v_mul_f32_e32 v105, 0x3d372713, v103
	v_mul_f32_e32 v104, v102, v104
	v_mul_f32_e32 v105, v103, v105
	v_fma_f32 v104, v102, v104, v102
	v_fma_f32 v105, v103, v105, v103
	v_mul_f32_e32 v104, 0x3f4c422a, v104
	v_mul_f32_e32 v105, 0x3f4c422a, v105
	v_mul_f32_e32 v104, 0xc038aa3b, v104
	v_mul_f32_e32 v105, 0xc038aa3b, v105
	v_exp_f32_e32 v104, v104
	v_exp_f32_e32 v105, v105
	v_cvt_pk_bf16_f32 v100, v100, v101
	v_add_f32_e32 v104, 1.0, v104
	v_add_f32_e32 v105, 1.0, v105
	v_rcp_f32_e32 v104, v104
	v_rcp_f32_e32 v105, v105
	s_nop 0
	v_pk_mul_f32 v[102:103], v[102:103], v[104:105]
	s_nop 0
	v_cvt_pk_bf16_f32 v101, v102, v103
	v_mul_f32_e32 v102, 0x3d372713, v96
	v_mul_f32_e32 v103, 0x3d372713, v97
	v_mul_f32_e32 v102, v96, v102
	v_mul_f32_e32 v103, v97, v103
	v_fma_f32 v102, v96, v102, v96
	v_fma_f32 v103, v97, v103, v97
	v_mul_f32_e32 v102, 0x3f4c422a, v102
	v_mul_f32_e32 v103, 0x3f4c422a, v103
	v_mul_f32_e32 v102, 0xc038aa3b, v102
	v_mul_f32_e32 v103, 0xc038aa3b, v103
	v_exp_f32_e32 v102, v102
	v_exp_f32_e32 v103, v103
	v_add_f32_e32 v102, 1.0, v102
	v_add_f32_e32 v103, 1.0, v103
	v_rcp_f32_e32 v102, v102
	v_rcp_f32_e32 v103, v103
	s_nop 0
	v_pk_mul_f32 v[96:97], v[96:97], v[102:103]
	v_mul_f32_e32 v102, 0x3d372713, v98
	v_mul_f32_e32 v103, 0x3d372713, v99
	v_mul_f32_e32 v102, v98, v102
	v_mul_f32_e32 v103, v99, v103
	v_fma_f32 v102, v98, v102, v98
	v_fma_f32 v103, v99, v103, v99
	v_mul_f32_e32 v102, 0x3f4c422a, v102
	v_mul_f32_e32 v103, 0x3f4c422a, v103
	v_mul_f32_e32 v102, 0xc038aa3b, v102
	v_mul_f32_e32 v103, 0xc038aa3b, v103
	v_exp_f32_e32 v102, v102
	v_exp_f32_e32 v103, v103
	v_cvt_pk_bf16_f32 v96, v96, v97
	v_add_f32_e32 v102, 1.0, v102
	v_add_f32_e32 v103, 1.0, v103
	v_rcp_f32_e32 v102, v102
	v_rcp_f32_e32 v103, v103
	s_nop 0
	v_pk_mul_f32 v[98:99], v[98:99], v[102:103]
	s_nop 0
	v_cvt_pk_bf16_f32 v97, v98, v99
	ds_write2_b64 v106, v[100:101], v[96:97] offset0:40 offset1:44
	ds_read_b32 v96, v127 offset:128
	s_waitcnt lgkmcnt(0)
	v_pk_mul_f32 v[92:93], v[92:93], v[96:97] op_sel_hi:[1,0]
	s_nop 0
	v_mul_f32_e32 v97, 0x3d372713, v92
	v_mul_f32_e32 v97, v92, v97
	v_fma_f32 v97, v92, v97, v92
	v_mul_f32_e32 v97, 0x3f4c422a, v97
	v_mul_f32_e32 v97, 0xc038aa3b, v97
	v_exp_f32_e32 v97, v97
	s_nop 0
	v_add_f32_e32 v97, 1.0, v97
	v_rcp_f32_e32 v98, v97
	v_mul_f32_e32 v97, 0x3d372713, v93
	v_mul_f32_e32 v97, v93, v97
	v_fma_f32 v97, v93, v97, v93
	v_mul_f32_e32 v97, 0x3f4c422a, v97
	v_mul_f32_e32 v97, 0xc038aa3b, v97
	v_exp_f32_e32 v97, v97
	s_nop 0
	v_add_f32_e32 v97, 1.0, v97
	v_pk_mul_f32 v[94:95], v[94:95], v[96:97] op_sel_hi:[1,0]
	v_rcp_f32_e32 v99, v97
	v_mul_f32_e32 v97, 0x3d372713, v94
	v_mul_f32_e32 v97, v94, v97
	v_fma_f32 v97, v94, v97, v94
	v_mul_f32_e32 v97, 0x3f4c422a, v97
	v_mul_f32_e32 v97, 0xc038aa3b, v97
	v_exp_f32_e32 v97, v97
	v_pk_mul_f32 v[92:93], v[92:93], v[98:99]
	v_add_f32_e32 v97, 1.0, v97
	v_rcp_f32_e32 v98, v97
	v_mul_f32_e32 v97, 0x3d372713, v95
	v_mul_f32_e32 v97, v95, v97
	v_fma_f32 v97, v95, v97, v95
	v_mul_f32_e32 v97, 0x3f4c422a, v97
	v_mul_f32_e32 v97, 0xc038aa3b, v97
	v_exp_f32_e32 v97, v97
	v_cvt_pk_bf16_f32 v92, v92, v93
	v_add_f32_e32 v97, 1.0, v97
	v_rcp_f32_e32 v99, v97
	v_pk_mul_f32 v[88:89], v[88:89], v[96:97] op_sel_hi:[1,0]
	v_pk_mul_f32 v[90:91], v[90:91], v[96:97] op_sel_hi:[1,0]
	v_pk_mul_f32 v[84:85], v[84:85], v[96:97] op_sel_hi:[1,0]
	v_pk_mul_f32 v[94:95], v[94:95], v[98:99]
	v_pk_mul_f32 v[86:87], v[86:87], v[96:97] op_sel_hi:[1,0]
	v_cvt_pk_bf16_f32 v93, v94, v95
	v_mul_f32_e32 v94, 0x3d372713, v88
	v_mul_f32_e32 v95, 0x3d372713, v89
	v_mul_f32_e32 v94, v88, v94
	v_mul_f32_e32 v95, v89, v95
	v_fma_f32 v94, v88, v94, v88
	v_fma_f32 v95, v89, v95, v89
	v_mul_f32_e32 v94, 0x3f4c422a, v94
	v_mul_f32_e32 v95, 0x3f4c422a, v95
	v_mul_f32_e32 v94, 0xc038aa3b, v94
	v_mul_f32_e32 v95, 0xc038aa3b, v95
; DI unsigned pk2(float a, float b) { f32x2 v = {a, b}; bf16x2_t r = __builtin_convertvector(v, bf16x2_t); return __builtin_bit_cast(unsigned, r); }
;     DI void operator()(gacc_t& acc, int pm, int pn, char* lds, int tid, int wr, int wc, int lane) const {
;     ...
;         for (int m = 0; m < 8; ++m) {
;             const float r = rl[m * 16];
; #pragma unroll
;             for (int n = 0; n < 4; ++n) {
;                 float g[4];
; #pragma unroll
;                 for (int j = 0; j < 4; ++j) {
;                     const float x = acc[m][n][j] * r;
;                     const float u = 0.7978845608028654f * (x + 0.044715f * x * x * x);
;                     const float e = __builtin_amdgcn_exp2f(-2.885390081777927f * u);
;                     g[j] = x * __builtin_amdgcn_rcpf(1.0f + e);
;                 }
;                 u32x2 w; w.x = pk2(g[0], g[1]); w.y = pk2(g[2], g[3]);
;                 *(u32x2*)(lbase + m * 16 * 528 + n * 32) = w;
;             }
	v_exp_f32_e32 v94, v94
	v_exp_f32_e32 v95, v95
	v_pk_mul_f32 v[80:81], v[80:81], v[96:97] op_sel_hi:[1,0]
	v_pk_mul_f32 v[82:83], v[82:83], v[96:97] op_sel_hi:[1,0]
	v_add_f32_e32 v94, 1.0, v94
	v_add_f32_e32 v95, 1.0, v95
	v_rcp_f32_e32 v94, v94
	v_rcp_f32_e32 v95, v95
	s_nop 0
	v_pk_mul_f32 v[88:89], v[88:89], v[94:95]
	v_mul_f32_e32 v94, 0x3d372713, v90
	v_mul_f32_e32 v95, 0x3d372713, v91
	v_mul_f32_e32 v94, v90, v94
	v_mul_f32_e32 v95, v91, v95
	v_fma_f32 v94, v90, v94, v90
	v_fma_f32 v95, v91, v95, v91
	v_mul_f32_e32 v94, 0x3f4c422a, v94
	v_mul_f32_e32 v95, 0x3f4c422a, v95
	v_mul_f32_e32 v94, 0xc038aa3b, v94
	v_mul_f32_e32 v95, 0xc038aa3b, v95
	v_exp_f32_e32 v94, v94
	v_exp_f32_e32 v95, v95
	v_cvt_pk_bf16_f32 v88, v88, v89
	v_add_f32_e32 v94, 1.0, v94
	v_add_f32_e32 v95, 1.0, v95
	v_rcp_f32_e32 v94, v94
	v_rcp_f32_e32 v95, v95
	s_nop 0
	v_pk_mul_f32 v[90:91], v[90:91], v[94:95]
	s_nop 0
	v_cvt_pk_bf16_f32 v89, v90, v91
	v_add_u32_e32 v90, 0x4000, v126
	ds_write2_b64 v90, v[92:93], v[88:89] offset0:64 offset1:68
	v_mul_f32_e32 v88, 0x3d372713, v84
	v_mul_f32_e32 v89, 0x3d372713, v85
	v_mul_f32_e32 v88, v84, v88
	v_mul_f32_e32 v89, v85, v89
	v_fma_f32 v88, v84, v88, v84
	v_fma_f32 v89, v85, v89, v85
	v_mul_f32_e32 v88, 0x3f4c422a, v88
	v_mul_f32_e32 v89, 0x3f4c422a, v89
	v_mul_f32_e32 v88, 0xc038aa3b, v88
	v_mul_f32_e32 v89, 0xc038aa3b, v89
	v_exp_f32_e32 v88, v88
	v_exp_f32_e32 v89, v89
	v_add_f32_e32 v88, 1.0, v88
	v_add_f32_e32 v89, 1.0, v89
	v_rcp_f32_e32 v88, v88
	v_rcp_f32_e32 v89, v89
	s_nop 0
	v_pk_mul_f32 v[84:85], v[84:85], v[88:89]
	v_mul_f32_e32 v88, 0x3d372713, v86
	v_mul_f32_e32 v89, 0x3d372713, v87
	v_mul_f32_e32 v88, v86, v88
	v_mul_f32_e32 v89, v87, v89
	v_fma_f32 v88, v86, v88, v86
	v_fma_f32 v89, v87, v89, v87
	v_mul_f32_e32 v88, 0x3f4c422a, v88
	v_mul_f32_e32 v89, 0x3f4c422a, v89
	v_mul_f32_e32 v88, 0xc038aa3b, v88
	v_mul_f32_e32 v89, 0xc038aa3b, v89
	v_exp_f32_e32 v88, v88
	v_exp_f32_e32 v89, v89
	v_cvt_pk_bf16_f32 v84, v84, v85
	v_add_f32_e32 v88, 1.0, v88
	v_add_f32_e32 v89, 1.0, v89
	v_rcp_f32_e32 v88, v88
	v_rcp_f32_e32 v89, v89
	s_nop 0
	v_pk_mul_f32 v[86:87], v[86:87], v[88:89]
	s_nop 0
	v_cvt_pk_bf16_f32 v85, v86, v87
	v_mul_f32_e32 v86, 0x3d372713, v80
	v_mul_f32_e32 v87, 0x3d372713, v81
	v_mul_f32_e32 v86, v80, v86
	v_mul_f32_e32 v87, v81, v87
	v_fma_f32 v86, v80, v86, v80
	v_fma_f32 v87, v81, v87, v81
	v_mul_f32_e32 v86, 0x3f4c422a, v86
	v_mul_f32_e32 v87, 0x3f4c422a, v87
	v_mul_f32_e32 v86, 0xc038aa3b, v86
	v_mul_f32_e32 v87, 0xc038aa3b, v87
	v_exp_f32_e32 v86, v86
	v_exp_f32_e32 v87, v87
	v_add_f32_e32 v86, 1.0, v86
	v_add_f32_e32 v87, 1.0, v87
	v_rcp_f32_e32 v86, v86
	v_rcp_f32_e32 v87, v87
	s_nop 0
	v_pk_mul_f32 v[80:81], v[80:81], v[86:87]
	v_mul_f32_e32 v86, 0x3d372713, v82
	v_mul_f32_e32 v87, 0x3d372713, v83
	v_mul_f32_e32 v86, v82, v86
	v_mul_f32_e32 v87, v83, v87
	v_fma_f32 v86, v82, v86, v82
	v_fma_f32 v87, v83, v87, v83
	v_mul_f32_e32 v86, 0x3f4c422a, v86
	v_mul_f32_e32 v87, 0x3f4c422a, v87
	v_mul_f32_e32 v86, 0xc038aa3b, v86
	v_mul_f32_e32 v87, 0xc038aa3b, v87
	v_exp_f32_e32 v86, v86
	v_exp_f32_e32 v87, v87
	v_cvt_pk_bf16_f32 v80, v80, v81
	v_add_f32_e32 v86, 1.0, v86
	v_add_f32_e32 v87, 1.0, v87
	v_rcp_f32_e32 v86, v86
	v_rcp_f32_e32 v87, v87
	s_nop 0
	v_pk_mul_f32 v[82:83], v[82:83], v[86:87]
	s_nop 0
	v_cvt_pk_bf16_f32 v81, v82, v83
	ds_write2_b64 v90, v[84:85], v[80:81] offset0:72 offset1:76
	ds_read_b32 v80, v127 offset:192
	s_waitcnt lgkmcnt(0)
	v_pk_mul_f32 v[76:77], v[76:77], v[80:81] op_sel_hi:[1,0]
	s_nop 0
	v_mul_f32_e32 v81, 0x3d372713, v76
	v_mul_f32_e32 v81, v76, v81
	v_fma_f32 v81, v76, v81, v76
	v_mul_f32_e32 v81, 0x3f4c422a, v81
	v_mul_f32_e32 v81, 0xc038aa3b, v81
	v_exp_f32_e32 v81, v81
	s_nop 0
	v_add_f32_e32 v81, 1.0, v81
	v_rcp_f32_e32 v82, v81
	v_mul_f32_e32 v81, 0x3d372713, v77
	v_mul_f32_e32 v81, v77, v81
	v_fma_f32 v81, v77, v81, v77
	v_mul_f32_e32 v81, 0x3f4c422a, v81
	v_mul_f32_e32 v81, 0xc038aa3b, v81
	v_exp_f32_e32 v81, v81
	s_nop 0
	v_add_f32_e32 v81, 1.0, v81
	v_pk_mul_f32 v[78:79], v[78:79], v[80:81] op_sel_hi:[1,0]
	v_rcp_f32_e32 v83, v81
	v_mul_f32_e32 v81, 0x3d372713, v78
	v_mul_f32_e32 v81, v78, v81
	v_fma_f32 v81, v78, v81, v78
	v_mul_f32_e32 v81, 0x3f4c422a, v81
	v_mul_f32_e32 v81, 0xc038aa3b, v81
	v_exp_f32_e32 v81, v81
	v_pk_mul_f32 v[76:77], v[76:77], v[82:83]
	v_add_f32_e32 v81, 1.0, v81
	v_rcp_f32_e32 v82, v81
	v_mul_f32_e32 v81, 0x3d372713, v79
	v_mul_f32_e32 v81, v79, v81
	v_fma_f32 v81, v79, v81, v79
	v_mul_f32_e32 v81, 0x3f4c422a, v81
	v_mul_f32_e32 v81, 0xc038aa3b, v81
	v_exp_f32_e32 v81, v81
	v_cvt_pk_bf16_f32 v76, v76, v77
	v_add_f32_e32 v81, 1.0, v81
	v_rcp_f32_e32 v83, v81
	v_pk_mul_f32 v[72:73], v[72:73], v[80:81] op_sel_hi:[1,0]
	v_pk_mul_f32 v[74:75], v[74:75], v[80:81] op_sel_hi:[1,0]
	v_pk_mul_f32 v[68:69], v[68:69], v[80:81] op_sel_hi:[1,0]
	v_pk_mul_f32 v[78:79], v[78:79], v[82:83]
	v_pk_mul_f32 v[70:71], v[70:71], v[80:81] op_sel_hi:[1,0]
	v_cvt_pk_bf16_f32 v77, v78, v79
	v_mul_f32_e32 v78, 0x3d372713, v72
	v_mul_f32_e32 v79, 0x3d372713, v73
	v_mul_f32_e32 v78, v72, v78
	v_mul_f32_e32 v79, v73, v79
	v_fma_f32 v78, v72, v78, v72
	v_fma_f32 v79, v73, v79, v73
	v_mul_f32_e32 v78, 0x3f4c422a, v78
	v_mul_f32_e32 v79, 0x3f4c422a, v79
	v_mul_f32_e32 v78, 0xc038aa3b, v78
	v_mul_f32_e32 v79, 0xc038aa3b, v79
	v_exp_f32_e32 v78, v78
	v_exp_f32_e32 v79, v79
	v_pk_mul_f32 v[64:65], v[64:65], v[80:81] op_sel_hi:[1,0]
	v_pk_mul_f32 v[66:67], v[66:67], v[80:81] op_sel_hi:[1,0]
	v_add_f32_e32 v78, 1.0, v78
	v_add_f32_e32 v79, 1.0, v79
	v_rcp_f32_e32 v78, v78
	v_rcp_f32_e32 v79, v79
	s_nop 0
	v_pk_mul_f32 v[72:73], v[72:73], v[78:79]
; DI unsigned pk2(float a, float b) { f32x2 v = {a, b}; bf16x2_t r = __builtin_convertvector(v, bf16x2_t); return __builtin_bit_cast(unsigned, r); }
;     DI void operator()(gacc_t& acc, int pm, int pn, char* lds, int tid, int wr, int wc, int lane) const {
;     ...
;         for (int m = 0; m < 8; ++m) {
;             const float r = rl[m * 16];
; #pragma unroll
;             for (int n = 0; n < 4; ++n) {
;                 float g[4];
; #pragma unroll
;                 for (int j = 0; j < 4; ++j) {
;                     const float x = acc[m][n][j] * r;
;                     const float u = 0.7978845608028654f * (x + 0.044715f * x * x * x);
;                     const float e = __builtin_amdgcn_exp2f(-2.885390081777927f * u);
;                     g[j] = x * __builtin_amdgcn_rcpf(1.0f + e);
;                 }
;                 u32x2 w; w.x = pk2(g[0], g[1]); w.y = pk2(g[2], g[3]);
;                 *(u32x2*)(lbase + m * 16 * 528 + n * 32) = w;
;             }
	v_mul_f32_e32 v78, 0x3d372713, v74
	v_mul_f32_e32 v79, 0x3d372713, v75
	v_mul_f32_e32 v78, v74, v78
	v_mul_f32_e32 v79, v75, v79
	v_fma_f32 v78, v74, v78, v74
	v_fma_f32 v79, v75, v79, v75
	v_mul_f32_e32 v78, 0x3f4c422a, v78
	v_mul_f32_e32 v79, 0x3f4c422a, v79
	v_mul_f32_e32 v78, 0xc038aa3b, v78
	v_mul_f32_e32 v79, 0xc038aa3b, v79
	v_exp_f32_e32 v78, v78
	v_exp_f32_e32 v79, v79
	v_cvt_pk_bf16_f32 v72, v72, v73
	v_add_f32_e32 v78, 1.0, v78
	v_add_f32_e32 v79, 1.0, v79
	v_rcp_f32_e32 v78, v78
	v_rcp_f32_e32 v79, v79
	s_nop 0
	v_pk_mul_f32 v[74:75], v[74:75], v[78:79]
	s_nop 0
	v_cvt_pk_bf16_f32 v73, v74, v75
	v_add_u32_e32 v74, 0x6000, v126
	ds_write2_b64 v74, v[76:77], v[72:73] offset0:96 offset1:100
	v_mul_f32_e32 v72, 0x3d372713, v68
	v_mul_f32_e32 v73, 0x3d372713, v69
	v_mul_f32_e32 v72, v68, v72
	v_mul_f32_e32 v73, v69, v73
	v_fma_f32 v72, v68, v72, v68
	v_fma_f32 v73, v69, v73, v69
	v_mul_f32_e32 v72, 0x3f4c422a, v72
	v_mul_f32_e32 v73, 0x3f4c422a, v73
	v_mul_f32_e32 v72, 0xc038aa3b, v72
	v_mul_f32_e32 v73, 0xc038aa3b, v73
	v_exp_f32_e32 v72, v72
	v_exp_f32_e32 v73, v73
	v_add_f32_e32 v72, 1.0, v72
	v_add_f32_e32 v73, 1.0, v73
	v_rcp_f32_e32 v72, v72
	v_rcp_f32_e32 v73, v73
	s_nop 0
	v_pk_mul_f32 v[68:69], v[68:69], v[72:73]
	v_mul_f32_e32 v72, 0x3d372713, v70
	v_mul_f32_e32 v73, 0x3d372713, v71
	v_mul_f32_e32 v72, v70, v72
	v_mul_f32_e32 v73, v71, v73
	v_fma_f32 v72, v70, v72, v70
	v_fma_f32 v73, v71, v73, v71
	v_mul_f32_e32 v72, 0x3f4c422a, v72
	v_mul_f32_e32 v73, 0x3f4c422a, v73
	v_mul_f32_e32 v72, 0xc038aa3b, v72
	v_mul_f32_e32 v73, 0xc038aa3b, v73
	v_exp_f32_e32 v72, v72
	v_exp_f32_e32 v73, v73
	v_cvt_pk_bf16_f32 v68, v68, v69
	v_add_f32_e32 v72, 1.0, v72
	v_add_f32_e32 v73, 1.0, v73
	v_rcp_f32_e32 v72, v72
	v_rcp_f32_e32 v73, v73
	s_nop 0
	v_pk_mul_f32 v[70:71], v[70:71], v[72:73]
	s_nop 0
	v_cvt_pk_bf16_f32 v69, v70, v71
	v_mul_f32_e32 v70, 0x3d372713, v64
	v_mul_f32_e32 v71, 0x3d372713, v65
	v_mul_f32_e32 v70, v64, v70
	v_mul_f32_e32 v71, v65, v71
	v_fma_f32 v70, v64, v70, v64
	v_fma_f32 v71, v65, v71, v65
	v_mul_f32_e32 v70, 0x3f4c422a, v70
	v_mul_f32_e32 v71, 0x3f4c422a, v71
	v_mul_f32_e32 v70, 0xc038aa3b, v70
	v_mul_f32_e32 v71, 0xc038aa3b, v71
	v_exp_f32_e32 v70, v70
	v_exp_f32_e32 v71, v71
	v_add_f32_e32 v70, 1.0, v70
	v_add_f32_e32 v71, 1.0, v71
	v_rcp_f32_e32 v70, v70
	v_rcp_f32_e32 v71, v71
	s_nop 0
	v_pk_mul_f32 v[64:65], v[64:65], v[70:71]
	v_mul_f32_e32 v70, 0x3d372713, v66
	v_mul_f32_e32 v71, 0x3d372713, v67
	v_mul_f32_e32 v70, v66, v70
	v_mul_f32_e32 v71, v67, v71
	v_fma_f32 v70, v66, v70, v66
	v_fma_f32 v71, v67, v71, v67
	v_mul_f32_e32 v70, 0x3f4c422a, v70
	v_mul_f32_e32 v71, 0x3f4c422a, v71
	v_mul_f32_e32 v70, 0xc038aa3b, v70
	v_mul_f32_e32 v71, 0xc038aa3b, v71
	v_exp_f32_e32 v70, v70
	v_exp_f32_e32 v71, v71
	v_cvt_pk_bf16_f32 v64, v64, v65
	v_add_f32_e32 v70, 1.0, v70
	v_add_f32_e32 v71, 1.0, v71
	v_rcp_f32_e32 v70, v70
	v_rcp_f32_e32 v71, v71
	s_nop 0
	v_pk_mul_f32 v[66:67], v[66:67], v[70:71]
	s_nop 0
	v_cvt_pk_bf16_f32 v65, v66, v67
	ds_write2_b64 v74, v[68:69], v[64:65] offset0:104 offset1:108
	ds_read_b32 v64, v127 offset:256
	s_waitcnt lgkmcnt(0)
	v_pk_mul_f32 v[60:61], v[60:61], v[64:65] op_sel_hi:[1,0]
	s_nop 0
	v_mul_f32_e32 v65, 0x3d372713, v60
	v_mul_f32_e32 v65, v60, v65
	v_fma_f32 v65, v60, v65, v60
	v_mul_f32_e32 v65, 0x3f4c422a, v65
	v_mul_f32_e32 v65, 0xc038aa3b, v65
	v_exp_f32_e32 v65, v65
	s_nop 0
	v_add_f32_e32 v65, 1.0, v65
	v_rcp_f32_e32 v66, v65
	v_mul_f32_e32 v65, 0x3d372713, v61
	v_mul_f32_e32 v65, v61, v65
	v_fma_f32 v65, v61, v65, v61
	v_mul_f32_e32 v65, 0x3f4c422a, v65
	v_mul_f32_e32 v65, 0xc038aa3b, v65
	v_exp_f32_e32 v65, v65
	s_nop 0
	v_add_f32_e32 v65, 1.0, v65
	v_pk_mul_f32 v[62:63], v[62:63], v[64:65] op_sel_hi:[1,0]
	v_rcp_f32_e32 v67, v65
	v_mul_f32_e32 v65, 0x3d372713, v62
	v_mul_f32_e32 v65, v62, v65
	v_fma_f32 v65, v62, v65, v62
	v_mul_f32_e32 v65, 0x3f4c422a, v65
	v_mul_f32_e32 v65, 0xc038aa3b, v65
	v_exp_f32_e32 v65, v65
	v_pk_mul_f32 v[60:61], v[60:61], v[66:67]
	v_add_f32_e32 v65, 1.0, v65
	v_rcp_f32_e32 v66, v65
	v_mul_f32_e32 v65, 0x3d372713, v63
	v_mul_f32_e32 v65, v63, v65
	v_fma_f32 v65, v63, v65, v63
	v_mul_f32_e32 v65, 0x3f4c422a, v65
	v_mul_f32_e32 v65, 0xc038aa3b, v65
	v_exp_f32_e32 v65, v65
	v_cvt_pk_bf16_f32 v60, v60, v61
	v_add_f32_e32 v65, 1.0, v65
	v_rcp_f32_e32 v67, v65
	v_pk_mul_f32 v[56:57], v[56:57], v[64:65] op_sel_hi:[1,0]
	v_pk_mul_f32 v[58:59], v[58:59], v[64:65] op_sel_hi:[1,0]
	v_pk_mul_f32 v[52:53], v[52:53], v[64:65] op_sel_hi:[1,0]
	v_pk_mul_f32 v[62:63], v[62:63], v[66:67]
	v_pk_mul_f32 v[54:55], v[54:55], v[64:65] op_sel_hi:[1,0]
	v_cvt_pk_bf16_f32 v61, v62, v63
	v_mul_f32_e32 v62, 0x3d372713, v56
	v_mul_f32_e32 v63, 0x3d372713, v57
	v_mul_f32_e32 v62, v56, v62
	v_mul_f32_e32 v63, v57, v63
	v_fma_f32 v62, v56, v62, v56
	v_fma_f32 v63, v57, v63, v57
	v_mul_f32_e32 v62, 0x3f4c422a, v62
	v_mul_f32_e32 v63, 0x3f4c422a, v63
	v_mul_f32_e32 v62, 0xc038aa3b, v62
	v_mul_f32_e32 v63, 0xc038aa3b, v63
	v_exp_f32_e32 v62, v62
	v_exp_f32_e32 v63, v63
	v_pk_mul_f32 v[48:49], v[48:49], v[64:65] op_sel_hi:[1,0]
	v_pk_mul_f32 v[50:51], v[50:51], v[64:65] op_sel_hi:[1,0]
	v_add_f32_e32 v62, 1.0, v62
	v_add_f32_e32 v63, 1.0, v63
	v_rcp_f32_e32 v62, v62
	v_rcp_f32_e32 v63, v63
	s_nop 0
	v_pk_mul_f32 v[56:57], v[56:57], v[62:63]
	v_mul_f32_e32 v62, 0x3d372713, v58
	v_mul_f32_e32 v63, 0x3d372713, v59
	v_mul_f32_e32 v62, v58, v62
	v_mul_f32_e32 v63, v59, v63
	v_fma_f32 v62, v58, v62, v58
	v_fma_f32 v63, v59, v63, v59
	v_mul_f32_e32 v62, 0x3f4c422a, v62
	v_mul_f32_e32 v63, 0x3f4c422a, v63
	v_mul_f32_e32 v62, 0xc038aa3b, v62
	v_mul_f32_e32 v63, 0xc038aa3b, v63
; DI unsigned pk2(float a, float b) { f32x2 v = {a, b}; bf16x2_t r = __builtin_convertvector(v, bf16x2_t); return __builtin_bit_cast(unsigned, r); }
;     DI void operator()(gacc_t& acc, int pm, int pn, char* lds, int tid, int wr, int wc, int lane) const {
;     ...
;         for (int m = 0; m < 8; ++m) {
;             const float r = rl[m * 16];
; #pragma unroll
;             for (int n = 0; n < 4; ++n) {
;                 float g[4];
; #pragma unroll
;                 for (int j = 0; j < 4; ++j) {
;                     const float x = acc[m][n][j] * r;
;                     const float u = 0.7978845608028654f * (x + 0.044715f * x * x * x);
;                     const float e = __builtin_amdgcn_exp2f(-2.885390081777927f * u);
;                     g[j] = x * __builtin_amdgcn_rcpf(1.0f + e);
;                 }
;                 u32x2 w; w.x = pk2(g[0], g[1]); w.y = pk2(g[2], g[3]);
;                 *(u32x2*)(lbase + m * 16 * 528 + n * 32) = w;
;             }
	v_exp_f32_e32 v62, v62
	v_exp_f32_e32 v63, v63
	v_cvt_pk_bf16_f32 v56, v56, v57
	v_add_f32_e32 v62, 1.0, v62
	v_add_f32_e32 v63, 1.0, v63
	v_rcp_f32_e32 v62, v62
	v_rcp_f32_e32 v63, v63
	s_nop 0
	v_pk_mul_f32 v[58:59], v[58:59], v[62:63]
	s_nop 0
	v_cvt_pk_bf16_f32 v57, v58, v59
	v_add_u32_e32 v58, 0x8000, v126
	ds_write2_b64 v58, v[60:61], v[56:57] offset0:128 offset1:132
	v_mul_f32_e32 v56, 0x3d372713, v52
	v_mul_f32_e32 v57, 0x3d372713, v53
	v_mul_f32_e32 v56, v52, v56
	v_mul_f32_e32 v57, v53, v57
	v_fma_f32 v56, v52, v56, v52
	v_fma_f32 v57, v53, v57, v53
	v_mul_f32_e32 v56, 0x3f4c422a, v56
	v_mul_f32_e32 v57, 0x3f4c422a, v57
	v_mul_f32_e32 v56, 0xc038aa3b, v56
	v_mul_f32_e32 v57, 0xc038aa3b, v57
	v_exp_f32_e32 v56, v56
	v_exp_f32_e32 v57, v57
	v_add_f32_e32 v56, 1.0, v56
	v_add_f32_e32 v57, 1.0, v57
	v_rcp_f32_e32 v56, v56
	v_rcp_f32_e32 v57, v57
	s_nop 0
	v_pk_mul_f32 v[52:53], v[52:53], v[56:57]
	v_mul_f32_e32 v56, 0x3d372713, v54
	v_mul_f32_e32 v57, 0x3d372713, v55
	v_mul_f32_e32 v56, v54, v56
	v_mul_f32_e32 v57, v55, v57
	v_fma_f32 v56, v54, v56, v54
	v_fma_f32 v57, v55, v57, v55
	v_mul_f32_e32 v56, 0x3f4c422a, v56
	v_mul_f32_e32 v57, 0x3f4c422a, v57
	v_mul_f32_e32 v56, 0xc038aa3b, v56
	v_mul_f32_e32 v57, 0xc038aa3b, v57
	v_exp_f32_e32 v56, v56
	v_exp_f32_e32 v57, v57
	v_cvt_pk_bf16_f32 v52, v52, v53
	v_add_f32_e32 v56, 1.0, v56
	v_add_f32_e32 v57, 1.0, v57
	v_rcp_f32_e32 v56, v56
	v_rcp_f32_e32 v57, v57
	s_nop 0
	v_pk_mul_f32 v[54:55], v[54:55], v[56:57]
	s_nop 0
	v_cvt_pk_bf16_f32 v53, v54, v55
	v_mul_f32_e32 v54, 0x3d372713, v48
	v_mul_f32_e32 v55, 0x3d372713, v49
	v_mul_f32_e32 v54, v48, v54
	v_mul_f32_e32 v55, v49, v55
	v_fma_f32 v54, v48, v54, v48
	v_fma_f32 v55, v49, v55, v49
	v_mul_f32_e32 v54, 0x3f4c422a, v54
	v_mul_f32_e32 v55, 0x3f4c422a, v55
	v_mul_f32_e32 v54, 0xc038aa3b, v54
	v_mul_f32_e32 v55, 0xc038aa3b, v55
	v_exp_f32_e32 v54, v54
	v_exp_f32_e32 v55, v55
	v_add_f32_e32 v54, 1.0, v54
	v_add_f32_e32 v55, 1.0, v55
	v_rcp_f32_e32 v54, v54
	v_rcp_f32_e32 v55, v55
	s_nop 0
	v_pk_mul_f32 v[48:49], v[48:49], v[54:55]
	v_mul_f32_e32 v54, 0x3d372713, v50
	v_mul_f32_e32 v55, 0x3d372713, v51
	v_mul_f32_e32 v54, v50, v54
	v_mul_f32_e32 v55, v51, v55
	v_fma_f32 v54, v50, v54, v50
	v_fma_f32 v55, v51, v55, v51
	v_mul_f32_e32 v54, 0x3f4c422a, v54
	v_mul_f32_e32 v55, 0x3f4c422a, v55
	v_mul_f32_e32 v54, 0xc038aa3b, v54
	v_mul_f32_e32 v55, 0xc038aa3b, v55
	v_exp_f32_e32 v54, v54
	v_exp_f32_e32 v55, v55
	v_cvt_pk_bf16_f32 v48, v48, v49
	v_add_f32_e32 v54, 1.0, v54
	v_add_f32_e32 v55, 1.0, v55
	v_rcp_f32_e32 v54, v54
	v_rcp_f32_e32 v55, v55
	s_nop 0
	v_pk_mul_f32 v[50:51], v[50:51], v[54:55]
	s_nop 0
	v_cvt_pk_bf16_f32 v49, v50, v51
	ds_write2_b64 v58, v[52:53], v[48:49] offset0:136 offset1:140
	ds_read_b32 v48, v127 offset:320
	s_waitcnt lgkmcnt(0)
	v_pk_mul_f32 v[44:45], v[44:45], v[48:49] op_sel_hi:[1,0]
	s_nop 0
	v_mul_f32_e32 v49, 0x3d372713, v44
	v_mul_f32_e32 v49, v44, v49
	v_fma_f32 v49, v44, v49, v44
	v_mul_f32_e32 v49, 0x3f4c422a, v49
	v_mul_f32_e32 v49, 0xc038aa3b, v49
	v_exp_f32_e32 v49, v49
	s_nop 0
	v_add_f32_e32 v49, 1.0, v49
	v_rcp_f32_e32 v50, v49
	v_mul_f32_e32 v49, 0x3d372713, v45
	v_mul_f32_e32 v49, v45, v49
	v_fma_f32 v49, v45, v49, v45
	v_mul_f32_e32 v49, 0x3f4c422a, v49
	v_mul_f32_e32 v49, 0xc038aa3b, v49
	v_exp_f32_e32 v49, v49
	s_nop 0
	v_add_f32_e32 v49, 1.0, v49
	v_pk_mul_f32 v[46:47], v[46:47], v[48:49] op_sel_hi:[1,0]
	v_rcp_f32_e32 v51, v49
	v_mul_f32_e32 v49, 0x3d372713, v46
	v_mul_f32_e32 v49, v46, v49
	v_fma_f32 v49, v46, v49, v46
	v_mul_f32_e32 v49, 0x3f4c422a, v49
	v_mul_f32_e32 v49, 0xc038aa3b, v49
	v_exp_f32_e32 v49, v49
	v_pk_mul_f32 v[44:45], v[44:45], v[50:51]
	v_add_f32_e32 v49, 1.0, v49
	v_rcp_f32_e32 v50, v49
	v_mul_f32_e32 v49, 0x3d372713, v47
	v_mul_f32_e32 v49, v47, v49
	v_fma_f32 v49, v47, v49, v47
	v_mul_f32_e32 v49, 0x3f4c422a, v49
	v_mul_f32_e32 v49, 0xc038aa3b, v49
	v_exp_f32_e32 v49, v49
	v_cvt_pk_bf16_f32 v44, v44, v45
	v_add_f32_e32 v49, 1.0, v49
	v_rcp_f32_e32 v51, v49
	v_pk_mul_f32 v[40:41], v[40:41], v[48:49] op_sel_hi:[1,0]
	v_pk_mul_f32 v[42:43], v[42:43], v[48:49] op_sel_hi:[1,0]
	v_pk_mul_f32 v[36:37], v[36:37], v[48:49] op_sel_hi:[1,0]
	v_pk_mul_f32 v[46:47], v[46:47], v[50:51]
	v_pk_mul_f32 v[38:39], v[38:39], v[48:49] op_sel_hi:[1,0]
	v_cvt_pk_bf16_f32 v45, v46, v47
	v_mul_f32_e32 v46, 0x3d372713, v40
	v_mul_f32_e32 v47, 0x3d372713, v41
	v_mul_f32_e32 v46, v40, v46
	v_mul_f32_e32 v47, v41, v47
	v_fma_f32 v46, v40, v46, v40
	v_fma_f32 v47, v41, v47, v41
	v_mul_f32_e32 v46, 0x3f4c422a, v46
	v_mul_f32_e32 v47, 0x3f4c422a, v47
	v_mul_f32_e32 v46, 0xc038aa3b, v46
	v_mul_f32_e32 v47, 0xc038aa3b, v47
	v_exp_f32_e32 v46, v46
	v_exp_f32_e32 v47, v47
	v_pk_mul_f32 v[32:33], v[32:33], v[48:49] op_sel_hi:[1,0]
	v_pk_mul_f32 v[34:35], v[34:35], v[48:49] op_sel_hi:[1,0]
	v_add_f32_e32 v46, 1.0, v46
	v_add_f32_e32 v47, 1.0, v47
	v_rcp_f32_e32 v46, v46
	v_rcp_f32_e32 v47, v47
	s_nop 0
	v_pk_mul_f32 v[40:41], v[40:41], v[46:47]
	v_mul_f32_e32 v46, 0x3d372713, v42
	v_mul_f32_e32 v47, 0x3d372713, v43
	v_mul_f32_e32 v46, v42, v46
	v_mul_f32_e32 v47, v43, v47
	v_fma_f32 v46, v42, v46, v42
	v_fma_f32 v47, v43, v47, v43
	v_mul_f32_e32 v46, 0x3f4c422a, v46
	v_mul_f32_e32 v47, 0x3f4c422a, v47
	v_mul_f32_e32 v46, 0xc038aa3b, v46
	v_mul_f32_e32 v47, 0xc038aa3b, v47
	v_exp_f32_e32 v46, v46
	v_exp_f32_e32 v47, v47
	v_cvt_pk_bf16_f32 v40, v40, v41
	v_add_f32_e32 v46, 1.0, v46
	v_add_f32_e32 v47, 1.0, v47
	v_rcp_f32_e32 v46, v46
	v_rcp_f32_e32 v47, v47
	s_nop 0
	v_pk_mul_f32 v[42:43], v[42:43], v[46:47]
	s_nop 0
	v_cvt_pk_bf16_f32 v41, v42, v43
	v_add_u32_e32 v42, 0xa000, v126
; DI unsigned pk2(float a, float b) { f32x2 v = {a, b}; bf16x2_t r = __builtin_convertvector(v, bf16x2_t); return __builtin_bit_cast(unsigned, r); }
;     DI void operator()(gacc_t& acc, int pm, int pn, char* lds, int tid, int wr, int wc, int lane) const {
;     ...
;         for (int m = 0; m < 8; ++m) {
;             const float r = rl[m * 16];
; #pragma unroll
;             for (int n = 0; n < 4; ++n) {
;                 float g[4];
; #pragma unroll
;                 for (int j = 0; j < 4; ++j) {
;                     const float x = acc[m][n][j] * r;
;                     const float u = 0.7978845608028654f * (x + 0.044715f * x * x * x);
;                     const float e = __builtin_amdgcn_exp2f(-2.885390081777927f * u);
;                     g[j] = x * __builtin_amdgcn_rcpf(1.0f + e);
;                 }
;                 u32x2 w; w.x = pk2(g[0], g[1]); w.y = pk2(g[2], g[3]);
;                 *(u32x2*)(lbase + m * 16 * 528 + n * 32) = w;
;             }
	ds_write2_b64 v42, v[44:45], v[40:41] offset0:160 offset1:164
	v_mul_f32_e32 v40, 0x3d372713, v36
	v_mul_f32_e32 v41, 0x3d372713, v37
	v_mul_f32_e32 v40, v36, v40
	v_mul_f32_e32 v41, v37, v41
	v_fma_f32 v40, v36, v40, v36
	v_fma_f32 v41, v37, v41, v37
	v_mul_f32_e32 v40, 0x3f4c422a, v40
	v_mul_f32_e32 v41, 0x3f4c422a, v41
	v_mul_f32_e32 v40, 0xc038aa3b, v40
	v_mul_f32_e32 v41, 0xc038aa3b, v41
	v_exp_f32_e32 v40, v40
	v_exp_f32_e32 v41, v41
	v_add_f32_e32 v40, 1.0, v40
	v_add_f32_e32 v41, 1.0, v41
	v_rcp_f32_e32 v40, v40
	v_rcp_f32_e32 v41, v41
	s_nop 0
	v_pk_mul_f32 v[36:37], v[36:37], v[40:41]
	v_mul_f32_e32 v40, 0x3d372713, v38
	v_mul_f32_e32 v41, 0x3d372713, v39
	v_mul_f32_e32 v40, v38, v40
	v_mul_f32_e32 v41, v39, v41
	v_fma_f32 v40, v38, v40, v38
	v_fma_f32 v41, v39, v41, v39
	v_mul_f32_e32 v40, 0x3f4c422a, v40
	v_mul_f32_e32 v41, 0x3f4c422a, v41
	v_mul_f32_e32 v40, 0xc038aa3b, v40
	v_mul_f32_e32 v41, 0xc038aa3b, v41
	v_exp_f32_e32 v40, v40
	v_exp_f32_e32 v41, v41
	v_cvt_pk_bf16_f32 v36, v36, v37
	v_add_f32_e32 v40, 1.0, v40
	v_add_f32_e32 v41, 1.0, v41
	v_rcp_f32_e32 v40, v40
	v_rcp_f32_e32 v41, v41
	s_nop 0
	v_pk_mul_f32 v[38:39], v[38:39], v[40:41]
	s_nop 0
	v_cvt_pk_bf16_f32 v37, v38, v39
	v_mul_f32_e32 v38, 0x3d372713, v32
	v_mul_f32_e32 v39, 0x3d372713, v33
	v_mul_f32_e32 v38, v32, v38
	v_mul_f32_e32 v39, v33, v39
	v_fma_f32 v38, v32, v38, v32
	v_fma_f32 v39, v33, v39, v33
	v_mul_f32_e32 v38, 0x3f4c422a, v38
	v_mul_f32_e32 v39, 0x3f4c422a, v39
	v_mul_f32_e32 v38, 0xc038aa3b, v38
	v_mul_f32_e32 v39, 0xc038aa3b, v39
	v_exp_f32_e32 v38, v38
	v_exp_f32_e32 v39, v39
	v_add_f32_e32 v38, 1.0, v38
	v_add_f32_e32 v39, 1.0, v39
	v_rcp_f32_e32 v38, v38
	v_rcp_f32_e32 v39, v39
	s_nop 0
	v_pk_mul_f32 v[32:33], v[32:33], v[38:39]
	v_mul_f32_e32 v38, 0x3d372713, v34
	v_mul_f32_e32 v39, 0x3d372713, v35
	v_mul_f32_e32 v38, v34, v38
	v_mul_f32_e32 v39, v35, v39
	v_fma_f32 v38, v34, v38, v34
	v_fma_f32 v39, v35, v39, v35
	v_mul_f32_e32 v38, 0x3f4c422a, v38
	v_mul_f32_e32 v39, 0x3f4c422a, v39
	v_mul_f32_e32 v38, 0xc038aa3b, v38
	v_mul_f32_e32 v39, 0xc038aa3b, v39
	v_exp_f32_e32 v38, v38
	v_exp_f32_e32 v39, v39
	v_cvt_pk_bf16_f32 v32, v32, v33
	v_add_f32_e32 v38, 1.0, v38
	v_add_f32_e32 v39, 1.0, v39
	v_rcp_f32_e32 v38, v38
	v_rcp_f32_e32 v39, v39
	s_nop 0
	v_pk_mul_f32 v[34:35], v[34:35], v[38:39]
	s_nop 0
	v_cvt_pk_bf16_f32 v33, v34, v35
	ds_write2_b64 v42, v[36:37], v[32:33] offset0:168 offset1:172
	ds_read_b32 v32, v127 offset:384
	s_waitcnt lgkmcnt(0)
	v_pk_mul_f32 v[28:29], v[28:29], v[32:33] op_sel_hi:[1,0]
	s_nop 0
	v_mul_f32_e32 v33, 0x3d372713, v28
	v_mul_f32_e32 v33, v28, v33
	v_fma_f32 v33, v28, v33, v28
	v_mul_f32_e32 v33, 0x3f4c422a, v33
	v_mul_f32_e32 v33, 0xc038aa3b, v33
	v_exp_f32_e32 v33, v33
	s_nop 0
	v_add_f32_e32 v33, 1.0, v33
	v_rcp_f32_e32 v34, v33
	v_mul_f32_e32 v33, 0x3d372713, v29
	v_mul_f32_e32 v33, v29, v33
	v_fma_f32 v33, v29, v33, v29
	v_mul_f32_e32 v33, 0x3f4c422a, v33
	v_mul_f32_e32 v33, 0xc038aa3b, v33
	v_exp_f32_e32 v33, v33
	s_nop 0
	v_add_f32_e32 v33, 1.0, v33
	v_pk_mul_f32 v[30:31], v[30:31], v[32:33] op_sel_hi:[1,0]
	v_rcp_f32_e32 v35, v33
	v_mul_f32_e32 v33, 0x3d372713, v30
	v_mul_f32_e32 v33, v30, v33
	v_fma_f32 v33, v30, v33, v30
	v_mul_f32_e32 v33, 0x3f4c422a, v33
	v_mul_f32_e32 v33, 0xc038aa3b, v33
	v_exp_f32_e32 v33, v33
	v_pk_mul_f32 v[28:29], v[28:29], v[34:35]
	v_add_f32_e32 v33, 1.0, v33
	v_rcp_f32_e32 v34, v33
	v_mul_f32_e32 v33, 0x3d372713, v31
	v_mul_f32_e32 v33, v31, v33
	v_fma_f32 v33, v31, v33, v31
	v_mul_f32_e32 v33, 0x3f4c422a, v33
	v_mul_f32_e32 v33, 0xc038aa3b, v33
	v_exp_f32_e32 v33, v33
	v_cvt_pk_bf16_f32 v28, v28, v29
	v_add_f32_e32 v33, 1.0, v33
	v_rcp_f32_e32 v35, v33
	v_pk_mul_f32 v[24:25], v[24:25], v[32:33] op_sel_hi:[1,0]
	v_pk_mul_f32 v[26:27], v[26:27], v[32:33] op_sel_hi:[1,0]
	v_pk_mul_f32 v[20:21], v[20:21], v[32:33] op_sel_hi:[1,0]
	v_pk_mul_f32 v[30:31], v[30:31], v[34:35]
	v_pk_mul_f32 v[22:23], v[22:23], v[32:33] op_sel_hi:[1,0]
	v_cvt_pk_bf16_f32 v29, v30, v31
	v_mul_f32_e32 v30, 0x3d372713, v24
	v_mul_f32_e32 v31, 0x3d372713, v25
	v_mul_f32_e32 v30, v24, v30
	v_mul_f32_e32 v31, v25, v31
	v_fma_f32 v30, v24, v30, v24
	v_fma_f32 v31, v25, v31, v25
	v_mul_f32_e32 v30, 0x3f4c422a, v30
	v_mul_f32_e32 v31, 0x3f4c422a, v31
	v_mul_f32_e32 v30, 0xc038aa3b, v30
	v_mul_f32_e32 v31, 0xc038aa3b, v31
	v_exp_f32_e32 v30, v30
	v_exp_f32_e32 v31, v31
	v_pk_mul_f32 v[16:17], v[16:17], v[32:33] op_sel_hi:[1,0]
	v_pk_mul_f32 v[18:19], v[18:19], v[32:33] op_sel_hi:[1,0]
	v_add_f32_e32 v30, 1.0, v30
	v_add_f32_e32 v31, 1.0, v31
	v_rcp_f32_e32 v30, v30
	v_rcp_f32_e32 v31, v31
	s_nop 0
	v_pk_mul_f32 v[24:25], v[24:25], v[30:31]
	v_mul_f32_e32 v30, 0x3d372713, v26
	v_mul_f32_e32 v31, 0x3d372713, v27
	v_mul_f32_e32 v30, v26, v30
	v_mul_f32_e32 v31, v27, v31
	v_fma_f32 v30, v26, v30, v26
	v_fma_f32 v31, v27, v31, v27
	v_mul_f32_e32 v30, 0x3f4c422a, v30
	v_mul_f32_e32 v31, 0x3f4c422a, v31
	v_mul_f32_e32 v30, 0xc038aa3b, v30
	v_mul_f32_e32 v31, 0xc038aa3b, v31
	v_exp_f32_e32 v30, v30
	v_exp_f32_e32 v31, v31
	v_cvt_pk_bf16_f32 v24, v24, v25
	v_add_f32_e32 v30, 1.0, v30
	v_add_f32_e32 v31, 1.0, v31
	v_rcp_f32_e32 v30, v30
	v_rcp_f32_e32 v31, v31
	s_nop 0
	v_pk_mul_f32 v[26:27], v[26:27], v[30:31]
	s_nop 0
	v_cvt_pk_bf16_f32 v25, v26, v27
	v_add_u32_e32 v26, 0xc000, v126
	ds_write2_b64 v26, v[28:29], v[24:25] offset0:192 offset1:196
	v_mul_f32_e32 v24, 0x3d372713, v20
	v_mul_f32_e32 v25, 0x3d372713, v21
	v_mul_f32_e32 v24, v20, v24
	v_mul_f32_e32 v25, v21, v25
	v_fma_f32 v24, v20, v24, v20
	v_fma_f32 v25, v21, v25, v21
	v_mul_f32_e32 v24, 0x3f4c422a, v24
	v_mul_f32_e32 v25, 0x3f4c422a, v25
; DI unsigned pk2(float a, float b) { f32x2 v = {a, b}; bf16x2_t r = __builtin_convertvector(v, bf16x2_t); return __builtin_bit_cast(unsigned, r); }
;     DI void operator()(gacc_t& acc, int pm, int pn, char* lds, int tid, int wr, int wc, int lane) const {
;     ...
;         for (int m = 0; m < 8; ++m) {
;             const float r = rl[m * 16];
; #pragma unroll
;             for (int n = 0; n < 4; ++n) {
;                 float g[4];
; #pragma unroll
;                 for (int j = 0; j < 4; ++j) {
;                     const float x = acc[m][n][j] * r;
;                     const float u = 0.7978845608028654f * (x + 0.044715f * x * x * x);
;                     const float e = __builtin_amdgcn_exp2f(-2.885390081777927f * u);
;                     g[j] = x * __builtin_amdgcn_rcpf(1.0f + e);
;                 }
;                 u32x2 w; w.x = pk2(g[0], g[1]); w.y = pk2(g[2], g[3]);
;                 *(u32x2*)(lbase + m * 16 * 528 + n * 32) = w;
;             }
	v_mul_f32_e32 v24, 0xc038aa3b, v24
	v_mul_f32_e32 v25, 0xc038aa3b, v25
	v_exp_f32_e32 v24, v24
	v_exp_f32_e32 v25, v25
	v_add_f32_e32 v24, 1.0, v24
	v_add_f32_e32 v25, 1.0, v25
	v_rcp_f32_e32 v24, v24
	v_rcp_f32_e32 v25, v25
	s_nop 0
	v_pk_mul_f32 v[20:21], v[20:21], v[24:25]
	v_mul_f32_e32 v24, 0x3d372713, v22
	v_mul_f32_e32 v25, 0x3d372713, v23
	v_mul_f32_e32 v24, v22, v24
	v_mul_f32_e32 v25, v23, v25
	v_fma_f32 v24, v22, v24, v22
	v_fma_f32 v25, v23, v25, v23
	v_mul_f32_e32 v24, 0x3f4c422a, v24
	v_mul_f32_e32 v25, 0x3f4c422a, v25
	v_mul_f32_e32 v24, 0xc038aa3b, v24
	v_mul_f32_e32 v25, 0xc038aa3b, v25
	v_exp_f32_e32 v24, v24
	v_exp_f32_e32 v25, v25
	v_cvt_pk_bf16_f32 v20, v20, v21
	v_add_f32_e32 v24, 1.0, v24
	v_add_f32_e32 v25, 1.0, v25
	v_rcp_f32_e32 v24, v24
	v_rcp_f32_e32 v25, v25
	s_nop 0
	v_pk_mul_f32 v[22:23], v[22:23], v[24:25]
	s_nop 0
	v_cvt_pk_bf16_f32 v21, v22, v23
	v_mul_f32_e32 v22, 0x3d372713, v16
	v_mul_f32_e32 v23, 0x3d372713, v17
	v_mul_f32_e32 v22, v16, v22
	v_mul_f32_e32 v23, v17, v23
	v_fma_f32 v22, v16, v22, v16
	v_fma_f32 v23, v17, v23, v17
	v_mul_f32_e32 v22, 0x3f4c422a, v22
	v_mul_f32_e32 v23, 0x3f4c422a, v23
	v_mul_f32_e32 v22, 0xc038aa3b, v22
	v_mul_f32_e32 v23, 0xc038aa3b, v23
	v_exp_f32_e32 v22, v22
	v_exp_f32_e32 v23, v23
	v_add_f32_e32 v22, 1.0, v22
	v_add_f32_e32 v23, 1.0, v23
	v_rcp_f32_e32 v22, v22
	v_rcp_f32_e32 v23, v23
	s_nop 0
	v_pk_mul_f32 v[16:17], v[16:17], v[22:23]
	v_mul_f32_e32 v22, 0x3d372713, v18
	v_mul_f32_e32 v23, 0x3d372713, v19
	v_mul_f32_e32 v22, v18, v22
	v_mul_f32_e32 v23, v19, v23
	v_fma_f32 v22, v18, v22, v18
	v_fma_f32 v23, v19, v23, v19
	v_mul_f32_e32 v22, 0x3f4c422a, v22
	v_mul_f32_e32 v23, 0x3f4c422a, v23
	v_mul_f32_e32 v22, 0xc038aa3b, v22
	v_mul_f32_e32 v23, 0xc038aa3b, v23
	v_exp_f32_e32 v22, v22
	v_exp_f32_e32 v23, v23
	v_cvt_pk_bf16_f32 v16, v16, v17
	v_add_f32_e32 v22, 1.0, v22
	v_add_f32_e32 v23, 1.0, v23
	v_rcp_f32_e32 v22, v22
	v_rcp_f32_e32 v23, v23
	s_nop 0
	v_pk_mul_f32 v[18:19], v[18:19], v[22:23]
	s_nop 0
	v_cvt_pk_bf16_f32 v17, v18, v19
	ds_write2_b64 v26, v[20:21], v[16:17] offset0:200 offset1:204
	ds_read_b32 v16, v127 offset:448
	s_waitcnt lgkmcnt(0)
	v_pk_mul_f32 v[12:13], v[12:13], v[16:17] op_sel_hi:[1,0]
	s_nop 0
	v_mul_f32_e32 v17, 0x3d372713, v12
	v_mul_f32_e32 v17, v12, v17
	v_fma_f32 v17, v12, v17, v12
	v_mul_f32_e32 v17, 0x3f4c422a, v17
	v_mul_f32_e32 v17, 0xc038aa3b, v17
	v_exp_f32_e32 v17, v17
	s_nop 0
	v_add_f32_e32 v17, 1.0, v17
	v_rcp_f32_e32 v18, v17
	v_mul_f32_e32 v17, 0x3d372713, v13
	v_mul_f32_e32 v17, v13, v17
	v_fma_f32 v17, v13, v17, v13
	v_mul_f32_e32 v17, 0x3f4c422a, v17
	v_mul_f32_e32 v17, 0xc038aa3b, v17
	v_exp_f32_e32 v17, v17
	s_nop 0
	v_add_f32_e32 v17, 1.0, v17
	v_pk_mul_f32 v[14:15], v[14:15], v[16:17] op_sel_hi:[1,0]
	v_rcp_f32_e32 v19, v17
	v_mul_f32_e32 v17, 0x3d372713, v14
	v_mul_f32_e32 v17, v14, v17
	v_fma_f32 v17, v14, v17, v14
	v_mul_f32_e32 v17, 0x3f4c422a, v17
	v_mul_f32_e32 v17, 0xc038aa3b, v17
	v_exp_f32_e32 v17, v17
	v_pk_mul_f32 v[12:13], v[12:13], v[18:19]
	v_add_f32_e32 v17, 1.0, v17
	v_rcp_f32_e32 v18, v17
	v_mul_f32_e32 v17, 0x3d372713, v15
	v_mul_f32_e32 v17, v15, v17
	v_fma_f32 v17, v15, v17, v15
	v_mul_f32_e32 v17, 0x3f4c422a, v17
	v_mul_f32_e32 v17, 0xc038aa3b, v17
	v_exp_f32_e32 v17, v17
	v_cvt_pk_bf16_f32 v12, v12, v13
	v_add_f32_e32 v17, 1.0, v17
	v_rcp_f32_e32 v19, v17
	v_pk_mul_f32 v[8:9], v[8:9], v[16:17] op_sel_hi:[1,0]
	v_pk_mul_f32 v[10:11], v[10:11], v[16:17] op_sel_hi:[1,0]
	v_pk_mul_f32 v[4:5], v[4:5], v[16:17] op_sel_hi:[1,0]
	v_pk_mul_f32 v[14:15], v[14:15], v[18:19]
	v_pk_mul_f32 v[6:7], v[6:7], v[16:17] op_sel_hi:[1,0]
	v_cvt_pk_bf16_f32 v13, v14, v15
	v_mul_f32_e32 v14, 0x3d372713, v8
	v_mul_f32_e32 v15, 0x3d372713, v9
	v_mul_f32_e32 v14, v8, v14
	v_mul_f32_e32 v15, v9, v15
	v_fma_f32 v14, v8, v14, v8
	v_fma_f32 v15, v9, v15, v9
	v_mul_f32_e32 v14, 0x3f4c422a, v14
	v_mul_f32_e32 v15, 0x3f4c422a, v15
	v_mul_f32_e32 v14, 0xc038aa3b, v14
	v_mul_f32_e32 v15, 0xc038aa3b, v15
	v_exp_f32_e32 v14, v14
	v_exp_f32_e32 v15, v15
	v_pk_mul_f32 v[0:1], v[0:1], v[16:17] op_sel_hi:[1,0]
	v_pk_mul_f32 v[2:3], v[2:3], v[16:17] op_sel_hi:[1,0]
	v_add_f32_e32 v14, 1.0, v14
	v_add_f32_e32 v15, 1.0, v15
	v_rcp_f32_e32 v14, v14
	v_rcp_f32_e32 v15, v15
	s_nop 0
	v_pk_mul_f32 v[8:9], v[8:9], v[14:15]
	v_mul_f32_e32 v14, 0x3d372713, v10
	v_mul_f32_e32 v15, 0x3d372713, v11
	v_mul_f32_e32 v14, v10, v14
	v_mul_f32_e32 v15, v11, v15
	v_fma_f32 v14, v10, v14, v10
	v_fma_f32 v15, v11, v15, v11
	v_mul_f32_e32 v14, 0x3f4c422a, v14
	v_mul_f32_e32 v15, 0x3f4c422a, v15
	v_mul_f32_e32 v14, 0xc038aa3b, v14
	v_mul_f32_e32 v15, 0xc038aa3b, v15
	v_exp_f32_e32 v14, v14
	v_exp_f32_e32 v15, v15
	v_cvt_pk_bf16_f32 v8, v8, v9
	v_add_f32_e32 v14, 1.0, v14
	v_add_f32_e32 v15, 1.0, v15
	v_rcp_f32_e32 v14, v14
	v_rcp_f32_e32 v15, v15
	s_nop 0
	v_pk_mul_f32 v[10:11], v[10:11], v[14:15]
	s_nop 0
	v_cvt_pk_bf16_f32 v9, v10, v11
	v_add_u32_e32 v10, 0xe000, v126
	ds_write2_b64 v10, v[12:13], v[8:9] offset0:224 offset1:228
	v_mul_f32_e32 v8, 0x3d372713, v4
	v_mul_f32_e32 v9, 0x3d372713, v5
	v_mul_f32_e32 v8, v4, v8
	v_mul_f32_e32 v9, v5, v9
	v_fma_f32 v8, v4, v8, v4
	v_fma_f32 v9, v5, v9, v5
	v_mul_f32_e32 v8, 0x3f4c422a, v8
	v_mul_f32_e32 v9, 0x3f4c422a, v9
	v_mul_f32_e32 v8, 0xc038aa3b, v8
	v_mul_f32_e32 v9, 0xc038aa3b, v9
	v_exp_f32_e32 v8, v8
	v_exp_f32_e32 v9, v9
	v_add_f32_e32 v8, 1.0, v8
	v_add_f32_e32 v9, 1.0, v9
	v_rcp_f32_e32 v8, v8
	v_rcp_f32_e32 v9, v9
	s_nop 0
	v_pk_mul_f32 v[4:5], v[4:5], v[8:9]
	v_mul_f32_e32 v8, 0x3d372713, v6
	v_mul_f32_e32 v9, 0x3d372713, v7
	v_mul_f32_e32 v8, v6, v8
	v_mul_f32_e32 v9, v7, v9
	v_fma_f32 v8, v6, v8, v6
; DI unsigned pk2(float a, float b) { f32x2 v = {a, b}; bf16x2_t r = __builtin_convertvector(v, bf16x2_t); return __builtin_bit_cast(unsigned, r); }
; DI void store_tile_from_lds(const char* lds, bf16_t* dst, long ld, int tid) {
; #pragma unroll
;     for (int k = 0; k < 16; ++k) {
;         const int id = tid + NTH * k, row = id >> 5, ch = id & 31;
;         const u32x4 v = *(const u32x4*)(lds + row * 528 + ch * 16);
;         *(u32x4*)(dst + (long)row * ld + ch * 8) = v;
;     }
; }
;     DI void operator()(gacc_t& acc, int pm, int pn, char* lds, int tid, int wr, int wc, int lane) const {
;     ...
;         for (int m = 0; m < 8; ++m) {
;             const float r = rl[m * 16];
; #pragma unroll
;             for (int n = 0; n < 4; ++n) {
;                 float g[4];
; #pragma unroll
;                 for (int j = 0; j < 4; ++j) {
;                     const float x = acc[m][n][j] * r;
;                     const float u = 0.7978845608028654f * (x + 0.044715f * x * x * x);
;                     const float e = __builtin_amdgcn_exp2f(-2.885390081777927f * u);
;                     g[j] = x * __builtin_amdgcn_rcpf(1.0f + e);
;                 }
;                 u32x2 w; w.x = pk2(g[0], g[1]); w.y = pk2(g[2], g[3]);
;                 *(u32x2*)(lbase + m * 16 * 528 + n * 32) = w;
;             }
;             __builtin_amdgcn_sched_barrier(0);
;         }
;         __syncthreads();
;         store_tile_from_lds(lds, z + (long)pm * 256 * 2048 + pn * 256, 2048, tid);
;         __syncthreads();
	v_fma_f32 v9, v7, v9, v7
	v_mul_f32_e32 v8, 0x3f4c422a, v8
	v_mul_f32_e32 v9, 0x3f4c422a, v9
	v_mul_f32_e32 v8, 0xc038aa3b, v8
	v_mul_f32_e32 v9, 0xc038aa3b, v9
	v_exp_f32_e32 v8, v8
	v_exp_f32_e32 v9, v9
	v_cvt_pk_bf16_f32 v4, v4, v5
	v_add_f32_e32 v8, 1.0, v8
	v_add_f32_e32 v9, 1.0, v9
	v_rcp_f32_e32 v8, v8
	v_rcp_f32_e32 v9, v9
	s_nop 0
	v_pk_mul_f32 v[6:7], v[6:7], v[8:9]
	s_nop 0
	v_cvt_pk_bf16_f32 v5, v6, v7
	v_mul_f32_e32 v6, 0x3d372713, v0
	v_mul_f32_e32 v7, 0x3d372713, v1
	v_mul_f32_e32 v6, v0, v6
	v_mul_f32_e32 v7, v1, v7
	v_fma_f32 v6, v0, v6, v0
	v_fma_f32 v7, v1, v7, v1
	v_mul_f32_e32 v6, 0x3f4c422a, v6
	v_mul_f32_e32 v7, 0x3f4c422a, v7
	v_mul_f32_e32 v6, 0xc038aa3b, v6
	v_mul_f32_e32 v7, 0xc038aa3b, v7
	v_exp_f32_e32 v6, v6
	v_exp_f32_e32 v7, v7
	v_add_f32_e32 v6, 1.0, v6
	v_add_f32_e32 v7, 1.0, v7
	v_rcp_f32_e32 v6, v6
	v_rcp_f32_e32 v7, v7
	s_nop 0
	v_pk_mul_f32 v[0:1], v[0:1], v[6:7]
	v_mul_f32_e32 v6, 0x3d372713, v2
	v_mul_f32_e32 v7, 0x3d372713, v3
	v_mul_f32_e32 v6, v2, v6
	v_mul_f32_e32 v7, v3, v7
	v_fma_f32 v6, v2, v6, v2
	v_fma_f32 v7, v3, v7, v3
	v_mul_f32_e32 v6, 0x3f4c422a, v6
	v_mul_f32_e32 v7, 0x3f4c422a, v7
	v_mul_f32_e32 v6, 0xc038aa3b, v6
	v_mul_f32_e32 v7, 0xc038aa3b, v7
	v_exp_f32_e32 v6, v6
	v_exp_f32_e32 v7, v7
	v_cvt_pk_bf16_f32 v0, v0, v1
	v_add_f32_e32 v6, 1.0, v6
	v_add_f32_e32 v7, 1.0, v7
	v_rcp_f32_e32 v6, v6
	v_rcp_f32_e32 v7, v7
	s_nop 0
	v_pk_mul_f32 v[2:3], v[2:3], v[6:7]
	s_nop 0
	v_cvt_pk_bf16_f32 v1, v2, v3
	ds_write2_b64 v10, v[4:5], v[0:1] offset0:232 offset1:236
	s_lshl_b64 s[8:9], s[8:9], 20
	s_add_u32 s8, s70, s8
	s_addc_u32 s9, s71, s9
	s_lshl_b32 s6, s6, 8
	s_ashr_i32 s7, s6, 31
	v_lshlrev_b32_e32 v0, 4, v125
	s_lshl_b64 s[6:7], s[6:7], 1
	v_and_b32_e32 v146, 0x1f0, v0
	s_add_u32 s6, s8, s6
	v_add_u32_e32 v4, 0, v146
	v_ashrrev_i32_e32 v6, 5, v125
	s_addc_u32 s7, s9, s7
	v_mad_u64_u32 v[0:1], s[8:9], v6, s3, v[4:5]
	s_waitcnt lgkmcnt(0)
	s_barrier
	ds_read_b128 v[0:3], v0
	v_ashrrev_i32_e32 v7, 31, v6
	v_lshl_add_u64 v[8:9], s[6:7], 0, v[146:147]
	v_lshlrev_b64 v[6:7], 12, v[6:7]
	v_lshl_add_u64 v[6:7], v[8:9], 0, v[6:7]
	s_waitcnt lgkmcnt(0)
	flat_store_dwordx4 v[6:7], v[0:3]
	s_add_i32 s17, s17, 1
	s_nop 0
	v_add_u32_e32 v0, 0x200, v125
	v_ashrrev_i32_e32 v6, 5, v0
	v_mad_u64_u32 v[0:1], s[6:7], v6, s3, v[4:5]
	ds_read_b128 v[0:3], v0
	v_ashrrev_i32_e32 v7, 31, v6
	v_lshlrev_b64 v[6:7], 12, v[6:7]
	v_lshl_add_u64 v[6:7], v[8:9], 0, v[6:7]
	s_waitcnt lgkmcnt(0)
	flat_store_dwordx4 v[6:7], v[0:3]
	s_nop 1
	v_add_u32_e32 v0, 0x400, v125
	v_ashrrev_i32_e32 v6, 5, v0
	v_mad_u64_u32 v[0:1], s[6:7], v6, s3, v[4:5]
	ds_read_b128 v[0:3], v0
	v_ashrrev_i32_e32 v7, 31, v6
	v_lshlrev_b64 v[6:7], 12, v[6:7]
	v_lshl_add_u64 v[6:7], v[8:9], 0, v[6:7]
	s_waitcnt lgkmcnt(0)
	flat_store_dwordx4 v[6:7], v[0:3]
	s_nop 1
	v_add_u32_e32 v0, 0x600, v125
	v_ashrrev_i32_e32 v6, 5, v0
	v_mad_u64_u32 v[0:1], s[6:7], v6, s3, v[4:5]
	ds_read_b128 v[0:3], v0
	v_ashrrev_i32_e32 v7, 31, v6
	v_lshlrev_b64 v[6:7], 12, v[6:7]
	v_lshl_add_u64 v[6:7], v[8:9], 0, v[6:7]
	s_waitcnt lgkmcnt(0)
	flat_store_dwordx4 v[6:7], v[0:3]
	s_nop 1
	v_add_u32_e32 v0, 0x800, v125
	v_ashrrev_i32_e32 v6, 5, v0
	v_mad_u64_u32 v[0:1], s[6:7], v6, s3, v[4:5]
	ds_read_b128 v[0:3], v0
	v_ashrrev_i32_e32 v7, 31, v6
	v_lshlrev_b64 v[6:7], 12, v[6:7]
	v_lshl_add_u64 v[6:7], v[8:9], 0, v[6:7]
	s_waitcnt lgkmcnt(0)
	flat_store_dwordx4 v[6:7], v[0:3]
	s_nop 1
	v_add_u32_e32 v0, 0xa00, v125
	v_ashrrev_i32_e32 v6, 5, v0
	v_mad_u64_u32 v[0:1], s[6:7], v6, s3, v[4:5]
	ds_read_b128 v[0:3], v0
	v_ashrrev_i32_e32 v7, 31, v6
	v_lshlrev_b64 v[6:7], 12, v[6:7]
	v_lshl_add_u64 v[6:7], v[8:9], 0, v[6:7]
	s_waitcnt lgkmcnt(0)
	flat_store_dwordx4 v[6:7], v[0:3]
	s_nop 1
	v_add_u32_e32 v0, 0xc00, v125
	v_ashrrev_i32_e32 v6, 5, v0
	v_mad_u64_u32 v[0:1], s[6:7], v6, s3, v[4:5]
	ds_read_b128 v[0:3], v0
	v_ashrrev_i32_e32 v7, 31, v6
	v_lshlrev_b64 v[6:7], 12, v[6:7]
	v_lshl_add_u64 v[6:7], v[8:9], 0, v[6:7]
	s_waitcnt lgkmcnt(0)
	flat_store_dwordx4 v[6:7], v[0:3]
	s_nop 1
	v_add_u32_e32 v0, 0xe00, v125
	v_ashrrev_i32_e32 v6, 5, v0
	v_mad_u64_u32 v[0:1], s[6:7], v6, s3, v[4:5]
	ds_read_b128 v[0:3], v0
	v_ashrrev_i32_e32 v7, 31, v6
	v_lshlrev_b64 v[6:7], 12, v[6:7]
	v_lshl_add_u64 v[6:7], v[8:9], 0, v[6:7]
	s_waitcnt lgkmcnt(0)
	flat_store_dwordx4 v[6:7], v[0:3]
	s_nop 1
	v_add_u32_e32 v0, 0x1000, v125
	v_ashrrev_i32_e32 v6, 5, v0
	v_mad_u64_u32 v[0:1], s[6:7], v6, s3, v[4:5]
	ds_read_b128 v[0:3], v0
	v_ashrrev_i32_e32 v7, 31, v6
	v_lshlrev_b64 v[6:7], 12, v[6:7]
	v_lshl_add_u64 v[6:7], v[8:9], 0, v[6:7]
	s_waitcnt lgkmcnt(0)
	flat_store_dwordx4 v[6:7], v[0:3]
	s_nop 1
	v_add_u32_e32 v0, 0x1200, v125
	v_ashrrev_i32_e32 v6, 5, v0
	v_mad_u64_u32 v[0:1], s[6:7], v6, s3, v[4:5]
	ds_read_b128 v[0:3], v0
	v_ashrrev_i32_e32 v7, 31, v6
	v_lshlrev_b64 v[6:7], 12, v[6:7]
	v_lshl_add_u64 v[6:7], v[8:9], 0, v[6:7]
	s_waitcnt lgkmcnt(0)
	flat_store_dwordx4 v[6:7], v[0:3]
	s_nop 1
	v_add_u32_e32 v0, 0x1400, v125
	v_ashrrev_i32_e32 v6, 5, v0
	v_mad_u64_u32 v[0:1], s[6:7], v6, s3, v[4:5]
	ds_read_b128 v[0:3], v0
	v_ashrrev_i32_e32 v7, 31, v6
	v_lshlrev_b64 v[6:7], 12, v[6:7]
	v_lshl_add_u64 v[6:7], v[8:9], 0, v[6:7]
	s_waitcnt lgkmcnt(0)
	flat_store_dwordx4 v[6:7], v[0:3]
	s_nop 1
	v_add_u32_e32 v0, 0x1600, v125
	v_ashrrev_i32_e32 v6, 5, v0
	v_mad_u64_u32 v[0:1], s[6:7], v6, s3, v[4:5]
	ds_read_b128 v[0:3], v0
	v_ashrrev_i32_e32 v7, 31, v6
	v_lshlrev_b64 v[6:7], 12, v[6:7]
	v_lshl_add_u64 v[6:7], v[8:9], 0, v[6:7]
	s_waitcnt lgkmcnt(0)
	flat_store_dwordx4 v[6:7], v[0:3]
	s_nop 1
	v_add_u32_e32 v0, 0x1800, v125
	v_ashrrev_i32_e32 v6, 5, v0
	v_mad_u64_u32 v[0:1], s[6:7], v6, s3, v[4:5]
	ds_read_b128 v[0:3], v0
	v_ashrrev_i32_e32 v7, 31, v6
	v_lshlrev_b64 v[6:7], 12, v[6:7]
	v_lshl_add_u64 v[6:7], v[8:9], 0, v[6:7]
	s_waitcnt lgkmcnt(0)
	flat_store_dwordx4 v[6:7], v[0:3]
	s_nop 1
	v_add_u32_e32 v0, 0x1a00, v125
	v_ashrrev_i32_e32 v6, 5, v0
	v_mad_u64_u32 v[0:1], s[6:7], v6, s3, v[4:5]
	ds_read_b128 v[0:3], v0
	v_ashrrev_i32_e32 v7, 31, v6
	v_lshlrev_b64 v[6:7], 12, v[6:7]
	v_lshl_add_u64 v[6:7], v[8:9], 0, v[6:7]
	s_waitcnt lgkmcnt(0)
	flat_store_dwordx4 v[6:7], v[0:3]
	s_nop 1
	v_add_u32_e32 v0, 0x1c00, v125
	v_ashrrev_i32_e32 v6, 5, v0
	v_mad_u64_u32 v[0:1], s[6:7], v6, s3, v[4:5]
	ds_read_b128 v[0:3], v0
	v_ashrrev_i32_e32 v7, 31, v6
	v_lshlrev_b64 v[6:7], 12, v[6:7]
	v_lshl_add_u64 v[6:7], v[8:9], 0, v[6:7]
	s_waitcnt lgkmcnt(0)
	flat_store_dwordx4 v[6:7], v[0:3]
	s_nop 1
	v_add_u32_e32 v0, 0x1e00, v125
	v_ashrrev_i32_e32 v6, 5, v0
	v_mad_u64_u32 v[0:1], s[6:7], v6, s3, v[4:5]
	ds_read_b128 v[0:3], v0
	v_ashrrev_i32_e32 v7, 31, v6
	s_mul_i32 s6, s17, s28
	v_lshlrev_b64 v[4:5], 12, v[6:7]
	s_add_i32 s6, s6, s2
	v_lshl_add_u64 v[4:5], v[8:9], 0, v[4:5]
	s_cmpk_lt_i32 s6, 0xa00
	s_waitcnt lgkmcnt(0)
	flat_store_dwordx4 v[4:5], v[0:3]
	s_waitcnt lgkmcnt(0)
	s_barrier
	s_cbranch_scc1 .LBB0_370

; #define MFMA16(a, b, c) __builtin_amdgcn_mfma_f32_16x16x32_bf16((a), (b), (c), 0, 0, 0)
; DI bf16x8 ldfrag(const char* lds, int row, int chunk) { return *(const bf16x8*)(lds + swz(row, chunk)); }
; template <bool RSTD, bool SWAP>
; DI void gemm_tile(gacc_t& acc, const bf16_t* __restrict__ A, int lda, const bf16_t* __restrict__ Bt, int ldb, int K,
;                   char* lds, int tid, int wr, int wc, int lane, const float* ssq_row) {
;     ...
;     GEMM_ISSUE(0, 0);
;     if (RSTD && tid < 256) {
;         const f32x4 q = *(const f32x4*)ssq_row;
;         ((float*)(lds + RSTD_OFF))[tid] = 1.0f / sqrtf(((q.x + q.y) + (q.z + q.w)) * (1.0f / 1024.0f) + 1e-6f);
;     }
;     asm volatile("s_waitcnt vmcnt(0)" ::: "memory");
;     __syncthreads();
;     for (int kt = 0; kt < nk; ++kt) {
;         const char* cur = lds + (kt & 1) * 65536;
;         if (kt + 1 < nk) GEMM_ISSUE(kt + 1, (kt + 1) & 1);
;         bf16x8 bfr[2][4], afr[3];
; #pragma unroll
;         for (int n = 0; n < 4; ++n) bfr[0][n] = ldfrag(cur + 32768, wc * 64 + n * 16 + fr, fq);
;         afr[0] = ldfrag(cur, wr * 128 + fr, fq);
;         afr[1] = ldfrag(cur, wr * 128 + 16 + fr, fq);
; #pragma unroll
;         for (int idx = 0; idx < 16; ++idx) {
;             const int ks = idx >> 3, m = idx & 7;
;             if (idx < 14) afr[(idx + 2) % 3] = ldfrag(cur, wr * 128 + ((idx + 2) & 7) * 16 + fr, ((idx + 2) >> 3) * 4 + fq);
;             if (ks == 0 && m >= 2 && m < 6) bfr[1][m - 2] = ldfrag(cur + 32768, wc * 64 + (m - 2) * 16 + fr, 4 + fq);
; #pragma unroll
;             for (int n = 0; n < 4; ++n) acc[m][n] = SWAP ? MFMA16(bfr[ks][n], afr[idx % 3], acc[m][n]) : MFMA16(afr[idx % 3], bfr[ks][n], acc[m][n]);
.LBB0_523:
	v_lshl_add_u64 v[158:159], v[136:137], 0, s[4:5]
	s_mov_b64 s[18:19], 0x800080
	v_lshl_add_u64 v[162:163], v[158:159], 0, s[18:19]
	s_mov_b64 s[18:19], 0x820080
	s_add_i32 s16, s13, 0xffff0000
	s_and_b32 s17, s13, 0x10000
	v_lshl_add_u64 v[166:167], v[158:159], 0, s[18:19]
	s_mov_b64 s[18:19], 0x840080
	s_and_b32 s21, s16, 0x10000
	s_add_i32 s16, s17, 0
	v_lshl_add_u64 v[174:175], v[158:159], 0, s[18:19]
	s_mov_b64 s[18:19], 0x860080
	v_lshl_add_u64 v[156:157], v[138:139], 0, s[4:5]
	v_lshl_add_u64 v[158:159], v[158:159], 0, s[18:19]
	s_add_i32 s18, s16, s12
	v_lshl_add_u64 v[160:161], v[156:157], 0, s[14:15]
	s_add_i32 s19, s18, 0x8000
	s_mov_b32 m0, s18
	v_lshl_add_u64 v[164:165], v[156:157], 0, s[72:73]
	global_load_lds_dwordx4 v[160:161], off
	v_mfma_f32_16x16x32_bf16 v[60:63], v[202:205], v[236:239], v[60:63]
	s_mov_b32 m0, s19
	v_lshl_add_u64 v[172:173], v[156:157], 0, s[76:77]
	global_load_lds_dwordx4 v[162:163], off
	v_mfma_f32_16x16x32_bf16 v[56:59], v[206:209], v[236:239], v[56:59]
	s_add_i32 m0, s18, 0x2000
	v_lshl_add_u64 v[156:157], v[156:157], 0, s[0:1]
	global_load_lds_dwordx4 v[164:165], off
	v_mfma_f32_16x16x32_bf16 v[52:55], v[210:213], v[236:239], v[52:55]
	s_add_i32 m0, s18, 0xa000
	s_add_i32 s17, s21, 0
	global_load_lds_dwordx4 v[166:167], off
	v_mfma_f32_16x16x32_bf16 v[48:51], v[214:217], v[236:239], v[48:51]
	s_add_i32 m0, s18, 0x4000
	v_add_u32_e32 v146, s17, v142
	global_load_lds_dwordx4 v[172:173], off
	v_mfma_f32_16x16x32_bf16 v[44:47], v[202:205], v[240:243], v[44:47]
	s_add_i32 m0, s18, 0xc000
	v_add3_u32 v155, v146, v148, v149
	global_load_lds_dwordx4 v[174:175], off
	v_mfma_f32_16x16x32_bf16 v[40:43], v[206:209], v[240:243], v[40:43]
	s_add_i32 m0, s18, 0x6000
	v_add_u32_e32 v176, v146, v144
	global_load_lds_dwordx4 v[156:157], off
	v_mfma_f32_16x16x32_bf16 v[36:39], v[210:213], v[240:243], v[36:39]
	s_add_i32 m0, s18, 0xe000
	s_nop 0
	global_load_lds_dwordx4 v[158:159], off
	v_mfma_f32_16x16x32_bf16 v[32:35], v[214:217], v[240:243], v[32:35]
	ds_read_b128 v[156:159], v155 offset:32768
	ds_read_b128 v[160:163], v155 offset:34816
	ds_read_b128 v[186:189], v155 offset:36864
	ds_read_b128 v[190:193], v155 offset:38912
	ds_read_b128 v[164:167], v176
	ds_read_b128 v[194:197], v176 offset:2048
	v_add_u32_e32 v155, v146, v150
	ds_read_b128 v[198:201], v176 offset:4096
	v_mfma_f32_16x16x32_bf16 v[28:31], v[202:205], v[244:247], v[28:31]
	v_mfma_f32_16x16x32_bf16 v[24:27], v[206:209], v[244:247], v[24:27]
	v_mfma_f32_16x16x32_bf16 v[20:23], v[210:213], v[244:247], v[20:23]
	v_mfma_f32_16x16x32_bf16 v[16:19], v[214:217], v[244:247], v[16:19]
	v_mfma_f32_16x16x32_bf16 v[12:15], v[202:205], v[248:251], v[12:15]
	v_mfma_f32_16x16x32_bf16 v[8:11], v[206:209], v[248:251], v[8:11]
	v_mfma_f32_16x16x32_bf16 v[4:7], v[210:213], v[248:251], v[4:7]
	v_mfma_f32_16x16x32_bf16 v[0:3], v[214:217], v[248:251], v[0:3]
	s_waitcnt lgkmcnt(2)
	v_mfma_f32_16x16x32_bf16 v[124:127], v[156:159], v[164:167], v[124:127]
	v_add_u32_e32 v146, v146, v152
	v_mfma_f32_16x16x32_bf16 v[120:123], v[160:163], v[164:167], v[120:123]
	v_mfma_f32_16x16x32_bf16 v[116:119], v[186:189], v[164:167], v[116:119]
	v_mfma_f32_16x16x32_bf16 v[112:115], v[190:193], v[164:167], v[112:115]
	ds_read_b128 v[164:167], v155
	v_add_u32_e32 v155, s17, v145
	v_add_u32_e32 v172, v155, v151
	s_waitcnt lgkmcnt(2)
	v_mfma_f32_16x16x32_bf16 v[108:111], v[156:159], v[194:197], v[108:111]
	v_mfma_f32_16x16x32_bf16 v[104:107], v[160:163], v[194:197], v[104:107]
	v_mfma_f32_16x16x32_bf16 v[100:103], v[186:189], v[194:197], v[100:103]
	v_mfma_f32_16x16x32_bf16 v[96:99], v[190:193], v[194:197], v[96:99]
	ds_read_b128 v[194:197], v176 offset:8192
	ds_read_b128 v[202:205], v172 offset:32768
	s_waitcnt lgkmcnt(3)
	v_mfma_f32_16x16x32_bf16 v[92:95], v[156:159], v[198:201], v[92:95]
	v_mfma_f32_16x16x32_bf16 v[88:91], v[160:163], v[198:201], v[88:91]
	v_mfma_f32_16x16x32_bf16 v[84:87], v[186:189], v[198:201], v[84:87]
	v_mfma_f32_16x16x32_bf16 v[80:83], v[190:193], v[198:201], v[80:83]
	ds_read_b128 v[198:201], v176 offset:10240
	ds_read_b128 v[206:209], v172 offset:34816
	s_waitcnt lgkmcnt(4)
	v_mfma_f32_16x16x32_bf16 v[76:79], v[156:159], v[164:167], v[76:79]
	v_mfma_f32_16x16x32_bf16 v[72:75], v[160:163], v[164:167], v[72:75]
	v_mfma_f32_16x16x32_bf16 v[68:71], v[186:189], v[164:167], v[68:71]
	v_mfma_f32_16x16x32_bf16 v[64:67], v[190:193], v[164:167], v[64:67]
	ds_read_b128 v[210:213], v172 offset:36864
	v_add_u32_e32 v172, v155, v153
	ds_read_b128 v[164:167], v176 offset:12288
	s_waitcnt lgkmcnt(5)
	v_mfma_f32_16x16x32_bf16 v[60:63], v[156:159], v[194:197], v[60:63]
	v_mfma_f32_16x16x32_bf16 v[56:59], v[160:163], v[194:197], v[56:59]
	v_mfma_f32_16x16x32_bf16 v[52:55], v[186:189], v[194:197], v[52:55]
	v_mfma_f32_16x16x32_bf16 v[48:51], v[190:193], v[194:197], v[48:51]
	ds_read_b128 v[214:217], v172 offset:38912
	ds_read_b128 v[194:197], v146
	v_add_u32_e32 v146, v155, v144
	s_waitcnt lgkmcnt(5)
	v_mfma_f32_16x16x32_bf16 v[44:47], v[156:159], v[198:201], v[44:47]
	v_mfma_f32_16x16x32_bf16 v[40:43], v[160:163], v[198:201], v[40:43]
	v_mfma_f32_16x16x32_bf16 v[36:39], v[186:189], v[198:201], v[36:39]
	v_mfma_f32_16x16x32_bf16 v[32:35], v[190:193], v[198:201], v[32:35]
	ds_read_b128 v[198:201], v146
	s_waitcnt lgkmcnt(3)
	v_mfma_f32_16x16x32_bf16 v[28:31], v[156:159], v[164:167], v[28:31]
	v_mfma_f32_16x16x32_bf16 v[24:27], v[160:163], v[164:167], v[24:27]
	v_mfma_f32_16x16x32_bf16 v[20:23], v[186:189], v[164:167], v[20:23]
	v_mfma_f32_16x16x32_bf16 v[16:19], v[190:193], v[164:167], v[16:19]
	ds_read_b128 v[164:167], v146 offset:2048
	s_waitcnt lgkmcnt(2)
; #define MFMA16(a, b, c) __builtin_amdgcn_mfma_f32_16x16x32_bf16((a), (b), (c), 0, 0, 0)
; DI bf16x8 ldfrag(const char* lds, int row, int chunk) { return *(const bf16x8*)(lds + swz(row, chunk)); }
; #define GEMM_SG1() do { __builtin_amdgcn_sched_group_barrier(0x100, 1, 0); __builtin_amdgcn_sched_group_barrier(0x008, 4, 0); } while (0)
; #define GEMM_SG2() do { __builtin_amdgcn_sched_group_barrier(0x100, 2, 0); __builtin_amdgcn_sched_group_barrier(0x008, 4, 0); } while (0)
; template <bool RSTD, bool SWAP>
; DI void gemm_tile(gacc_t& acc, const bf16_t* __restrict__ A, int lda, const bf16_t* __restrict__ Bt, int ldb, int K,
;                   char* lds, int tid, int wr, int wc, int lane, const float* ssq_row) {
;     ...
;     for (int kt = 0; kt < nk; ++kt) {
;         const char* cur = lds + (kt & 1) * 65536;
;         if (kt + 1 < nk) GEMM_ISSUE(kt + 1, (kt + 1) & 1);
;         bf16x8 bfr[2][4], afr[3];
; #pragma unroll
;         for (int n = 0; n < 4; ++n) bfr[0][n] = ldfrag(cur + 32768, wc * 64 + n * 16 + fr, fq);
;         afr[0] = ldfrag(cur, wr * 128 + fr, fq);
;         afr[1] = ldfrag(cur, wr * 128 + 16 + fr, fq);
; #pragma unroll
;         for (int idx = 0; idx < 16; ++idx) {
;             const int ks = idx >> 3, m = idx & 7;
;             if (idx < 14) afr[(idx + 2) % 3] = ldfrag(cur, wr * 128 + ((idx + 2) & 7) * 16 + fr, ((idx + 2) >> 3) * 4 + fq);
;             if (ks == 0 && m >= 2 && m < 6) bfr[1][m - 2] = ldfrag(cur + 32768, wc * 64 + (m - 2) * 16 + fr, 4 + fq);
; #pragma unroll
;             for (int n = 0; n < 4; ++n) acc[m][n] = SWAP ? MFMA16(bfr[ks][n], afr[idx % 3], acc[m][n]) : MFMA16(afr[idx % 3], bfr[ks][n], acc[m][n]);
;         }
;         __builtin_amdgcn_sched_group_barrier(0x100, 6, 0);
;     ...
;         GEMM_SG1(); GEMM_SG1(); GEMM_SG2(); GEMM_SG2(); GEMM_SG2(); GEMM_SG2(); GEMM_SG1(); GEMM_SG1();
;         GEMM_SG1(); GEMM_SG1(); GEMM_SG1(); GEMM_SG1(); GEMM_SG1(); GEMM_SG1();
;         __builtin_amdgcn_sched_group_barrier(0x008, 8, 0);
;         __builtin_amdgcn_sched_barrier(0);
;         asm volatile("s_waitcnt vmcnt(0)" ::: "memory");
;         __syncthreads();
	v_mfma_f32_16x16x32_bf16 v[8:11], v[160:163], v[194:197], v[8:11]
	v_add_u32_e32 v160, v155, v150
	v_mfma_f32_16x16x32_bf16 v[12:15], v[156:159], v[194:197], v[12:15]
	v_mfma_f32_16x16x32_bf16 v[4:7], v[186:189], v[194:197], v[4:7]
	v_mfma_f32_16x16x32_bf16 v[0:3], v[190:193], v[194:197], v[0:3]
	ds_read_b128 v[156:159], v146 offset:4096
	s_waitcnt lgkmcnt(2)
	v_mfma_f32_16x16x32_bf16 v[124:127], v[202:205], v[198:201], v[124:127]
	v_mfma_f32_16x16x32_bf16 v[120:123], v[206:209], v[198:201], v[120:123]
	v_mfma_f32_16x16x32_bf16 v[116:119], v[210:213], v[198:201], v[116:119]
	v_mfma_f32_16x16x32_bf16 v[112:115], v[214:217], v[198:201], v[112:115]
	ds_read_b128 v[160:163], v160
	s_waitcnt lgkmcnt(2)
	v_mfma_f32_16x16x32_bf16 v[108:111], v[202:205], v[164:167], v[108:111]
	v_mfma_f32_16x16x32_bf16 v[104:107], v[206:209], v[164:167], v[104:107]
	v_mfma_f32_16x16x32_bf16 v[100:103], v[210:213], v[164:167], v[100:103]
	v_mfma_f32_16x16x32_bf16 v[96:99], v[214:217], v[164:167], v[96:99]
	ds_read_b128 v[236:239], v146 offset:8192
	s_waitcnt lgkmcnt(2)
	v_mfma_f32_16x16x32_bf16 v[92:95], v[202:205], v[156:159], v[92:95]
	v_mfma_f32_16x16x32_bf16 v[88:91], v[206:209], v[156:159], v[88:91]
	v_mfma_f32_16x16x32_bf16 v[84:87], v[210:213], v[156:159], v[84:87]
	v_mfma_f32_16x16x32_bf16 v[80:83], v[214:217], v[156:159], v[80:83]
	ds_read_b128 v[240:243], v146 offset:10240
	ds_read_b128 v[244:247], v146 offset:12288
	v_add_u32_e32 v146, v155, v152
	ds_read_b128 v[248:251], v146
	s_waitcnt lgkmcnt(4)
	v_mfma_f32_16x16x32_bf16 v[76:79], v[202:205], v[160:163], v[76:79]
	v_mfma_f32_16x16x32_bf16 v[72:75], v[206:209], v[160:163], v[72:75]
	v_mfma_f32_16x16x32_bf16 v[68:71], v[210:213], v[160:163], v[68:71]
	v_mfma_f32_16x16x32_bf16 v[64:67], v[214:217], v[160:163], v[64:67]
	s_waitcnt lgkmcnt(0)
	s_waitcnt vmcnt(0)
	s_add_u32 s4, s4, 0x80
	s_addc_u32 s5, s5, 0
	s_add_i32 s13, s13, 0x10000
	s_cmpk_eq_i32 s4, 0x780
	s_waitcnt vmcnt(0)
	s_cbranch_scc0 .Lkhead_523
	s_barrier
	v_mfma_f32_16x16x32_bf16 v[60:63], v[202:205], v[236:239], v[60:63]
	v_mfma_f32_16x16x32_bf16 v[56:59], v[206:209], v[236:239], v[56:59]
	v_mfma_f32_16x16x32_bf16 v[52:55], v[210:213], v[236:239], v[52:55]
	v_mfma_f32_16x16x32_bf16 v[48:51], v[214:217], v[236:239], v[48:51]
	v_mfma_f32_16x16x32_bf16 v[44:47], v[202:205], v[240:243], v[44:47]
	v_mfma_f32_16x16x32_bf16 v[40:43], v[206:209], v[240:243], v[40:43]
	v_mfma_f32_16x16x32_bf16 v[36:39], v[210:213], v[240:243], v[36:39]
	v_mfma_f32_16x16x32_bf16 v[32:35], v[214:217], v[240:243], v[32:35]
	v_mfma_f32_16x16x32_bf16 v[28:31], v[202:205], v[244:247], v[28:31]
	v_mfma_f32_16x16x32_bf16 v[24:27], v[206:209], v[244:247], v[24:27]
	v_mfma_f32_16x16x32_bf16 v[20:23], v[210:213], v[244:247], v[20:23]
	v_mfma_f32_16x16x32_bf16 v[16:19], v[214:217], v[244:247], v[16:19]
	v_mfma_f32_16x16x32_bf16 v[12:15], v[202:205], v[248:251], v[12:15]
	v_mfma_f32_16x16x32_bf16 v[8:11], v[206:209], v[248:251], v[8:11]
	v_mfma_f32_16x16x32_bf16 v[4:7], v[210:213], v[248:251], v[4:7]
	v_mfma_f32_16x16x32_bf16 v[0:3], v[214:217], v[248:251], v[0:3]
	v_add_u32_e32 v146, s16, v142
	v_add3_u32 v155, v146, v148, v149
	ds_read_b128 v[136:139], v155 offset:32768
	ds_read_b128 v[156:159], v155 offset:34816
	ds_read_b128 v[164:167], v155 offset:36864
	ds_read_b128 v[186:189], v155 offset:38912
	v_add_u32_e32 v172, v146, v144
	ds_read_b128 v[160:163], v172
	ds_read_b128 v[190:193], v172 offset:2048
	v_add_u32_e32 v155, v146, v150
	ds_read_b128 v[194:197], v172 offset:4096
	s_waitcnt lgkmcnt(2)
	v_mfma_f32_16x16x32_bf16 v[124:127], v[136:139], v[160:163], v[124:127]
	v_add_u32_e32 v146, v146, v152
	s_lshl_b64 s[12:13], s[8:9], 8
	v_mfma_f32_16x16x32_bf16 v[120:123], v[156:159], v[160:163], v[120:123]
	v_mfma_f32_16x16x32_bf16 v[116:119], v[164:167], v[160:163], v[116:119]
	v_mfma_f32_16x16x32_bf16 v[112:115], v[186:189], v[160:163], v[112:115]
	ds_read_b128 v[160:163], v155
	v_add_u32_e32 v155, s16, v145
	v_add_u32_e32 v173, v155, v151
	s_waitcnt lgkmcnt(2)
	v_mfma_f32_16x16x32_bf16 v[108:111], v[136:139], v[190:193], v[108:111]
	v_mfma_f32_16x16x32_bf16 v[104:107], v[156:159], v[190:193], v[104:107]
	v_mfma_f32_16x16x32_bf16 v[100:103], v[164:167], v[190:193], v[100:103]
	v_mfma_f32_16x16x32_bf16 v[96:99], v[186:189], v[190:193], v[96:99]
	ds_read_b128 v[190:193], v172 offset:8192
	ds_read_b128 v[198:201], v173 offset:32768
	s_waitcnt lgkmcnt(3)
	v_mfma_f32_16x16x32_bf16 v[92:95], v[136:139], v[194:197], v[92:95]
	v_mfma_f32_16x16x32_bf16 v[88:91], v[156:159], v[194:197], v[88:91]
	v_mfma_f32_16x16x32_bf16 v[84:87], v[164:167], v[194:197], v[84:87]
	v_mfma_f32_16x16x32_bf16 v[80:83], v[186:189], v[194:197], v[80:83]
	ds_read_b128 v[194:197], v172 offset:10240
	ds_read_b128 v[202:205], v173 offset:34816
	s_waitcnt lgkmcnt(4)
	v_mfma_f32_16x16x32_bf16 v[76:79], v[136:139], v[160:163], v[76:79]
	v_mfma_f32_16x16x32_bf16 v[72:75], v[156:159], v[160:163], v[72:75]
	v_mfma_f32_16x16x32_bf16 v[68:71], v[164:167], v[160:163], v[68:71]
	v_mfma_f32_16x16x32_bf16 v[64:67], v[186:189], v[160:163], v[64:67]
	ds_read_b128 v[160:163], v172 offset:12288
	ds_read_b128 v[206:209], v173 offset:36864
	s_waitcnt lgkmcnt(5)
	v_mfma_f32_16x16x32_bf16 v[60:63], v[136:139], v[190:193], v[60:63]
	v_mfma_f32_16x16x32_bf16 v[56:59], v[156:159], v[190:193], v[56:59]
	v_mfma_f32_16x16x32_bf16 v[52:55], v[164:167], v[190:193], v[52:55]
	v_mfma_f32_16x16x32_bf16 v[48:51], v[186:189], v[190:193], v[48:51]
	ds_read_b128 v[190:193], v146
	v_add_u32_e32 v146, v155, v153
	ds_read_b128 v[210:213], v146 offset:38912
	v_add_u32_e32 v146, v155, v144
	s_waitcnt lgkmcnt(5)
; #define MFMA16(a, b, c) __builtin_amdgcn_mfma_f32_16x16x32_bf16((a), (b), (c), 0, 0, 0)
; DI unsigned pk2(float a, float b) { f32x2 v = {a, b}; bf16x2_t r = __builtin_convertvector(v, bf16x2_t); return __builtin_bit_cast(unsigned, r); }
; DI bf16x8 ldfrag(const char* lds, int row, int chunk) { return *(const bf16x8*)(lds + swz(row, chunk)); }
; #define GEMM_SG1() do { __builtin_amdgcn_sched_group_barrier(0x100, 1, 0); __builtin_amdgcn_sched_group_barrier(0x008, 4, 0); } while (0)
; template <bool RSTD, bool SWAP>
; DI void gemm_tile(gacc_t& acc, const bf16_t* __restrict__ A, int lda, const bf16_t* __restrict__ Bt, int ldb, int K,
;                   char* lds, int tid, int wr, int wc, int lane, const float* ssq_row) {
;     ...
;         for (int idx = 0; idx < 16; ++idx) {
;             const int ks = idx >> 3, m = idx & 7;
;             if (idx < 14) afr[(idx + 2) % 3] = ldfrag(cur, wr * 128 + ((idx + 2) & 7) * 16 + fr, ((idx + 2) >> 3) * 4 + fq);
;             if (ks == 0 && m >= 2 && m < 6) bfr[1][m - 2] = ldfrag(cur + 32768, wc * 64 + (m - 2) * 16 + fr, 4 + fq);
; #pragma unroll
;             for (int n = 0; n < 4; ++n) acc[m][n] = SWAP ? MFMA16(bfr[ks][n], afr[idx % 3], acc[m][n]) : MFMA16(afr[idx % 3], bfr[ks][n], acc[m][n]);
;         }
;         __builtin_amdgcn_sched_group_barrier(0x100, 6, 0);
;     ...
;         GEMM_SG1(); GEMM_SG1(); GEMM_SG2(); GEMM_SG2(); GEMM_SG2(); GEMM_SG2(); GEMM_SG1(); GEMM_SG1();
;         GEMM_SG1(); GEMM_SG1(); GEMM_SG1(); GEMM_SG1(); GEMM_SG1(); GEMM_SG1();
;         __builtin_amdgcn_sched_group_barrier(0x008, 8, 0);
;         __builtin_amdgcn_sched_barrier(0);
;         asm volatile("s_waitcnt vmcnt(0)" ::: "memory");
;         __syncthreads();
;     DI void operator()(gacc_t& acc, int pm, int pn, char* lds, int tid, int wr, int wc, int lane) const {
;         asm volatile("" : "+v"(tid), "+v"(lane));
;         const int fr = lane & 15, fq = lane >> 4, wid = tid >> 6;
;         char* lbase = lds + (wr * 128 + fr) * 528 + (wc * 64 + 4 * fq) * 2;
; #pragma unroll
;         for (int m = 0; m < 8; ++m)
; #pragma unroll
;             for (int n = 0; n < 4; ++n) { u32x2 w; w.x = pk2(acc[m][n][0], acc[m][n][1]); w.y = pk2(acc[m][n][2], acc[m][n][3]); *(u32x2*)(lbase + m * 16 * 528 + n * 32) = w; }
;         __builtin_amdgcn_sched_barrier(0);
	v_mfma_f32_16x16x32_bf16 v[44:47], v[136:139], v[194:197], v[44:47]
	v_mfma_f32_16x16x32_bf16 v[40:43], v[156:159], v[194:197], v[40:43]
	v_mfma_f32_16x16x32_bf16 v[36:39], v[164:167], v[194:197], v[36:39]
	v_mfma_f32_16x16x32_bf16 v[32:35], v[186:189], v[194:197], v[32:35]
	ds_read_b128 v[194:197], v146
	s_waitcnt lgkmcnt(4)
	v_mfma_f32_16x16x32_bf16 v[28:31], v[136:139], v[160:163], v[28:31]
	v_mfma_f32_16x16x32_bf16 v[24:27], v[156:159], v[160:163], v[24:27]
	v_mfma_f32_16x16x32_bf16 v[20:23], v[164:167], v[160:163], v[20:23]
	v_mfma_f32_16x16x32_bf16 v[16:19], v[186:189], v[160:163], v[16:19]
	ds_read_b128 v[160:163], v146 offset:2048
	s_waitcnt lgkmcnt(3)
	v_mfma_f32_16x16x32_bf16 v[8:11], v[156:159], v[190:193], v[8:11]
	v_add_u32_e32 v156, v155, v150
	v_mfma_f32_16x16x32_bf16 v[12:15], v[136:139], v[190:193], v[12:15]
	v_mfma_f32_16x16x32_bf16 v[4:7], v[164:167], v[190:193], v[4:7]
	v_mfma_f32_16x16x32_bf16 v[0:3], v[186:189], v[190:193], v[0:3]
	ds_read_b128 v[136:139], v146 offset:4096
	s_waitcnt lgkmcnt(2)
	v_mfma_f32_16x16x32_bf16 v[124:127], v[198:201], v[194:197], v[124:127]
	v_mfma_f32_16x16x32_bf16 v[120:123], v[202:205], v[194:197], v[120:123]
	v_mfma_f32_16x16x32_bf16 v[116:119], v[206:209], v[194:197], v[116:119]
	v_mfma_f32_16x16x32_bf16 v[112:115], v[210:213], v[194:197], v[112:115]
	ds_read_b128 v[156:159], v156
	s_waitcnt lgkmcnt(2)
	v_mfma_f32_16x16x32_bf16 v[108:111], v[198:201], v[160:163], v[108:111]
	v_mfma_f32_16x16x32_bf16 v[104:107], v[202:205], v[160:163], v[104:107]
	v_mfma_f32_16x16x32_bf16 v[100:103], v[206:209], v[160:163], v[100:103]
	v_mfma_f32_16x16x32_bf16 v[96:99], v[210:213], v[160:163], v[96:99]
	ds_read_b128 v[160:163], v146 offset:8192
	s_waitcnt lgkmcnt(2)
	v_mfma_f32_16x16x32_bf16 v[92:95], v[198:201], v[136:139], v[92:95]
	v_mfma_f32_16x16x32_bf16 v[88:91], v[202:205], v[136:139], v[88:91]
	v_mfma_f32_16x16x32_bf16 v[84:87], v[206:209], v[136:139], v[84:87]
	v_mfma_f32_16x16x32_bf16 v[80:83], v[210:213], v[136:139], v[80:83]
	ds_read_b128 v[136:139], v146 offset:10240
	s_waitcnt lgkmcnt(2)
	v_mfma_f32_16x16x32_bf16 v[76:79], v[198:201], v[156:159], v[76:79]
	v_mfma_f32_16x16x32_bf16 v[72:75], v[202:205], v[156:159], v[72:75]
	v_mfma_f32_16x16x32_bf16 v[68:71], v[206:209], v[156:159], v[68:71]
	v_mfma_f32_16x16x32_bf16 v[64:67], v[210:213], v[156:159], v[64:67]
	ds_read_b128 v[156:159], v146 offset:12288
	v_add_u32_e32 v146, v155, v152
	s_waitcnt lgkmcnt(2)
	v_mfma_f32_16x16x32_bf16 v[60:63], v[198:201], v[160:163], v[60:63]
	v_mfma_f32_16x16x32_bf16 v[56:59], v[202:205], v[160:163], v[56:59]
	v_mfma_f32_16x16x32_bf16 v[52:55], v[206:209], v[160:163], v[52:55]
	v_mfma_f32_16x16x32_bf16 v[48:51], v[210:213], v[160:163], v[48:51]
	ds_read_b128 v[160:163], v146
	s_waitcnt lgkmcnt(2)
	v_mfma_f32_16x16x32_bf16 v[44:47], v[198:201], v[136:139], v[44:47]
	v_mfma_f32_16x16x32_bf16 v[40:43], v[202:205], v[136:139], v[40:43]
	v_mfma_f32_16x16x32_bf16 v[36:39], v[206:209], v[136:139], v[36:39]
	v_mfma_f32_16x16x32_bf16 v[32:35], v[210:213], v[136:139], v[32:35]
	s_waitcnt lgkmcnt(1)
	v_mfma_f32_16x16x32_bf16 v[24:27], v[202:205], v[156:159], v[24:27]
	v_mfma_f32_16x16x32_bf16 v[20:23], v[206:209], v[156:159], v[20:23]
	v_mfma_f32_16x16x32_bf16 v[16:19], v[210:213], v[156:159], v[16:19]
	s_waitcnt lgkmcnt(0)
	v_mfma_f32_16x16x32_bf16 v[12:15], v[198:201], v[160:163], v[12:15]
	v_mfma_f32_16x16x32_bf16 v[8:11], v[202:205], v[160:163], v[8:11]
	v_mfma_f32_16x16x32_bf16 v[4:7], v[206:209], v[160:163], v[4:7]
	v_mfma_f32_16x16x32_bf16 v[0:3], v[210:213], v[160:163], v[0:3]
	v_mfma_f32_16x16x32_bf16 v[28:31], v[198:201], v[156:159], v[28:31]
	v_mov_b32_e32 v136, v141
	v_mov_b32_e32 v137, v140
	s_waitcnt vmcnt(0)
	s_barrier
	v_cvt_pk_bf16_f32 v124, v124, v125
	v_and_or_b32 v138, v136, 15, v143
	v_ashrrev_i32_e32 v139, 1, v136
	v_mul_lo_u32 v138, v138, s3
	v_and_b32_e32 v139, -8, v139
	v_add3_u32 v138, v154, v138, v139
	v_cvt_pk_bf16_f32 v125, v126, v127
	v_cvt_pk_bf16_f32 v120, v120, v121
	v_cvt_pk_bf16_f32 v121, v122, v123
	v_cvt_pk_bf16_f32 v116, v116, v117
	v_cvt_pk_bf16_f32 v117, v118, v119
	v_cvt_pk_bf16_f32 v112, v112, v113
	v_cvt_pk_bf16_f32 v113, v114, v115
	v_cvt_pk_bf16_f32 v108, v108, v109
	v_cvt_pk_bf16_f32 v109, v110, v111
	v_cvt_pk_bf16_f32 v104, v104, v105
	v_cvt_pk_bf16_f32 v105, v106, v107
	v_add_u32_e32 v106, 0x2000, v138
	v_cvt_pk_bf16_f32 v100, v100, v101
	v_cvt_pk_bf16_f32 v101, v102, v103
	v_cvt_pk_bf16_f32 v96, v96, v97
	v_cvt_pk_bf16_f32 v97, v98, v99
	v_cvt_pk_bf16_f32 v92, v92, v93
	v_cvt_pk_bf16_f32 v93, v94, v95
	v_cvt_pk_bf16_f32 v88, v88, v89
	v_cvt_pk_bf16_f32 v89, v90, v91
	v_add_u32_e32 v90, 0x4000, v138
	v_cvt_pk_bf16_f32 v84, v84, v85
	v_cvt_pk_bf16_f32 v85, v86, v87
	v_cvt_pk_bf16_f32 v80, v80, v81
	v_cvt_pk_bf16_f32 v81, v82, v83
	v_cvt_pk_bf16_f32 v76, v76, v77
	v_cvt_pk_bf16_f32 v77, v78, v79
	v_cvt_pk_bf16_f32 v72, v72, v73
	v_cvt_pk_bf16_f32 v73, v74, v75
	v_add_u32_e32 v74, 0x6000, v138
	v_cvt_pk_bf16_f32 v68, v68, v69
	v_cvt_pk_bf16_f32 v69, v70, v71
	v_cvt_pk_bf16_f32 v64, v64, v65
	v_cvt_pk_bf16_f32 v65, v66, v67
	v_cvt_pk_bf16_f32 v60, v60, v61
	v_cvt_pk_bf16_f32 v61, v62, v63
	v_cvt_pk_bf16_f32 v56, v56, v57
	v_cvt_pk_bf16_f32 v57, v58, v59
	v_add_u32_e32 v58, 0x8000, v138
	v_cvt_pk_bf16_f32 v52, v52, v53
	v_cvt_pk_bf16_f32 v53, v54, v55
	v_cvt_pk_bf16_f32 v48, v48, v49
	v_cvt_pk_bf16_f32 v49, v50, v51
	v_cvt_pk_bf16_f32 v44, v44, v45
	v_cvt_pk_bf16_f32 v45, v46, v47
	v_cvt_pk_bf16_f32 v40, v40, v41
	v_cvt_pk_bf16_f32 v41, v42, v43
	v_add_u32_e32 v42, 0xa000, v138
	v_cvt_pk_bf16_f32 v36, v36, v37
	v_cvt_pk_bf16_f32 v37, v38, v39
	v_cvt_pk_bf16_f32 v32, v32, v33
; DI unsigned pk2(float a, float b) { f32x2 v = {a, b}; bf16x2_t r = __builtin_convertvector(v, bf16x2_t); return __builtin_bit_cast(unsigned, r); }
; DI float bflo(unsigned w) { return __uint_as_float(w << 16); }
; DI float bfhi(unsigned w) { return __uint_as_float(w & 0xffff0000u); }
;     DI void operator()(gacc_t& acc, int pm, int pn, char* lds, int tid, int wr, int wc, int lane) const {
;     ...
;             for (int n = 0; n < 4; ++n) { u32x2 w; w.x = pk2(acc[m][n][0], acc[m][n][1]); w.y = pk2(acc[m][n][2], acc[m][n][3]); *(u32x2*)(lbase + m * 16 * 528 + n * 32) = w; }
;         __builtin_amdgcn_sched_barrier(0);
;         __syncthreads();
;         __builtin_amdgcn_sched_barrier(0);
;         const int g = lane >> 5, j32 = lane & 31;
; #pragma unroll
;         for (int ib = 0; ib < 4; ++ib) {
;             __builtin_amdgcn_sched_barrier(0);
;             u32x4 xv[4];
; #pragma unroll
;             for (int u = 0; u < 4; ++u) {
;                 const long row = (long)pm * 256 + (ib * 4 + u) * 16 + wid * 2 + g;
;                 xv[u] = *(const u32x4*)(xold + row * 1024 + pn * 256 + j32 * 8);
;             }
; #pragma unroll
;             for (int u = 0; u < 4; ++u) {
;                 const int rloc = (ib * 4 + u) * 16 + wid * 2 + g;
;                 const long row = (long)pm * 256 + rloc;
;                 const u32x4 a = *(const u32x4*)(lds + rloc * 528 + j32 * 16);
;                 u32x4 w; float ss = 0.f;
; #pragma unroll
;                 for (int e = 0; e < 4; ++e) {
;                     w[e] = pk2(bflo(xv[u][e]) + bflo(a[e]), bfhi(xv[u][e]) + bfhi(a[e]));
;                     const float b0 = bflo(w[e]), b1 = bfhi(w[e]);
;                     ss += b0 * b0 + b1 * b1;
;                 }
;                 *(u32x4*)(xnew + row * 1024 + pn * 256 + j32 * 8) = w;
; #pragma unroll
;                 for (int o = 1; o < 32; o <<= 1) ss += __shfl_xor(ss, o);
;                 if (j32 == 0) ssq[row * 4 + pn] = ss;
	v_cvt_pk_bf16_f32 v33, v34, v35
	v_cvt_pk_bf16_f32 v28, v28, v29
	v_cvt_pk_bf16_f32 v29, v30, v31
	v_cvt_pk_bf16_f32 v24, v24, v25
	v_cvt_pk_bf16_f32 v25, v26, v27
	v_add_u32_e32 v26, 0xc000, v138
	v_cvt_pk_bf16_f32 v20, v20, v21
	v_cvt_pk_bf16_f32 v21, v22, v23
	v_cvt_pk_bf16_f32 v16, v16, v17
	v_cvt_pk_bf16_f32 v17, v18, v19
	v_cvt_pk_bf16_f32 v12, v12, v13
	v_cvt_pk_bf16_f32 v13, v14, v15
	v_cvt_pk_bf16_f32 v8, v8, v9
	v_cvt_pk_bf16_f32 v9, v10, v11
	v_add_u32_e32 v10, 0xe000, v138
	v_cvt_pk_bf16_f32 v4, v4, v5
	v_cvt_pk_bf16_f32 v5, v6, v7
	v_cvt_pk_bf16_f32 v0, v0, v1
	v_cvt_pk_bf16_f32 v1, v2, v3
	ds_write2_b64 v138, v[124:125], v[120:121] offset1:4
	ds_write2_b64 v138, v[116:117], v[112:113] offset0:8 offset1:12
	ds_write2_b64 v106, v[108:109], v[104:105] offset0:32 offset1:36
	ds_write2_b64 v106, v[100:101], v[96:97] offset0:40 offset1:44
	ds_write2_b64 v90, v[92:93], v[88:89] offset0:64 offset1:68
	ds_write2_b64 v90, v[84:85], v[80:81] offset0:72 offset1:76
	ds_write2_b64 v74, v[76:77], v[72:73] offset0:96 offset1:100
	ds_write2_b64 v74, v[68:69], v[64:65] offset0:104 offset1:108
	ds_write2_b64 v58, v[60:61], v[56:57] offset0:128 offset1:132
	ds_write2_b64 v58, v[52:53], v[48:49] offset0:136 offset1:140
	ds_write2_b64 v42, v[44:45], v[40:41] offset0:160 offset1:164
	ds_write2_b64 v42, v[36:37], v[32:33] offset0:168 offset1:172
	ds_write2_b64 v26, v[28:29], v[24:25] offset0:192 offset1:196
	ds_write2_b64 v26, v[20:21], v[16:17] offset0:200 offset1:204
	ds_write2_b64 v10, v[12:13], v[8:9] offset0:224 offset1:228
	ds_write2_b64 v10, v[4:5], v[0:1] offset0:232 offset1:236
	s_waitcnt lgkmcnt(0)
	s_barrier
	v_ashrrev_i32_e32 v0, 5, v136
	v_ashrrev_i32_e32 v1, 5, v137
	v_and_b32_e32 v14, 31, v136
	v_and_b32_e32 v2, -2, v1
	v_ashrrev_i32_e32 v1, 31, v0
	v_ashrrev_i32_e32 v3, 31, v2
	v_lshl_add_u64 v[4:5], s[12:13], 0, v[0:1]
	s_lshl_b32 s16, s6, 8
	v_add_u32_e32 v16, v2, v0
	v_lshlrev_b32_e32 v146, 4, v14
	v_and_b32_e32 v0, 64, v169
	v_lshl_add_u64 v[4:5], v[4:5], 0, v[2:3]
	s_ashr_i32 s17, s16, 31
	v_add_u32_e32 v26, 0, v146
	v_add_u32_e32 v15, 64, v0
	v_cmp_eq_u32_e64 s[4:5], 0, v14
	v_cmp_eq_u32_e64 s[98:99], 16, v14
	s_lshl_b64 s[18:19], s[16:17], 1
	s_add_u32 s22, s10, s18
	s_addc_u32 s23, s11, s19
	v_lshl_add_u64 v[0:1], s[22:23], 0, v[146:147]
	v_lshlrev_b64 v[2:3], 11, v[4:5]
	v_lshl_add_u64 v[18:19], v[0:1], 0, v[2:3]
	flat_load_dwordx4 v[22:25], v[18:19]
	v_add_co_u32_e32 v0, vcc, s49, v18
	v_mul_lo_u32 v20, v16, s3
	s_nop 0
	v_addc_co_u32_e32 v1, vcc, 0, v19, vcc
	flat_load_dwordx4 v[8:11], v[0:1]
	v_add_co_u32_e32 v0, vcc, s48, v18
	v_add_u32_e32 v12, v26, v20
	s_nop 0
	v_addc_co_u32_e32 v1, vcc, 0, v19, vcc
	flat_load_dwordx4 v[4:7], v[0:1]
	v_add_co_u32_e32 v0, vcc, s47, v18
	ds_read_b128 v[28:31], v12
	s_nop 0
	v_addc_co_u32_e32 v1, vcc, 0, v19, vcc
	flat_load_dwordx4 v[0:3], v[0:1]
	v_ashrrev_i32_e32 v17, 31, v16
	s_waitcnt lgkmcnt(0)
	v_lshlrev_b32_e32 v32, 16, v28
	v_and_b32_e32 v33, 0xffff0000, v28
	v_lshlrev_b32_e32 v28, 16, v29
	v_and_b32_e32 v29, 0xffff0000, v29
	s_waitcnt vmcnt(0)
	v_lshlrev_b32_e32 v12, 16, v22
	v_and_b32_e32 v13, 0xffff0000, v22
	v_pk_add_f32 v[12:13], v[12:13], v[32:33]
	s_nop 0
	v_cvt_pk_bf16_f32 v22, v12, v13
	v_and_b32_e32 v13, 0xffff0000, v22
	v_lshlrev_b32_e32 v12, 16, v22
	v_mul_f32_e32 v21, v13, v13
	v_fmac_f32_e32 v21, v12, v12
	v_lshlrev_b32_e32 v12, 16, v23
	v_and_b32_e32 v13, 0xffff0000, v23
	v_pk_add_f32 v[12:13], v[12:13], v[28:29]
	v_lshlrev_b32_e32 v28, 16, v30
	v_cvt_pk_bf16_f32 v23, v12, v13
	v_and_b32_e32 v13, 0xffff0000, v23
	v_lshlrev_b32_e32 v12, 16, v23
	v_mul_f32_e32 v13, v13, v13
	v_fmac_f32_e32 v13, v12, v12
	v_add_f32_e32 v21, v21, v13
	v_lshlrev_b32_e32 v12, 16, v24
	v_and_b32_e32 v13, 0xffff0000, v24
	v_and_b32_e32 v29, 0xffff0000, v30
	v_pk_add_f32 v[12:13], v[12:13], v[28:29]
	v_lshlrev_b32_e32 v28, 16, v31
	v_cvt_pk_bf16_f32 v24, v12, v13
	v_and_b32_e32 v13, 0xffff0000, v24
	v_lshlrev_b32_e32 v12, 16, v24
	v_mul_f32_e32 v13, v13, v13
	v_fmac_f32_e32 v13, v12, v12
	v_add_f32_e32 v21, v13, v21
	v_lshlrev_b32_e32 v12, 16, v25
	v_and_b32_e32 v13, 0xffff0000, v25
	v_and_b32_e32 v29, 0xffff0000, v31
	v_pk_add_f32 v[12:13], v[12:13], v[28:29]
	s_nop 0
	v_cvt_pk_bf16_f32 v25, v12, v13
	v_and_b32_e32 v13, 0xffff0000, v25
	v_lshlrev_b32_e32 v12, 16, v25
	v_mul_f32_e32 v13, v13, v13
	v_fmac_f32_e32 v13, v12, v12
	v_add_f32_e32 v21, v13, v21
	v_lshl_add_u64 v[12:13], s[12:13], 0, v[16:17]
	v_lshlrev_b64 v[28:29], 11, v[12:13]
	v_xor_b32_e32 v17, 1, v169
	v_lshl_add_u64 v[28:29], s[68:69], 0, v[28:29]
	v_cmp_lt_i32_e32 vcc, v17, v15
	v_lshl_add_u64 v[28:29], v[28:29], 0, s[18:19]
	v_lshl_add_u64 v[28:29], v[28:29], 0, v[146:147]
	v_cndmask_b32_e32 v17, v169, v17, vcc
	v_lshlrev_b32_e32 v17, 2, v17
	flat_store_dwordx4 v[28:29], v[22:25]
	s_nop 1
	v_add_f32_dpp v86, v21, v21 quad_perm:[1,0,3,2] row_mask:0xf bank_mask:0xf
	s_nop 1
	v_add_f32_dpp v86, v86, v86 quad_perm:[2,3,0,1] row_mask:0xf bank_mask:0xf
	s_nop 1
	v_add_f32_dpp v86, v86, v86 row_half_mirror row_mask:0xf bank_mask:0xf
	s_nop 1
	v_add_f32_dpp v86, v86, v86 row_mirror row_mask:0xf bank_mask:0xf
	s_nop 1
	v_add_f32_dpp v86, v86, v86 row_bcast:15 row_mask:0xa bank_mask:0xf
	s_waitcnt lgkmcnt(0)
	v_xor_b32_e32 v22, 2, v169
	v_cmp_lt_i32_e32 vcc, v22, v15
	s_nop 1
	v_cndmask_b32_e32 v22, v169, v22, vcc
	v_lshlrev_b32_e32 v22, 2, v22
	s_waitcnt lgkmcnt(0)
	v_xor_b32_e32 v23, 4, v169
	v_cmp_lt_i32_e32 vcc, v23, v15
	s_nop 1
	v_cndmask_b32_e32 v23, v169, v23, vcc
	v_lshlrev_b32_e32 v23, 2, v23
	s_waitcnt lgkmcnt(0)
	v_xor_b32_e32 v24, 8, v169
	v_cmp_lt_i32_e32 vcc, v24, v15
	s_nop 1
	v_cndmask_b32_e32 v24, v169, v24, vcc
	v_lshlrev_b32_e32 v24, 2, v24
	s_waitcnt lgkmcnt(0)
	v_xor_b32_e32 v25, 16, v169
	v_cmp_lt_i32_e32 vcc, v25, v15
	s_nop 1
	v_cndmask_b32_e32 v15, v169, v25, vcc
	v_lshlrev_b32_e32 v25, 2, v15
	s_and_saveexec_b64 s[18:19], s[98:99]
	s_cbranch_execz .LBB0_526
	v_lshl_add_u64 v[12:13], v[12:13], 4, s[78:79]
	v_lshl_add_u64 v[12:13], s[6:7], 2, v[12:13]
	s_waitcnt lgkmcnt(0)
	v_mov_b32_e32 v15, v86
	flat_store_dword v[12:13], v15

; #define MFMA16(a, b, c) __builtin_amdgcn_mfma_f32_16x16x32_bf16((a), (b), (c), 0, 0, 0)
; DI bf16x8 ldfrag(const char* lds, int row, int chunk) { return *(const bf16x8*)(lds + swz(row, chunk)); }
; #define GEMM_SG1() do { __builtin_amdgcn_sched_group_barrier(0x100, 1, 0); __builtin_amdgcn_sched_group_barrier(0x008, 4, 0); } while (0)
; #define GEMM_SG2() do { __builtin_amdgcn_sched_group_barrier(0x100, 2, 0); __builtin_amdgcn_sched_group_barrier(0x008, 4, 0); } while (0)
; template <bool RSTD, bool SWAP>
; DI void gemm_tile(gacc_t& acc, const bf16_t* __restrict__ A, int lda, const bf16_t* __restrict__ Bt, int ldb, int K,
;                   char* lds, int tid, int wr, int wc, int lane, const float* ssq_row) {
;     ...
;     for (int kt = 0; kt < nk; ++kt) {
;         const char* cur = lds + (kt & 1) * 65536;
;         if (kt + 1 < nk) GEMM_ISSUE(kt + 1, (kt + 1) & 1);
;         bf16x8 bfr[2][4], afr[3];
; #pragma unroll
;         for (int n = 0; n < 4; ++n) bfr[0][n] = ldfrag(cur + 32768, wc * 64 + n * 16 + fr, fq);
;         afr[0] = ldfrag(cur, wr * 128 + fr, fq);
;         afr[1] = ldfrag(cur, wr * 128 + 16 + fr, fq);
; #pragma unroll
;         for (int idx = 0; idx < 16; ++idx) {
;             const int ks = idx >> 3, m = idx & 7;
;             if (idx < 14) afr[(idx + 2) % 3] = ldfrag(cur, wr * 128 + ((idx + 2) & 7) * 16 + fr, ((idx + 2) >> 3) * 4 + fq);
;             if (ks == 0 && m >= 2 && m < 6) bfr[1][m - 2] = ldfrag(cur + 32768, wc * 64 + (m - 2) * 16 + fr, 4 + fq);
; #pragma unroll
;             for (int n = 0; n < 4; ++n) acc[m][n] = SWAP ? MFMA16(bfr[ks][n], afr[idx % 3], acc[m][n]) : MFMA16(afr[idx % 3], bfr[ks][n], acc[m][n]);
;         }
;         __builtin_amdgcn_sched_group_barrier(0x100, 6, 0);
;     ...
;         GEMM_SG1(); GEMM_SG1(); GEMM_SG2(); GEMM_SG2(); GEMM_SG2(); GEMM_SG2(); GEMM_SG1(); GEMM_SG1();
;         GEMM_SG1(); GEMM_SG1(); GEMM_SG1(); GEMM_SG1(); GEMM_SG1(); GEMM_SG1();
;         __builtin_amdgcn_sched_group_barrier(0x008, 8, 0);
;         __builtin_amdgcn_sched_barrier(0);
;         asm volatile("s_waitcnt vmcnt(0)" ::: "memory");
;         __syncthreads();
;     }
.LBB0_618:
	s_add_i32 s45, s44, 0xffff0000
	s_and_b32 s45, s45, 0x10000
	s_add_i32 s45, s45, 0
	v_add_u32_e32 v146, s45, v144
	v_add3_u32 v161, v146, v150, v151
	v_add_u32_e32 v166, v146, v148
	ds_read_b128 v[162:165], v161 offset:32768
	ds_read_b128 v[172:175], v161 offset:34816
	ds_read_b128 v[180:183], v161 offset:36864
	ds_read_b128 v[186:189], v161 offset:38912
	ds_read_b128 v[176:179], v166
	ds_read_b128 v[190:193], v166 offset:2048
	v_add_u32_e32 v161, v146, v152
	ds_read_b128 v[194:197], v166 offset:4096
	v_lshl_add_u64 v[240:241], v[140:141], 0, s[12:13]
	v_lshl_add_u64 v[242:243], v[138:139], 0, s[12:13]
	s_and_b32 s48, s44, 0x10000
	s_add_i32 s48, s43, s48
	s_mov_b64 s[46:47], 0x2ee40080
	v_lshl_add_u64 v[232:233], v[240:241], 0, s[46:47]
	s_mov_b32 m0, s48
	v_mfma_f32_16x16x32_bf16 v[60:63], v[198:201], v[214:217], v[60:63]
	global_load_lds_dwordx4 v[232:233], off
	v_mfma_f32_16x16x32_bf16 v[56:59], v[202:205], v[214:217], v[56:59]
	s_mov_b64 s[46:47], 0x1c80080
	v_lshl_add_u64 v[234:235], v[242:243], 0, s[46:47]
	s_add_i32 m0, s48, 0x8000
	v_mfma_f32_16x16x32_bf16 v[52:55], v[206:209], v[214:217], v[52:55]
	global_load_lds_dwordx4 v[234:235], off
	v_mfma_f32_16x16x32_bf16 v[48:51], v[210:213], v[214:217], v[48:51]
	s_mov_b64 s[46:47], 0x2ee60080
	v_lshl_add_u64 v[232:233], v[240:241], 0, s[46:47]
	s_add_i32 m0, s48, 0x2000
	v_mfma_f32_16x16x32_bf16 v[44:47], v[198:201], v[218:221], v[44:47]
	global_load_lds_dwordx4 v[232:233], off
	v_mfma_f32_16x16x32_bf16 v[40:43], v[202:205], v[218:221], v[40:43]
	s_mov_b64 s[46:47], 0x1ca0080
	v_lshl_add_u64 v[234:235], v[242:243], 0, s[46:47]
	s_add_i32 m0, s48, 0xa000
	v_mfma_f32_16x16x32_bf16 v[36:39], v[206:209], v[218:221], v[36:39]
	global_load_lds_dwordx4 v[234:235], off
	v_mfma_f32_16x16x32_bf16 v[32:35], v[210:213], v[218:221], v[32:35]
	s_mov_b64 s[46:47], 0x2ee80080
	v_lshl_add_u64 v[232:233], v[240:241], 0, s[46:47]
	s_add_i32 m0, s48, 0x4000
	v_mfma_f32_16x16x32_bf16 v[28:31], v[198:201], v[222:225], v[28:31]
	global_load_lds_dwordx4 v[232:233], off
	v_mfma_f32_16x16x32_bf16 v[24:27], v[202:205], v[222:225], v[24:27]
	s_mov_b64 s[46:47], 0x1cc0080
	v_lshl_add_u64 v[234:235], v[242:243], 0, s[46:47]
	s_add_i32 m0, s48, 0xc000
	v_mfma_f32_16x16x32_bf16 v[20:23], v[206:209], v[222:225], v[20:23]
	global_load_lds_dwordx4 v[234:235], off
	v_mfma_f32_16x16x32_bf16 v[16:19], v[210:213], v[222:225], v[16:19]
	s_mov_b64 s[46:47], 0x2eea0080
	v_lshl_add_u64 v[232:233], v[240:241], 0, s[46:47]
	s_add_i32 m0, s48, 0x6000
	v_mfma_f32_16x16x32_bf16 v[12:15], v[198:201], v[236:239], v[12:15]
	global_load_lds_dwordx4 v[232:233], off
	v_mfma_f32_16x16x32_bf16 v[8:11], v[202:205], v[236:239], v[8:11]
	s_mov_b64 s[46:47], 0x1ce0080
	v_lshl_add_u64 v[234:235], v[242:243], 0, s[46:47]
	s_add_i32 m0, s48, 0xe000
	v_mfma_f32_16x16x32_bf16 v[4:7], v[206:209], v[236:239], v[4:7]
	global_load_lds_dwordx4 v[234:235], off
	v_mfma_f32_16x16x32_bf16 v[0:3], v[210:213], v[236:239], v[0:3]
	s_waitcnt lgkmcnt(2)
	v_mfma_f32_16x16x32_bf16 v[124:127], v[162:165], v[176:179], v[124:127]
	v_add_u32_e32 v146, v146, v154
	v_mfma_f32_16x16x32_bf16 v[120:123], v[172:175], v[176:179], v[120:123]
	v_mfma_f32_16x16x32_bf16 v[116:119], v[180:183], v[176:179], v[116:119]
	v_mfma_f32_16x16x32_bf16 v[112:115], v[186:189], v[176:179], v[112:115]
	ds_read_b128 v[176:179], v161
	v_add_u32_e32 v161, s45, v149
	v_add_u32_e32 v167, v161, v153
	s_waitcnt lgkmcnt(2)
	v_mfma_f32_16x16x32_bf16 v[108:111], v[162:165], v[190:193], v[108:111]
	v_mfma_f32_16x16x32_bf16 v[104:107], v[172:175], v[190:193], v[104:107]
	v_mfma_f32_16x16x32_bf16 v[100:103], v[180:183], v[190:193], v[100:103]
	v_mfma_f32_16x16x32_bf16 v[96:99], v[186:189], v[190:193], v[96:99]
	ds_read_b128 v[190:193], v166 offset:8192
	ds_read_b128 v[198:201], v167 offset:32768
	s_waitcnt lgkmcnt(3)
	v_mfma_f32_16x16x32_bf16 v[92:95], v[162:165], v[194:197], v[92:95]
	v_mfma_f32_16x16x32_bf16 v[88:91], v[172:175], v[194:197], v[88:91]
	v_mfma_f32_16x16x32_bf16 v[84:87], v[180:183], v[194:197], v[84:87]
	v_mfma_f32_16x16x32_bf16 v[80:83], v[186:189], v[194:197], v[80:83]
	ds_read_b128 v[194:197], v166 offset:10240
	ds_read_b128 v[202:205], v167 offset:34816
	s_waitcnt lgkmcnt(4)
	v_mfma_f32_16x16x32_bf16 v[76:79], v[162:165], v[176:179], v[76:79]
	v_mfma_f32_16x16x32_bf16 v[72:75], v[172:175], v[176:179], v[72:75]
	v_mfma_f32_16x16x32_bf16 v[68:71], v[180:183], v[176:179], v[68:71]
	v_mfma_f32_16x16x32_bf16 v[64:67], v[186:189], v[176:179], v[64:67]
	ds_read_b128 v[176:179], v166 offset:12288
	v_add_u32_e32 v166, v161, v155
	ds_read_b128 v[206:209], v167 offset:36864
	s_waitcnt lgkmcnt(5)
	v_mfma_f32_16x16x32_bf16 v[60:63], v[162:165], v[190:193], v[60:63]
	v_mfma_f32_16x16x32_bf16 v[56:59], v[172:175], v[190:193], v[56:59]
	v_mfma_f32_16x16x32_bf16 v[52:55], v[180:183], v[190:193], v[52:55]
	v_mfma_f32_16x16x32_bf16 v[48:51], v[186:189], v[190:193], v[48:51]
	ds_read_b128 v[210:213], v166 offset:38912
	ds_read_b128 v[190:193], v146
	v_add_u32_e32 v146, v161, v148
	s_waitcnt lgkmcnt(5)
	v_mfma_f32_16x16x32_bf16 v[44:47], v[162:165], v[194:197], v[44:47]
	v_add_u32_e32 v166, v161, v152
	v_mfma_f32_16x16x32_bf16 v[40:43], v[172:175], v[194:197], v[40:43]
	v_mfma_f32_16x16x32_bf16 v[36:39], v[180:183], v[194:197], v[36:39]
	v_mfma_f32_16x16x32_bf16 v[32:35], v[186:189], v[194:197], v[32:35]
	ds_read_b128 v[194:197], v146
	v_add_u32_e32 v230, v161, v154
	s_waitcnt lgkmcnt(4)
	v_mfma_f32_16x16x32_bf16 v[28:31], v[162:165], v[176:179], v[28:31]
	v_mfma_f32_16x16x32_bf16 v[24:27], v[172:175], v[176:179], v[24:27]
	v_mfma_f32_16x16x32_bf16 v[20:23], v[180:183], v[176:179], v[20:23]
	v_mfma_f32_16x16x32_bf16 v[16:19], v[186:189], v[176:179], v[16:19]
	ds_read_b128 v[176:179], v146 offset:2048
	s_waitcnt lgkmcnt(2)
; #define MFMA16(a, b, c) __builtin_amdgcn_mfma_f32_16x16x32_bf16((a), (b), (c), 0, 0, 0)
; DI bf16x8 ldfrag(const char* lds, int row, int chunk) { return *(const bf16x8*)(lds + swz(row, chunk)); }
; #define GEMM_SG1() do { __builtin_amdgcn_sched_group_barrier(0x100, 1, 0); __builtin_amdgcn_sched_group_barrier(0x008, 4, 0); } while (0)
; #define GEMM_SG2() do { __builtin_amdgcn_sched_group_barrier(0x100, 2, 0); __builtin_amdgcn_sched_group_barrier(0x008, 4, 0); } while (0)
; template <bool RSTD, bool SWAP>
; DI void gemm_tile(gacc_t& acc, const bf16_t* __restrict__ A, int lda, const bf16_t* __restrict__ Bt, int ldb, int K,
;                   char* lds, int tid, int wr, int wc, int lane, const float* ssq_row) {
;     ...
;         for (int idx = 0; idx < 16; ++idx) {
;             const int ks = idx >> 3, m = idx & 7;
;             if (idx < 14) afr[(idx + 2) % 3] = ldfrag(cur, wr * 128 + ((idx + 2) & 7) * 16 + fr, ((idx + 2) >> 3) * 4 + fq);
;             if (ks == 0 && m >= 2 && m < 6) bfr[1][m - 2] = ldfrag(cur + 32768, wc * 64 + (m - 2) * 16 + fr, 4 + fq);
; #pragma unroll
;             for (int n = 0; n < 4; ++n) acc[m][n] = SWAP ? MFMA16(bfr[ks][n], afr[idx % 3], acc[m][n]) : MFMA16(afr[idx % 3], bfr[ks][n], acc[m][n]);
;         }
;         __builtin_amdgcn_sched_group_barrier(0x100, 6, 0);
;     ...
;         GEMM_SG1(); GEMM_SG1(); GEMM_SG2(); GEMM_SG2(); GEMM_SG2(); GEMM_SG2(); GEMM_SG1(); GEMM_SG1();
;         GEMM_SG1(); GEMM_SG1(); GEMM_SG1(); GEMM_SG1(); GEMM_SG1(); GEMM_SG1();
;         __builtin_amdgcn_sched_group_barrier(0x008, 8, 0);
;         __builtin_amdgcn_sched_barrier(0);
;         asm volatile("s_waitcnt vmcnt(0)" ::: "memory");
;         __syncthreads();
;     }
	v_mfma_f32_16x16x32_bf16 v[12:15], v[162:165], v[190:193], v[12:15]
	v_mfma_f32_16x16x32_bf16 v[8:11], v[172:175], v[190:193], v[8:11]
	v_mfma_f32_16x16x32_bf16 v[4:7], v[180:183], v[190:193], v[4:7]
	v_mfma_f32_16x16x32_bf16 v[0:3], v[186:189], v[190:193], v[0:3]
	ds_read_b128 v[162:165], v146 offset:4096
	s_waitcnt lgkmcnt(2)
	v_mfma_f32_16x16x32_bf16 v[124:127], v[198:201], v[194:197], v[124:127]
	v_mfma_f32_16x16x32_bf16 v[120:123], v[202:205], v[194:197], v[120:123]
	v_mfma_f32_16x16x32_bf16 v[116:119], v[206:209], v[194:197], v[116:119]
	v_mfma_f32_16x16x32_bf16 v[112:115], v[210:213], v[194:197], v[112:115]
	ds_read_b128 v[172:175], v166
	ds_read_b128 v[214:217], v146 offset:8192
	s_waitcnt lgkmcnt(3)
	v_mfma_f32_16x16x32_bf16 v[108:111], v[198:201], v[176:179], v[108:111]
	v_mfma_f32_16x16x32_bf16 v[104:107], v[202:205], v[176:179], v[104:107]
	v_mfma_f32_16x16x32_bf16 v[100:103], v[206:209], v[176:179], v[100:103]
	v_mfma_f32_16x16x32_bf16 v[96:99], v[210:213], v[176:179], v[96:99]
	ds_read_b128 v[218:221], v146 offset:10240
	s_waitcnt lgkmcnt(3)
	v_mfma_f32_16x16x32_bf16 v[92:95], v[198:201], v[162:165], v[92:95]
	v_mfma_f32_16x16x32_bf16 v[88:91], v[202:205], v[162:165], v[88:91]
	v_mfma_f32_16x16x32_bf16 v[84:87], v[206:209], v[162:165], v[84:87]
	v_mfma_f32_16x16x32_bf16 v[80:83], v[210:213], v[162:165], v[80:83]
	ds_read_b128 v[222:225], v146 offset:12288
	ds_read_b128 v[236:239], v230
	s_waitcnt lgkmcnt(4)
	v_mfma_f32_16x16x32_bf16 v[76:79], v[198:201], v[172:175], v[76:79]
	v_mfma_f32_16x16x32_bf16 v[72:75], v[202:205], v[172:175], v[72:75]
	v_mfma_f32_16x16x32_bf16 v[68:71], v[206:209], v[172:175], v[68:71]
	v_mfma_f32_16x16x32_bf16 v[64:67], v[210:213], v[172:175], v[64:67]
	s_waitcnt lgkmcnt(0)
	s_waitcnt vmcnt(0)
	s_add_u32 s12, s12, 0x80
	s_addc_u32 s13, s13, 0
	s_add_i32 s44, s44, 0x10000
	s_cmpk_lg_i32 s12, 0x780
	s_waitcnt vmcnt(0)
	s_cbranch_scc1 .Lkhead_618
	s_barrier
	v_mfma_f32_16x16x32_bf16 v[60:63], v[198:201], v[214:217], v[60:63]
	v_mfma_f32_16x16x32_bf16 v[56:59], v[202:205], v[214:217], v[56:59]
	v_mfma_f32_16x16x32_bf16 v[52:55], v[206:209], v[214:217], v[52:55]
	v_mfma_f32_16x16x32_bf16 v[48:51], v[210:213], v[214:217], v[48:51]
	v_mfma_f32_16x16x32_bf16 v[44:47], v[198:201], v[218:221], v[44:47]
	v_mfma_f32_16x16x32_bf16 v[40:43], v[202:205], v[218:221], v[40:43]
	v_mfma_f32_16x16x32_bf16 v[36:39], v[206:209], v[218:221], v[36:39]
	v_mfma_f32_16x16x32_bf16 v[32:35], v[210:213], v[218:221], v[32:35]
	v_mfma_f32_16x16x32_bf16 v[28:31], v[198:201], v[222:225], v[28:31]
	v_mfma_f32_16x16x32_bf16 v[24:27], v[202:205], v[222:225], v[24:27]
	v_mfma_f32_16x16x32_bf16 v[20:23], v[206:209], v[222:225], v[20:23]
	v_mfma_f32_16x16x32_bf16 v[16:19], v[210:213], v[222:225], v[16:19]
	v_mfma_f32_16x16x32_bf16 v[12:15], v[198:201], v[236:239], v[12:15]
	v_mfma_f32_16x16x32_bf16 v[8:11], v[202:205], v[236:239], v[8:11]
	v_mfma_f32_16x16x32_bf16 v[4:7], v[206:209], v[236:239], v[4:7]
	v_mfma_f32_16x16x32_bf16 v[0:3], v[210:213], v[236:239], v[0:3]
	ds_read_b128 v[138:141], v160
	ds_read_b128 v[162:165], v160 offset:2048
	ds_read_b128 v[176:179], v160 offset:4096
	ds_read_b128 v[180:183], v160 offset:6144
	v_add_u32_e32 v146, v156, v148
	ds_read_b128 v[172:175], v146
	ds_read_b128 v[186:189], v146 offset:2048
	v_add_u32_e32 v161, v156, v152
	ds_read_b128 v[190:193], v146 offset:4096
	s_waitcnt lgkmcnt(2)
	v_mfma_f32_16x16x32_bf16 v[124:127], v[138:141], v[172:175], v[124:127]
	v_mfma_f32_16x16x32_bf16 v[120:123], v[162:165], v[172:175], v[120:123]
	v_mfma_f32_16x16x32_bf16 v[116:119], v[176:179], v[172:175], v[116:119]
	v_mfma_f32_16x16x32_bf16 v[112:115], v[180:183], v[172:175], v[112:115]
	ds_read_b128 v[172:175], v161
	v_add_u32_e32 v161, v157, v153
	s_waitcnt lgkmcnt(2)
	v_mfma_f32_16x16x32_bf16 v[108:111], v[138:141], v[186:189], v[108:111]
	v_mfma_f32_16x16x32_bf16 v[104:107], v[162:165], v[186:189], v[104:107]
	v_mfma_f32_16x16x32_bf16 v[100:103], v[176:179], v[186:189], v[100:103]
	v_mfma_f32_16x16x32_bf16 v[96:99], v[180:183], v[186:189], v[96:99]
	ds_read_b128 v[186:189], v146 offset:8192
	ds_read_b128 v[194:197], v161
	s_waitcnt lgkmcnt(3)
	v_mfma_f32_16x16x32_bf16 v[92:95], v[138:141], v[190:193], v[92:95]
	v_mfma_f32_16x16x32_bf16 v[88:91], v[162:165], v[190:193], v[88:91]
	v_mfma_f32_16x16x32_bf16 v[84:87], v[176:179], v[190:193], v[84:87]
	v_mfma_f32_16x16x32_bf16 v[80:83], v[180:183], v[190:193], v[80:83]
	ds_read_b128 v[190:193], v146 offset:10240
	ds_read_b128 v[198:201], v161 offset:2048
	s_waitcnt lgkmcnt(4)
	v_mfma_f32_16x16x32_bf16 v[76:79], v[138:141], v[172:175], v[76:79]
	v_mfma_f32_16x16x32_bf16 v[72:75], v[162:165], v[172:175], v[72:75]
	v_mfma_f32_16x16x32_bf16 v[68:71], v[176:179], v[172:175], v[68:71]
	v_mfma_f32_16x16x32_bf16 v[64:67], v[180:183], v[172:175], v[64:67]
	ds_read_b128 v[172:175], v146 offset:12288
	v_add_u32_e32 v146, v156, v154
	ds_read_b128 v[202:205], v161 offset:4096
	s_waitcnt lgkmcnt(5)
	v_mfma_f32_16x16x32_bf16 v[60:63], v[138:141], v[186:189], v[60:63]
	v_mfma_f32_16x16x32_bf16 v[56:59], v[162:165], v[186:189], v[56:59]
	v_mfma_f32_16x16x32_bf16 v[52:55], v[176:179], v[186:189], v[52:55]
	v_mfma_f32_16x16x32_bf16 v[48:51], v[180:183], v[186:189], v[48:51]
	ds_read_b128 v[186:189], v146
	v_add_u32_e32 v146, v157, v155
	ds_read_b128 v[206:209], v146 offset:6144
	v_add_u32_e32 v146, v158, v148
	s_waitcnt lgkmcnt(5)
; #define MFMA16(a, b, c) __builtin_amdgcn_mfma_f32_16x16x32_bf16((a), (b), (c), 0, 0, 0)
; DI unsigned pk2(float a, float b) { f32x2 v = {a, b}; bf16x2_t r = __builtin_convertvector(v, bf16x2_t); return __builtin_bit_cast(unsigned, r); }
; template <bool RSTD, bool SWAP>
; DI void gemm_tile(gacc_t& acc, const bf16_t* __restrict__ A, int lda, const bf16_t* __restrict__ Bt, int ldb, int K,
;                   char* lds, int tid, int wr, int wc, int lane, const float* ssq_row) {
;     ...
;         for (int idx = 0; idx < 16; ++idx) {
;             const int ks = idx >> 3, m = idx & 7;
;             if (idx < 14) afr[(idx + 2) % 3] = ldfrag(cur, wr * 128 + ((idx + 2) & 7) * 16 + fr, ((idx + 2) >> 3) * 4 + fq);
;             if (ks == 0 && m >= 2 && m < 6) bfr[1][m - 2] = ldfrag(cur + 32768, wc * 64 + (m - 2) * 16 + fr, 4 + fq);
; #pragma unroll
;             for (int n = 0; n < 4; ++n) acc[m][n] = SWAP ? MFMA16(bfr[ks][n], afr[idx % 3], acc[m][n]) : MFMA16(afr[idx % 3], bfr[ks][n], acc[m][n]);
;         }
;         __builtin_amdgcn_sched_group_barrier(0x100, 6, 0);
;     ...
;         GEMM_SG1(); GEMM_SG1(); GEMM_SG2(); GEMM_SG2(); GEMM_SG2(); GEMM_SG2(); GEMM_SG1(); GEMM_SG1();
;         GEMM_SG1(); GEMM_SG1(); GEMM_SG1(); GEMM_SG1(); GEMM_SG1(); GEMM_SG1();
;         __builtin_amdgcn_sched_group_barrier(0x008, 8, 0);
;         __builtin_amdgcn_sched_barrier(0);
;         asm volatile("s_waitcnt vmcnt(0)" ::: "memory");
;         __syncthreads();
;     DI void operator()(gacc_t& acc, int pm, int pn, char* lds, int tid, int wr, int wc, int lane) const {
;     ...
;         const float* rl = (const float*)(lds + RSTD_OFF) + wr * 128 + fr;
;         {
;             char* lbase = lds + (wr * 128 + fr) * RS + (wc * 64 + 4 * fq) * 2;
;             bf16_t* hrow = halo + (long)(pm * 4) * 5632 + pn * 256 + wc * 64 + 4 * fq;
; #pragma unroll
;             for (int m = 0; m < 8; ++m) {
;                 const float r = rl[m * 16];
; #pragma unroll
;                 for (int n = 0; n < 4; ++n) {
;                     u32x2 w; w.x = pk2(acc[m][n][0] * r, acc[m][n][1] * r); w.y = pk2(acc[m][n][2] * r, acc[m][n][3] * r);
;                     *(u32x2*)(lbase + m * 16 * RS + n * 32) = w;
;                     if (m == 0 && wr == 0 && fr < 2) *(u32x2*)(hrow + fr * 5632 + n * 16) = w;
;                     if (m == 7 && wr == 1 && fr >= 14) *(u32x2*)(hrow + (fr - 12) * 5632 + n * 16) = w;
	v_mfma_f32_16x16x32_bf16 v[44:47], v[138:141], v[190:193], v[44:47]
	v_mfma_f32_16x16x32_bf16 v[40:43], v[162:165], v[190:193], v[40:43]
	v_mfma_f32_16x16x32_bf16 v[36:39], v[176:179], v[190:193], v[36:39]
	v_mfma_f32_16x16x32_bf16 v[32:35], v[180:183], v[190:193], v[32:35]
	ds_read_b128 v[190:193], v146
	s_waitcnt lgkmcnt(4)
	v_mfma_f32_16x16x32_bf16 v[28:31], v[138:141], v[172:175], v[28:31]
	v_mfma_f32_16x16x32_bf16 v[24:27], v[162:165], v[172:175], v[24:27]
	v_mfma_f32_16x16x32_bf16 v[20:23], v[176:179], v[172:175], v[20:23]
	v_mfma_f32_16x16x32_bf16 v[16:19], v[180:183], v[172:175], v[16:19]
	ds_read_b128 v[172:175], v146 offset:2048
	s_waitcnt lgkmcnt(3)
	v_mfma_f32_16x16x32_bf16 v[12:15], v[138:141], v[186:189], v[12:15]
	v_mfma_f32_16x16x32_bf16 v[8:11], v[162:165], v[186:189], v[8:11]
	v_mfma_f32_16x16x32_bf16 v[4:7], v[176:179], v[186:189], v[4:7]
	v_mfma_f32_16x16x32_bf16 v[138:141], v[180:183], v[186:189], v[0:3]
	s_nop 2
	ds_read_b128 v[0:3], v146 offset:4096
	s_waitcnt lgkmcnt(2)
	v_mfma_f32_16x16x32_bf16 v[164:167], v[194:197], v[190:193], v[124:127]
	v_mfma_f32_16x16x32_bf16 v[120:123], v[198:201], v[190:193], v[120:123]
	s_nop 1
	v_add_u32_e32 v124, v158, v152
	v_mfma_f32_16x16x32_bf16 v[116:119], v[202:205], v[190:193], v[116:119]
	v_mfma_f32_16x16x32_bf16 v[112:115], v[206:209], v[190:193], v[112:115]
	ds_read_b128 v[124:127], v124
	s_waitcnt lgkmcnt(2)
	v_mfma_f32_16x16x32_bf16 v[108:111], v[194:197], v[172:175], v[108:111]
	v_mfma_f32_16x16x32_bf16 v[104:107], v[198:201], v[172:175], v[104:107]
	v_mfma_f32_16x16x32_bf16 v[100:103], v[202:205], v[172:175], v[100:103]
	v_mfma_f32_16x16x32_bf16 v[96:99], v[206:209], v[172:175], v[96:99]
	ds_read_b128 v[172:175], v146 offset:8192
	s_waitcnt lgkmcnt(2)
	v_mfma_f32_16x16x32_bf16 v[92:95], v[194:197], v[0:3], v[92:95]
	v_mfma_f32_16x16x32_bf16 v[88:91], v[198:201], v[0:3], v[88:91]
	v_mfma_f32_16x16x32_bf16 v[84:87], v[202:205], v[0:3], v[84:87]
	v_mfma_f32_16x16x32_bf16 v[80:83], v[206:209], v[0:3], v[80:83]
	ds_read_b128 v[0:3], v146 offset:10240
	s_waitcnt lgkmcnt(2)
	v_mfma_f32_16x16x32_bf16 v[76:79], v[194:197], v[124:127], v[76:79]
	v_mfma_f32_16x16x32_bf16 v[72:75], v[198:201], v[124:127], v[72:75]
	v_mfma_f32_16x16x32_bf16 v[68:71], v[202:205], v[124:127], v[68:71]
	v_mfma_f32_16x16x32_bf16 v[64:67], v[206:209], v[124:127], v[64:67]
	ds_read_b128 v[124:127], v146 offset:12288
	v_add_u32_e32 v146, v158, v154
	s_waitcnt lgkmcnt(2)
	v_mfma_f32_16x16x32_bf16 v[60:63], v[194:197], v[172:175], v[60:63]
	v_mfma_f32_16x16x32_bf16 v[56:59], v[198:201], v[172:175], v[56:59]
	v_mfma_f32_16x16x32_bf16 v[52:55], v[202:205], v[172:175], v[52:55]
	v_mfma_f32_16x16x32_bf16 v[48:51], v[206:209], v[172:175], v[48:51]
	ds_read_b128 v[172:175], v146
	s_waitcnt lgkmcnt(2)
	v_mfma_f32_16x16x32_bf16 v[44:47], v[194:197], v[0:3], v[44:47]
	v_mfma_f32_16x16x32_bf16 v[40:43], v[198:201], v[0:3], v[40:43]
	v_mfma_f32_16x16x32_bf16 v[36:39], v[202:205], v[0:3], v[36:39]
	v_mfma_f32_16x16x32_bf16 v[32:35], v[206:209], v[0:3], v[32:35]
	s_waitcnt lgkmcnt(1)
	v_mfma_f32_16x16x32_bf16 v[28:31], v[194:197], v[124:127], v[28:31]
	v_mfma_f32_16x16x32_bf16 v[24:27], v[198:201], v[124:127], v[24:27]
	v_mfma_f32_16x16x32_bf16 v[20:23], v[202:205], v[124:127], v[20:23]
	v_mfma_f32_16x16x32_bf16 v[16:19], v[206:209], v[124:127], v[16:19]
	s_waitcnt lgkmcnt(0)
	v_mfma_f32_16x16x32_bf16 v[12:15], v[194:197], v[172:175], v[12:15]
	v_mfma_f32_16x16x32_bf16 v[8:11], v[198:201], v[172:175], v[8:11]
	v_mfma_f32_16x16x32_bf16 v[0:3], v[202:205], v[172:175], v[4:7]
	v_mfma_f32_16x16x32_bf16 v[4:7], v[206:209], v[172:175], v[138:141]
	s_lshl_b32 s12, s42, 2
	s_mul_i32 s13, s42, 0xb000
	s_mul_hi_i32 s12, s12, 0x2c00
	s_add_u32 s43, s22, s13
	v_mov_b32_e32 v124, v142
	v_mov_b32_e32 v140, v133
	s_addc_u32 s44, s23, s12
	s_lshl_b32 s12, s40, 8
	s_waitcnt vmcnt(0)
	s_barrier
	s_ashr_i32 s13, s12, 31
	v_and_b32_e32 v162, 15, v124
	v_or_b32_e32 v125, v162, v145
	v_ashrrev_i32_e32 v124, 2, v124
	s_lshl_b64 s[12:13], s[12:13], 1
	v_mul_lo_u32 v125, v125, s3
	v_and_b32_e32 v124, -4, v124
	s_add_u32 s12, s43, s12
	v_add_u32_e32 v125, 0, v125
	v_add_lshl_u32 v126, v124, v132, 1
	s_addc_u32 s13, s44, s13
	v_lshlrev_b32_e32 v146, 1, v132
	v_lshl_add_u32 v161, v162, 2, v159
	v_add_u32_e32 v141, v125, v126
	v_lshl_add_u64 v[126:127], s[12:13], 0, v[146:147]
	v_ashrrev_i32_e32 v125, 31, v124
	v_lshl_add_u64 v[124:125], v[124:125], 1, v[126:127]
	ds_read_b32 v126, v161
	v_mul_u32_u24_e32 v127, 0x1600, v162
	v_cmp_gt_u32_e32 vcc, 2, v162
	v_lshlrev_b32_e32 v146, 1, v127
	v_lshl_add_u64 v[124:125], v[124:125], 0, v[146:147]
	s_waitcnt lgkmcnt(0)
	v_pk_mul_f32 v[138:139], v[164:165], v[126:127] op_sel_hi:[1,0]
	v_pk_mul_f32 v[164:165], v[166:167], v[126:127] op_sel_hi:[1,0]
	s_and_b64 s[12:13], s[8:9], vcc
	v_cvt_pk_bf16_f32 v138, v138, v139
	v_cvt_pk_bf16_f32 v139, v164, v165
	ds_write_b64 v141, v[138:139]
	s_and_saveexec_b64 s[44:45], s[12:13]
	s_cbranch_execz .LBB0_621
	flat_store_dwordx2 v[124:125], v[138:139]

; #define MFMA16(a, b, c) __builtin_amdgcn_mfma_f32_16x16x32_bf16((a), (b), (c), 0, 0, 0)
; DI bf16x8 ldfrag(const char* lds, int row, int chunk) { return *(const bf16x8*)(lds + swz(row, chunk)); }
; #define GEMM_SG1() do { __builtin_amdgcn_sched_group_barrier(0x100, 1, 0); __builtin_amdgcn_sched_group_barrier(0x008, 4, 0); } while (0)
; #define GEMM_SG2() do { __builtin_amdgcn_sched_group_barrier(0x100, 2, 0); __builtin_amdgcn_sched_group_barrier(0x008, 4, 0); } while (0)
; template <bool RSTD, bool SWAP>
; DI void gemm_tile(gacc_t& acc, const bf16_t* __restrict__ A, int lda, const bf16_t* __restrict__ Bt, int ldb, int K,
;                   char* lds, int tid, int wr, int wc, int lane, const float* ssq_row) {
;     ...
;     for (int kt = 0; kt < nk; ++kt) {
;         const char* cur = lds + (kt & 1) * 65536;
;         if (kt + 1 < nk) GEMM_ISSUE(kt + 1, (kt + 1) & 1);
;         bf16x8 bfr[2][4], afr[3];
; #pragma unroll
;         for (int n = 0; n < 4; ++n) bfr[0][n] = ldfrag(cur + 32768, wc * 64 + n * 16 + fr, fq);
;         afr[0] = ldfrag(cur, wr * 128 + fr, fq);
;         afr[1] = ldfrag(cur, wr * 128 + 16 + fr, fq);
; #pragma unroll
;         for (int idx = 0; idx < 16; ++idx) {
;             const int ks = idx >> 3, m = idx & 7;
;             if (idx < 14) afr[(idx + 2) % 3] = ldfrag(cur, wr * 128 + ((idx + 2) & 7) * 16 + fr, ((idx + 2) >> 3) * 4 + fq);
;             if (ks == 0 && m >= 2 && m < 6) bfr[1][m - 2] = ldfrag(cur + 32768, wc * 64 + (m - 2) * 16 + fr, 4 + fq);
; #pragma unroll
;             for (int n = 0; n < 4; ++n) acc[m][n] = SWAP ? MFMA16(bfr[ks][n], afr[idx % 3], acc[m][n]) : MFMA16(afr[idx % 3], bfr[ks][n], acc[m][n]);
;         }
;         __builtin_amdgcn_sched_group_barrier(0x100, 6, 0);
;     ...
;         GEMM_SG1(); GEMM_SG1(); GEMM_SG2(); GEMM_SG2(); GEMM_SG2(); GEMM_SG2(); GEMM_SG1(); GEMM_SG1();
;         GEMM_SG1(); GEMM_SG1(); GEMM_SG1(); GEMM_SG1(); GEMM_SG1(); GEMM_SG1();
;         __builtin_amdgcn_sched_group_barrier(0x008, 8, 0);
;         __builtin_amdgcn_sched_barrier(0);
;         asm volatile("s_waitcnt vmcnt(0)" ::: "memory");
;         __syncthreads();
;     }
.LBB0_775:
	s_add_i32 s16, s13, 0xffff0000
	v_lshl_add_u64 v[156:157], v[138:139], 0, s[4:5]
	s_and_b32 s18, s13, 0x10000
	s_and_b32 s21, s16, 0x10000
	s_mov_b64 s[16:17], 0x10080080
	v_lshl_add_u64 v[158:159], v[136:137], 0, s[4:5]
	v_lshl_add_u64 v[160:161], v[156:157], 0, s[16:17]
	s_add_i32 s16, s18, 0
	s_mov_b64 s[18:19], 0x4880080
	v_lshl_add_u64 v[162:163], v[158:159], 0, s[18:19]
	s_mov_b64 s[18:19], 0x100d8080
	v_lshl_add_u64 v[164:165], v[156:157], 0, s[18:19]
	s_mov_b64 s[18:19], 0x48d8080
	v_lshl_add_u64 v[166:167], v[158:159], 0, s[18:19]
	s_mov_b64 s[18:19], 0x10130080
	v_lshl_add_u64 v[172:173], v[156:157], 0, s[18:19]
	s_mov_b64 s[18:19], 0x4930080
	v_lshl_add_u64 v[174:175], v[158:159], 0, s[18:19]
	s_mov_b64 s[18:19], 0x10188080
	v_lshl_add_u64 v[156:157], v[156:157], 0, s[18:19]
	s_mov_b64 s[18:19], 0x4988080
	v_lshl_add_u64 v[158:159], v[158:159], 0, s[18:19]
	s_add_i32 s18, s16, s12
	s_add_i32 s19, s18, 0x8000
	s_mov_b32 m0, s18
	s_add_i32 s17, s21, 0
	global_load_lds_dwordx4 v[160:161], off
	v_mfma_f32_16x16x32_bf16 v[60:63], v[190:193], v[236:239], v[60:63]
	s_mov_b32 m0, s19
	v_add_u32_e32 v146, s17, v142
	global_load_lds_dwordx4 v[162:163], off
	v_mfma_f32_16x16x32_bf16 v[56:59], v[194:197], v[236:239], v[56:59]
	s_add_i32 m0, s18, 0x2000
	v_add3_u32 v155, v146, v148, v149
	global_load_lds_dwordx4 v[164:165], off
	v_mfma_f32_16x16x32_bf16 v[52:55], v[198:201], v[236:239], v[52:55]
	s_add_i32 m0, s18, 0xa000
	v_add_u32_e32 v185, v146, v144
	global_load_lds_dwordx4 v[166:167], off
	v_mfma_f32_16x16x32_bf16 v[48:51], v[202:205], v[236:239], v[48:51]
	s_add_i32 m0, s18, 0x4000
	s_nop 0
	global_load_lds_dwordx4 v[172:173], off
	v_mfma_f32_16x16x32_bf16 v[44:47], v[190:193], v[240:243], v[44:47]
	s_add_i32 m0, s18, 0xc000
	s_nop 0
	global_load_lds_dwordx4 v[174:175], off
	v_mfma_f32_16x16x32_bf16 v[40:43], v[194:197], v[240:243], v[40:43]
	s_add_i32 m0, s18, 0x6000
	s_nop 0
	global_load_lds_dwordx4 v[156:157], off
	v_mfma_f32_16x16x32_bf16 v[36:39], v[198:201], v[240:243], v[36:39]
	s_add_i32 m0, s18, 0xe000
	s_nop 0
	global_load_lds_dwordx4 v[158:159], off
	v_mfma_f32_16x16x32_bf16 v[32:35], v[202:205], v[240:243], v[32:35]
	ds_read_b128 v[156:159], v155 offset:32768
	ds_read_b128 v[160:163], v155 offset:34816
	ds_read_b128 v[172:175], v155 offset:36864
	ds_read_b128 v[176:179], v155 offset:38912
	ds_read_b128 v[164:167], v185
	ds_read_b128 v[180:183], v185 offset:2048
	v_add_u32_e32 v155, v146, v150
	ds_read_b128 v[186:189], v185 offset:4096
	v_mfma_f32_16x16x32_bf16 v[28:31], v[190:193], v[244:247], v[28:31]
	v_mfma_f32_16x16x32_bf16 v[24:27], v[194:197], v[244:247], v[24:27]
	v_mfma_f32_16x16x32_bf16 v[20:23], v[198:201], v[244:247], v[20:23]
	v_mfma_f32_16x16x32_bf16 v[16:19], v[202:205], v[244:247], v[16:19]
	v_mfma_f32_16x16x32_bf16 v[12:15], v[190:193], v[248:251], v[12:15]
	v_mfma_f32_16x16x32_bf16 v[8:11], v[194:197], v[248:251], v[8:11]
	v_mfma_f32_16x16x32_bf16 v[4:7], v[198:201], v[248:251], v[4:7]
	v_mfma_f32_16x16x32_bf16 v[0:3], v[202:205], v[248:251], v[0:3]
	s_waitcnt lgkmcnt(2)
	v_mfma_f32_16x16x32_bf16 v[124:127], v[156:159], v[164:167], v[124:127]
	v_add_u32_e32 v146, v146, v152
	v_mfma_f32_16x16x32_bf16 v[120:123], v[160:163], v[164:167], v[120:123]
	v_mfma_f32_16x16x32_bf16 v[116:119], v[172:175], v[164:167], v[116:119]
	v_mfma_f32_16x16x32_bf16 v[112:115], v[176:179], v[164:167], v[112:115]
	ds_read_b128 v[164:167], v155
	v_add_u32_e32 v155, s17, v145
	v_add_u32_e32 v198, v155, v151
	s_waitcnt lgkmcnt(2)
	v_mfma_f32_16x16x32_bf16 v[108:111], v[156:159], v[180:183], v[108:111]
	v_mfma_f32_16x16x32_bf16 v[104:107], v[160:163], v[180:183], v[104:107]
	v_mfma_f32_16x16x32_bf16 v[100:103], v[172:175], v[180:183], v[100:103]
	v_mfma_f32_16x16x32_bf16 v[96:99], v[176:179], v[180:183], v[96:99]
	ds_read_b128 v[180:183], v185 offset:8192
	ds_read_b128 v[190:193], v198 offset:32768
	s_waitcnt lgkmcnt(3)
	v_mfma_f32_16x16x32_bf16 v[92:95], v[156:159], v[186:189], v[92:95]
	v_mfma_f32_16x16x32_bf16 v[88:91], v[160:163], v[186:189], v[88:91]
	v_mfma_f32_16x16x32_bf16 v[84:87], v[172:175], v[186:189], v[84:87]
	v_mfma_f32_16x16x32_bf16 v[80:83], v[176:179], v[186:189], v[80:83]
	ds_read_b128 v[186:189], v185 offset:10240
	ds_read_b128 v[194:197], v198 offset:34816
	s_waitcnt lgkmcnt(4)
	v_mfma_f32_16x16x32_bf16 v[76:79], v[156:159], v[164:167], v[76:79]
	v_mfma_f32_16x16x32_bf16 v[72:75], v[160:163], v[164:167], v[72:75]
	v_mfma_f32_16x16x32_bf16 v[68:71], v[172:175], v[164:167], v[68:71]
	v_mfma_f32_16x16x32_bf16 v[64:67], v[176:179], v[164:167], v[64:67]
	ds_read_b128 v[164:167], v185 offset:12288
	v_add_u32_e32 v185, v155, v153
	ds_read_b128 v[198:201], v198 offset:36864
	s_waitcnt lgkmcnt(5)
	v_mfma_f32_16x16x32_bf16 v[60:63], v[156:159], v[180:183], v[60:63]
	v_mfma_f32_16x16x32_bf16 v[56:59], v[160:163], v[180:183], v[56:59]
	v_mfma_f32_16x16x32_bf16 v[52:55], v[172:175], v[180:183], v[52:55]
	v_mfma_f32_16x16x32_bf16 v[48:51], v[176:179], v[180:183], v[48:51]
	ds_read_b128 v[202:205], v185 offset:38912
	ds_read_b128 v[180:183], v146
	v_add_u32_e32 v146, v155, v144
	s_waitcnt lgkmcnt(5)
	v_mfma_f32_16x16x32_bf16 v[44:47], v[156:159], v[186:189], v[44:47]
	v_mfma_f32_16x16x32_bf16 v[40:43], v[160:163], v[186:189], v[40:43]
	v_mfma_f32_16x16x32_bf16 v[36:39], v[172:175], v[186:189], v[36:39]
	v_mfma_f32_16x16x32_bf16 v[32:35], v[176:179], v[186:189], v[32:35]
	ds_read_b128 v[186:189], v146
	s_waitcnt lgkmcnt(4)
	v_mfma_f32_16x16x32_bf16 v[28:31], v[156:159], v[164:167], v[28:31]
	v_mfma_f32_16x16x32_bf16 v[24:27], v[160:163], v[164:167], v[24:27]
	v_mfma_f32_16x16x32_bf16 v[20:23], v[172:175], v[164:167], v[20:23]
	v_mfma_f32_16x16x32_bf16 v[16:19], v[176:179], v[164:167], v[16:19]
	ds_read_b128 v[164:167], v146 offset:2048
	s_waitcnt lgkmcnt(2)
; #define MFMA16(a, b, c) __builtin_amdgcn_mfma_f32_16x16x32_bf16((a), (b), (c), 0, 0, 0)
; DI bf16x8 ldfrag(const char* lds, int row, int chunk) { return *(const bf16x8*)(lds + swz(row, chunk)); }
; #define GEMM_SG1() do { __builtin_amdgcn_sched_group_barrier(0x100, 1, 0); __builtin_amdgcn_sched_group_barrier(0x008, 4, 0); } while (0)
; #define GEMM_SG2() do { __builtin_amdgcn_sched_group_barrier(0x100, 2, 0); __builtin_amdgcn_sched_group_barrier(0x008, 4, 0); } while (0)
; template <bool RSTD, bool SWAP>
; DI void gemm_tile(gacc_t& acc, const bf16_t* __restrict__ A, int lda, const bf16_t* __restrict__ Bt, int ldb, int K,
;                   char* lds, int tid, int wr, int wc, int lane, const float* ssq_row) {
;     ...
;         for (int idx = 0; idx < 16; ++idx) {
;             const int ks = idx >> 3, m = idx & 7;
;             if (idx < 14) afr[(idx + 2) % 3] = ldfrag(cur, wr * 128 + ((idx + 2) & 7) * 16 + fr, ((idx + 2) >> 3) * 4 + fq);
;             if (ks == 0 && m >= 2 && m < 6) bfr[1][m - 2] = ldfrag(cur + 32768, wc * 64 + (m - 2) * 16 + fr, 4 + fq);
; #pragma unroll
;             for (int n = 0; n < 4; ++n) acc[m][n] = SWAP ? MFMA16(bfr[ks][n], afr[idx % 3], acc[m][n]) : MFMA16(afr[idx % 3], bfr[ks][n], acc[m][n]);
;         }
;         __builtin_amdgcn_sched_group_barrier(0x100, 6, 0);
;     ...
;         GEMM_SG1(); GEMM_SG1(); GEMM_SG2(); GEMM_SG2(); GEMM_SG2(); GEMM_SG2(); GEMM_SG1(); GEMM_SG1();
;         GEMM_SG1(); GEMM_SG1(); GEMM_SG1(); GEMM_SG1(); GEMM_SG1(); GEMM_SG1();
;         __builtin_amdgcn_sched_group_barrier(0x008, 8, 0);
;         __builtin_amdgcn_sched_barrier(0);
;         asm volatile("s_waitcnt vmcnt(0)" ::: "memory");
;         __syncthreads();
;     }
	v_mfma_f32_16x16x32_bf16 v[8:11], v[160:163], v[180:183], v[8:11]
	v_add_u32_e32 v160, v155, v150
	v_mfma_f32_16x16x32_bf16 v[12:15], v[156:159], v[180:183], v[12:15]
	v_mfma_f32_16x16x32_bf16 v[4:7], v[172:175], v[180:183], v[4:7]
	v_mfma_f32_16x16x32_bf16 v[0:3], v[176:179], v[180:183], v[0:3]
	ds_read_b128 v[156:159], v146 offset:4096
	s_waitcnt lgkmcnt(2)
	v_mfma_f32_16x16x32_bf16 v[124:127], v[190:193], v[186:189], v[124:127]
	v_mfma_f32_16x16x32_bf16 v[120:123], v[194:197], v[186:189], v[120:123]
	v_mfma_f32_16x16x32_bf16 v[116:119], v[198:201], v[186:189], v[116:119]
	v_mfma_f32_16x16x32_bf16 v[112:115], v[202:205], v[186:189], v[112:115]
	ds_read_b128 v[160:163], v160
	s_waitcnt lgkmcnt(2)
	v_mfma_f32_16x16x32_bf16 v[108:111], v[190:193], v[164:167], v[108:111]
	v_mfma_f32_16x16x32_bf16 v[104:107], v[194:197], v[164:167], v[104:107]
	v_mfma_f32_16x16x32_bf16 v[100:103], v[198:201], v[164:167], v[100:103]
	v_mfma_f32_16x16x32_bf16 v[96:99], v[202:205], v[164:167], v[96:99]
	ds_read_b128 v[236:239], v146 offset:8192
	s_waitcnt lgkmcnt(2)
	v_mfma_f32_16x16x32_bf16 v[92:95], v[190:193], v[156:159], v[92:95]
	v_mfma_f32_16x16x32_bf16 v[88:91], v[194:197], v[156:159], v[88:91]
	v_mfma_f32_16x16x32_bf16 v[84:87], v[198:201], v[156:159], v[84:87]
	v_mfma_f32_16x16x32_bf16 v[80:83], v[202:205], v[156:159], v[80:83]
	ds_read_b128 v[240:243], v146 offset:10240
	ds_read_b128 v[244:247], v146 offset:12288
	v_add_u32_e32 v146, v155, v152
	ds_read_b128 v[248:251], v146
	s_waitcnt lgkmcnt(4)
	v_mfma_f32_16x16x32_bf16 v[76:79], v[190:193], v[160:163], v[76:79]
	v_mfma_f32_16x16x32_bf16 v[72:75], v[194:197], v[160:163], v[72:75]
	v_mfma_f32_16x16x32_bf16 v[68:71], v[198:201], v[160:163], v[68:71]
	v_mfma_f32_16x16x32_bf16 v[64:67], v[202:205], v[160:163], v[64:67]
	s_waitcnt lgkmcnt(0)
	s_waitcnt vmcnt(0)
	s_add_u32 s4, s4, 0x80
	s_addc_u32 s5, s5, 0
	s_add_i32 s13, s13, 0x10000
	s_cmpk_eq_i32 s4, 0x1580
	s_waitcnt vmcnt(0)
	s_cbranch_scc0 .Lkhead_775
	s_barrier
	v_mfma_f32_16x16x32_bf16 v[60:63], v[190:193], v[236:239], v[60:63]
	v_mfma_f32_16x16x32_bf16 v[56:59], v[194:197], v[236:239], v[56:59]
	v_mfma_f32_16x16x32_bf16 v[52:55], v[198:201], v[236:239], v[52:55]
	v_mfma_f32_16x16x32_bf16 v[48:51], v[202:205], v[236:239], v[48:51]
	v_mfma_f32_16x16x32_bf16 v[44:47], v[190:193], v[240:243], v[44:47]
	v_mfma_f32_16x16x32_bf16 v[40:43], v[194:197], v[240:243], v[40:43]
	v_mfma_f32_16x16x32_bf16 v[36:39], v[198:201], v[240:243], v[36:39]
	v_mfma_f32_16x16x32_bf16 v[32:35], v[202:205], v[240:243], v[32:35]
	v_mfma_f32_16x16x32_bf16 v[28:31], v[190:193], v[244:247], v[28:31]
	v_mfma_f32_16x16x32_bf16 v[24:27], v[194:197], v[244:247], v[24:27]
	v_mfma_f32_16x16x32_bf16 v[20:23], v[198:201], v[244:247], v[20:23]
	v_mfma_f32_16x16x32_bf16 v[16:19], v[202:205], v[244:247], v[16:19]
	v_mfma_f32_16x16x32_bf16 v[12:15], v[190:193], v[248:251], v[12:15]
	v_mfma_f32_16x16x32_bf16 v[8:11], v[194:197], v[248:251], v[8:11]
	v_mfma_f32_16x16x32_bf16 v[4:7], v[198:201], v[248:251], v[4:7]
	v_mfma_f32_16x16x32_bf16 v[0:3], v[202:205], v[248:251], v[0:3]
	v_add_u32_e32 v146, s16, v142
	v_add3_u32 v155, v146, v148, v149
	ds_read_b128 v[136:139], v155 offset:32768
	ds_read_b128 v[156:159], v155 offset:34816
	ds_read_b128 v[164:167], v155 offset:36864
	ds_read_b128 v[172:175], v155 offset:38912
	v_add_u32_e32 v185, v146, v144
	ds_read_b128 v[160:163], v185
	ds_read_b128 v[176:179], v185 offset:2048
	v_add_u32_e32 v155, v146, v150
	ds_read_b128 v[180:183], v185 offset:4096
	s_waitcnt lgkmcnt(2)
	v_mfma_f32_16x16x32_bf16 v[124:127], v[136:139], v[160:163], v[124:127]
	v_add_u32_e32 v146, v146, v152
	s_lshl_b64 s[12:13], s[8:9], 8
	v_mfma_f32_16x16x32_bf16 v[120:123], v[156:159], v[160:163], v[120:123]
	v_mfma_f32_16x16x32_bf16 v[116:119], v[164:167], v[160:163], v[116:119]
	v_mfma_f32_16x16x32_bf16 v[112:115], v[172:175], v[160:163], v[112:115]
	ds_read_b128 v[160:163], v155
	v_add_u32_e32 v155, s16, v145
	v_add_u32_e32 v194, v155, v151
	s_waitcnt lgkmcnt(2)
	v_mfma_f32_16x16x32_bf16 v[108:111], v[136:139], v[176:179], v[108:111]
	v_mfma_f32_16x16x32_bf16 v[104:107], v[156:159], v[176:179], v[104:107]
	v_mfma_f32_16x16x32_bf16 v[100:103], v[164:167], v[176:179], v[100:103]
	v_mfma_f32_16x16x32_bf16 v[96:99], v[172:175], v[176:179], v[96:99]
	ds_read_b128 v[176:179], v185 offset:8192
	ds_read_b128 v[186:189], v194 offset:32768
	s_waitcnt lgkmcnt(3)
	v_mfma_f32_16x16x32_bf16 v[92:95], v[136:139], v[180:183], v[92:95]
	v_mfma_f32_16x16x32_bf16 v[88:91], v[156:159], v[180:183], v[88:91]
	v_mfma_f32_16x16x32_bf16 v[84:87], v[164:167], v[180:183], v[84:87]
	v_mfma_f32_16x16x32_bf16 v[80:83], v[172:175], v[180:183], v[80:83]
	ds_read_b128 v[180:183], v185 offset:10240
	ds_read_b128 v[190:193], v194 offset:34816
	s_waitcnt lgkmcnt(4)
	v_mfma_f32_16x16x32_bf16 v[76:79], v[136:139], v[160:163], v[76:79]
	v_mfma_f32_16x16x32_bf16 v[72:75], v[156:159], v[160:163], v[72:75]
	v_mfma_f32_16x16x32_bf16 v[68:71], v[164:167], v[160:163], v[68:71]
	v_mfma_f32_16x16x32_bf16 v[64:67], v[172:175], v[160:163], v[64:67]
	ds_read_b128 v[160:163], v185 offset:12288
	ds_read_b128 v[194:197], v194 offset:36864
	s_waitcnt lgkmcnt(5)
	v_mfma_f32_16x16x32_bf16 v[60:63], v[136:139], v[176:179], v[60:63]
	v_mfma_f32_16x16x32_bf16 v[56:59], v[156:159], v[176:179], v[56:59]
	v_mfma_f32_16x16x32_bf16 v[52:55], v[164:167], v[176:179], v[52:55]
	v_mfma_f32_16x16x32_bf16 v[48:51], v[172:175], v[176:179], v[48:51]
	ds_read_b128 v[176:179], v146
	v_add_u32_e32 v146, v155, v153
	ds_read_b128 v[198:201], v146 offset:38912
	v_add_u32_e32 v146, v155, v144
	s_waitcnt lgkmcnt(5)
; #define MFMA16(a, b, c) __builtin_amdgcn_mfma_f32_16x16x32_bf16((a), (b), (c), 0, 0, 0)
; DI unsigned pk2(float a, float b) { f32x2 v = {a, b}; bf16x2_t r = __builtin_convertvector(v, bf16x2_t); return __builtin_bit_cast(unsigned, r); }
; DI bf16x8 ldfrag(const char* lds, int row, int chunk) { return *(const bf16x8*)(lds + swz(row, chunk)); }
; #define GEMM_SG1() do { __builtin_amdgcn_sched_group_barrier(0x100, 1, 0); __builtin_amdgcn_sched_group_barrier(0x008, 4, 0); } while (0)
; template <bool RSTD, bool SWAP>
; DI void gemm_tile(gacc_t& acc, const bf16_t* __restrict__ A, int lda, const bf16_t* __restrict__ Bt, int ldb, int K,
;                   char* lds, int tid, int wr, int wc, int lane, const float* ssq_row) {
;     ...
;         for (int idx = 0; idx < 16; ++idx) {
;             const int ks = idx >> 3, m = idx & 7;
;             if (idx < 14) afr[(idx + 2) % 3] = ldfrag(cur, wr * 128 + ((idx + 2) & 7) * 16 + fr, ((idx + 2) >> 3) * 4 + fq);
;             if (ks == 0 && m >= 2 && m < 6) bfr[1][m - 2] = ldfrag(cur + 32768, wc * 64 + (m - 2) * 16 + fr, 4 + fq);
; #pragma unroll
;             for (int n = 0; n < 4; ++n) acc[m][n] = SWAP ? MFMA16(bfr[ks][n], afr[idx % 3], acc[m][n]) : MFMA16(afr[idx % 3], bfr[ks][n], acc[m][n]);
;         }
;         __builtin_amdgcn_sched_group_barrier(0x100, 6, 0);
;     ...
;         GEMM_SG1(); GEMM_SG1(); GEMM_SG2(); GEMM_SG2(); GEMM_SG2(); GEMM_SG2(); GEMM_SG1(); GEMM_SG1();
;         GEMM_SG1(); GEMM_SG1(); GEMM_SG1(); GEMM_SG1(); GEMM_SG1(); GEMM_SG1();
;         __builtin_amdgcn_sched_group_barrier(0x008, 8, 0);
;         __builtin_amdgcn_sched_barrier(0);
;         asm volatile("s_waitcnt vmcnt(0)" ::: "memory");
;         __syncthreads();
;     DI void operator()(gacc_t& acc, int pm, int pn, char* lds, int tid, int wr, int wc, int lane) const {
;         asm volatile("" : "+v"(tid), "+v"(lane));
;         const int fr = lane & 15, fq = lane >> 4, wid = tid >> 6;
;         char* lbase = lds + (wr * 128 + fr) * 528 + (wc * 64 + 4 * fq) * 2;
; #pragma unroll
;         for (int m = 0; m < 8; ++m)
; #pragma unroll
;             for (int n = 0; n < 4; ++n) { u32x2 w; w.x = pk2(acc[m][n][0], acc[m][n][1]); w.y = pk2(acc[m][n][2], acc[m][n][3]); *(u32x2*)(lbase + m * 16 * 528 + n * 32) = w; }
;         __builtin_amdgcn_sched_barrier(0);
;         __syncthreads();
	v_mfma_f32_16x16x32_bf16 v[44:47], v[136:139], v[180:183], v[44:47]
	v_mfma_f32_16x16x32_bf16 v[40:43], v[156:159], v[180:183], v[40:43]
	v_mfma_f32_16x16x32_bf16 v[36:39], v[164:167], v[180:183], v[36:39]
	v_mfma_f32_16x16x32_bf16 v[32:35], v[172:175], v[180:183], v[32:35]
	ds_read_b128 v[180:183], v146
	s_waitcnt lgkmcnt(4)
	v_mfma_f32_16x16x32_bf16 v[28:31], v[136:139], v[160:163], v[28:31]
	v_mfma_f32_16x16x32_bf16 v[24:27], v[156:159], v[160:163], v[24:27]
	v_mfma_f32_16x16x32_bf16 v[20:23], v[164:167], v[160:163], v[20:23]
	v_mfma_f32_16x16x32_bf16 v[16:19], v[172:175], v[160:163], v[16:19]
	ds_read_b128 v[160:163], v146 offset:2048
	s_waitcnt lgkmcnt(3)
	v_mfma_f32_16x16x32_bf16 v[8:11], v[156:159], v[176:179], v[8:11]
	v_add_u32_e32 v156, v155, v150
	v_mfma_f32_16x16x32_bf16 v[12:15], v[136:139], v[176:179], v[12:15]
	v_mfma_f32_16x16x32_bf16 v[4:7], v[164:167], v[176:179], v[4:7]
	v_mfma_f32_16x16x32_bf16 v[0:3], v[172:175], v[176:179], v[0:3]
	ds_read_b128 v[136:139], v146 offset:4096
	s_waitcnt lgkmcnt(2)
	v_mfma_f32_16x16x32_bf16 v[124:127], v[186:189], v[180:183], v[124:127]
	v_mfma_f32_16x16x32_bf16 v[120:123], v[190:193], v[180:183], v[120:123]
	v_mfma_f32_16x16x32_bf16 v[116:119], v[194:197], v[180:183], v[116:119]
	v_mfma_f32_16x16x32_bf16 v[112:115], v[198:201], v[180:183], v[112:115]
	ds_read_b128 v[156:159], v156
	s_waitcnt lgkmcnt(2)
	v_mfma_f32_16x16x32_bf16 v[108:111], v[186:189], v[160:163], v[108:111]
	v_mfma_f32_16x16x32_bf16 v[104:107], v[190:193], v[160:163], v[104:107]
	v_mfma_f32_16x16x32_bf16 v[100:103], v[194:197], v[160:163], v[100:103]
	v_mfma_f32_16x16x32_bf16 v[96:99], v[198:201], v[160:163], v[96:99]
	ds_read_b128 v[160:163], v146 offset:8192
	s_waitcnt lgkmcnt(2)
	v_mfma_f32_16x16x32_bf16 v[92:95], v[186:189], v[136:139], v[92:95]
	v_mfma_f32_16x16x32_bf16 v[88:91], v[190:193], v[136:139], v[88:91]
	v_mfma_f32_16x16x32_bf16 v[84:87], v[194:197], v[136:139], v[84:87]
	v_mfma_f32_16x16x32_bf16 v[80:83], v[198:201], v[136:139], v[80:83]
	ds_read_b128 v[136:139], v146 offset:10240
	s_waitcnt lgkmcnt(2)
	v_mfma_f32_16x16x32_bf16 v[76:79], v[186:189], v[156:159], v[76:79]
	v_mfma_f32_16x16x32_bf16 v[72:75], v[190:193], v[156:159], v[72:75]
	v_mfma_f32_16x16x32_bf16 v[68:71], v[194:197], v[156:159], v[68:71]
	v_mfma_f32_16x16x32_bf16 v[64:67], v[198:201], v[156:159], v[64:67]
	ds_read_b128 v[156:159], v146 offset:12288
	v_add_u32_e32 v146, v155, v152
	s_waitcnt lgkmcnt(2)
	v_mfma_f32_16x16x32_bf16 v[60:63], v[186:189], v[160:163], v[60:63]
	v_mfma_f32_16x16x32_bf16 v[56:59], v[190:193], v[160:163], v[56:59]
	v_mfma_f32_16x16x32_bf16 v[52:55], v[194:197], v[160:163], v[52:55]
	v_mfma_f32_16x16x32_bf16 v[48:51], v[198:201], v[160:163], v[48:51]
	ds_read_b128 v[160:163], v146
	s_waitcnt lgkmcnt(2)
	v_mfma_f32_16x16x32_bf16 v[44:47], v[186:189], v[136:139], v[44:47]
	v_mfma_f32_16x16x32_bf16 v[40:43], v[190:193], v[136:139], v[40:43]
	v_mfma_f32_16x16x32_bf16 v[36:39], v[194:197], v[136:139], v[36:39]
	v_mfma_f32_16x16x32_bf16 v[32:35], v[198:201], v[136:139], v[32:35]
	s_waitcnt lgkmcnt(1)
	v_mfma_f32_16x16x32_bf16 v[24:27], v[190:193], v[156:159], v[24:27]
	v_mfma_f32_16x16x32_bf16 v[20:23], v[194:197], v[156:159], v[20:23]
	v_mfma_f32_16x16x32_bf16 v[16:19], v[198:201], v[156:159], v[16:19]
	s_waitcnt lgkmcnt(0)
	v_mfma_f32_16x16x32_bf16 v[12:15], v[186:189], v[160:163], v[12:15]
	v_mfma_f32_16x16x32_bf16 v[8:11], v[190:193], v[160:163], v[8:11]
	v_mfma_f32_16x16x32_bf16 v[4:7], v[194:197], v[160:163], v[4:7]
	v_mfma_f32_16x16x32_bf16 v[0:3], v[198:201], v[160:163], v[0:3]
	v_mfma_f32_16x16x32_bf16 v[28:31], v[186:189], v[156:159], v[28:31]
	v_mov_b32_e32 v136, v140
	v_mov_b32_e32 v137, v141
	s_waitcnt vmcnt(0)
	s_barrier
	v_cvt_pk_bf16_f32 v124, v124, v125
	v_and_or_b32 v138, v137, 15, v143
	v_ashrrev_i32_e32 v139, 1, v137
	v_mul_lo_u32 v138, v138, s3
	v_and_b32_e32 v139, -8, v139
	v_add3_u32 v138, v154, v138, v139
	v_cvt_pk_bf16_f32 v125, v126, v127
	v_cvt_pk_bf16_f32 v120, v120, v121
	v_cvt_pk_bf16_f32 v121, v122, v123
	v_cvt_pk_bf16_f32 v116, v116, v117
	v_cvt_pk_bf16_f32 v117, v118, v119
	v_cvt_pk_bf16_f32 v112, v112, v113
	v_cvt_pk_bf16_f32 v113, v114, v115
	v_cvt_pk_bf16_f32 v108, v108, v109
	v_cvt_pk_bf16_f32 v109, v110, v111
	v_cvt_pk_bf16_f32 v104, v104, v105
	v_cvt_pk_bf16_f32 v105, v106, v107
	v_add_u32_e32 v106, 0x2000, v138
	v_cvt_pk_bf16_f32 v100, v100, v101
	v_cvt_pk_bf16_f32 v101, v102, v103
	v_cvt_pk_bf16_f32 v96, v96, v97
	v_cvt_pk_bf16_f32 v97, v98, v99
	v_cvt_pk_bf16_f32 v92, v92, v93
	v_cvt_pk_bf16_f32 v93, v94, v95
	v_cvt_pk_bf16_f32 v88, v88, v89
	v_cvt_pk_bf16_f32 v89, v90, v91
	v_add_u32_e32 v90, 0x4000, v138
	v_cvt_pk_bf16_f32 v84, v84, v85
	v_cvt_pk_bf16_f32 v85, v86, v87
	v_cvt_pk_bf16_f32 v80, v80, v81
	v_cvt_pk_bf16_f32 v81, v82, v83
	v_cvt_pk_bf16_f32 v76, v76, v77
	v_cvt_pk_bf16_f32 v77, v78, v79
	v_cvt_pk_bf16_f32 v72, v72, v73
	v_cvt_pk_bf16_f32 v73, v74, v75
	v_add_u32_e32 v74, 0x6000, v138
	v_cvt_pk_bf16_f32 v68, v68, v69
	v_cvt_pk_bf16_f32 v69, v70, v71
	v_cvt_pk_bf16_f32 v64, v64, v65
	v_cvt_pk_bf16_f32 v65, v66, v67
	v_cvt_pk_bf16_f32 v60, v60, v61
	v_cvt_pk_bf16_f32 v61, v62, v63
	v_cvt_pk_bf16_f32 v56, v56, v57
	v_cvt_pk_bf16_f32 v57, v58, v59
	v_add_u32_e32 v58, 0x8000, v138
	v_cvt_pk_bf16_f32 v52, v52, v53
	v_cvt_pk_bf16_f32 v53, v54, v55
	v_cvt_pk_bf16_f32 v48, v48, v49
	v_cvt_pk_bf16_f32 v49, v50, v51
	v_cvt_pk_bf16_f32 v44, v44, v45
	v_cvt_pk_bf16_f32 v45, v46, v47
	v_cvt_pk_bf16_f32 v40, v40, v41
	v_cvt_pk_bf16_f32 v41, v42, v43
	v_add_u32_e32 v42, 0xa000, v138
	v_cvt_pk_bf16_f32 v36, v36, v37
	v_cvt_pk_bf16_f32 v37, v38, v39
	v_cvt_pk_bf16_f32 v32, v32, v33
; DI unsigned pk2(float a, float b) { f32x2 v = {a, b}; bf16x2_t r = __builtin_convertvector(v, bf16x2_t); return __builtin_bit_cast(unsigned, r); }
; DI float bflo(unsigned w) { return __uint_as_float(w << 16); }
; DI float bfhi(unsigned w) { return __uint_as_float(w & 0xffff0000u); }
;     DI void operator()(gacc_t& acc, int pm, int pn, char* lds, int tid, int wr, int wc, int lane) const {
;     ...
;         char* lbase = lds + (wr * 128 + fr) * 528 + (wc * 64 + 4 * fq) * 2;
; #pragma unroll
;         for (int m = 0; m < 8; ++m)
; #pragma unroll
;             for (int n = 0; n < 4; ++n) { u32x2 w; w.x = pk2(acc[m][n][0], acc[m][n][1]); w.y = pk2(acc[m][n][2], acc[m][n][3]); *(u32x2*)(lbase + m * 16 * 528 + n * 32) = w; }
;         __builtin_amdgcn_sched_barrier(0);
;         __syncthreads();
;         __builtin_amdgcn_sched_barrier(0);
;         const int g = lane >> 5, j32 = lane & 31;
; #pragma unroll
;         for (int ib = 0; ib < 4; ++ib) {
;             __builtin_amdgcn_sched_barrier(0);
;             u32x4 xv[4];
; #pragma unroll
;             for (int u = 0; u < 4; ++u) {
;                 const long row = (long)pm * 256 + (ib * 4 + u) * 16 + wid * 2 + g;
;                 xv[u] = *(const u32x4*)(xold + row * 1024 + pn * 256 + j32 * 8);
;             }
; #pragma unroll
;             for (int u = 0; u < 4; ++u) {
;                 const int rloc = (ib * 4 + u) * 16 + wid * 2 + g;
;                 const long row = (long)pm * 256 + rloc;
;                 const u32x4 a = *(const u32x4*)(lds + rloc * 528 + j32 * 16);
;                 u32x4 w; float ss = 0.f;
; #pragma unroll
;                 for (int e = 0; e < 4; ++e) {
;                     w[e] = pk2(bflo(xv[u][e]) + bflo(a[e]), bfhi(xv[u][e]) + bfhi(a[e]));
;                     const float b0 = bflo(w[e]), b1 = bfhi(w[e]);
;                     ss += b0 * b0 + b1 * b1;
;                 }
;                 *(u32x4*)(xnew + row * 1024 + pn * 256 + j32 * 8) = w;
; #pragma unroll
;                 for (int o = 1; o < 32; o <<= 1) ss += __shfl_xor(ss, o);
;                 if (j32 == 0) ssq[row * 4 + pn] = ss;
	v_cvt_pk_bf16_f32 v33, v34, v35
	v_cvt_pk_bf16_f32 v28, v28, v29
	v_cvt_pk_bf16_f32 v29, v30, v31
	v_cvt_pk_bf16_f32 v24, v24, v25
	v_cvt_pk_bf16_f32 v25, v26, v27
	v_add_u32_e32 v26, 0xc000, v138
	v_cvt_pk_bf16_f32 v20, v20, v21
	v_cvt_pk_bf16_f32 v21, v22, v23
	v_cvt_pk_bf16_f32 v16, v16, v17
	v_cvt_pk_bf16_f32 v17, v18, v19
	v_cvt_pk_bf16_f32 v12, v12, v13
	v_cvt_pk_bf16_f32 v13, v14, v15
	v_cvt_pk_bf16_f32 v8, v8, v9
	v_cvt_pk_bf16_f32 v9, v10, v11
	v_add_u32_e32 v10, 0xe000, v138
	v_cvt_pk_bf16_f32 v4, v4, v5
	v_cvt_pk_bf16_f32 v5, v6, v7
	v_cvt_pk_bf16_f32 v0, v0, v1
	v_cvt_pk_bf16_f32 v1, v2, v3
	ds_write2_b64 v138, v[124:125], v[120:121] offset1:4
	ds_write2_b64 v138, v[116:117], v[112:113] offset0:8 offset1:12
	ds_write2_b64 v106, v[108:109], v[104:105] offset0:32 offset1:36
	ds_write2_b64 v106, v[100:101], v[96:97] offset0:40 offset1:44
	ds_write2_b64 v90, v[92:93], v[88:89] offset0:64 offset1:68
	ds_write2_b64 v90, v[84:85], v[80:81] offset0:72 offset1:76
	ds_write2_b64 v74, v[76:77], v[72:73] offset0:96 offset1:100
	ds_write2_b64 v74, v[68:69], v[64:65] offset0:104 offset1:108
	ds_write2_b64 v58, v[60:61], v[56:57] offset0:128 offset1:132
	ds_write2_b64 v58, v[52:53], v[48:49] offset0:136 offset1:140
	ds_write2_b64 v42, v[44:45], v[40:41] offset0:160 offset1:164
	ds_write2_b64 v42, v[36:37], v[32:33] offset0:168 offset1:172
	ds_write2_b64 v26, v[28:29], v[24:25] offset0:192 offset1:196
	ds_write2_b64 v26, v[20:21], v[16:17] offset0:200 offset1:204
	ds_write2_b64 v10, v[12:13], v[8:9] offset0:224 offset1:228
	ds_write2_b64 v10, v[4:5], v[0:1] offset0:232 offset1:236
	s_waitcnt lgkmcnt(0)
	s_barrier
	v_ashrrev_i32_e32 v0, 5, v137
	v_ashrrev_i32_e32 v1, 5, v136
	v_and_b32_e32 v14, 31, v137
	v_and_b32_e32 v2, -2, v1
	v_ashrrev_i32_e32 v1, 31, v0
	v_ashrrev_i32_e32 v3, 31, v2
	v_lshl_add_u64 v[4:5], s[12:13], 0, v[0:1]
	s_lshl_b32 s16, s6, 8
	v_add_u32_e32 v16, v2, v0
	v_lshlrev_b32_e32 v146, 4, v14
	v_and_b32_e32 v0, 64, v169
	v_lshl_add_u64 v[4:5], v[4:5], 0, v[2:3]
	s_ashr_i32 s17, s16, 31
	v_add_u32_e32 v26, 0, v146
	v_add_u32_e32 v15, 64, v0
	v_cmp_eq_u32_e64 s[4:5], 0, v14
	v_cmp_eq_u32_e64 s[98:99], 16, v14
	s_lshl_b64 s[18:19], s[16:17], 1
	s_add_u32 s22, s68, s18
	s_addc_u32 s23, s69, s19
	v_lshl_add_u64 v[0:1], s[22:23], 0, v[146:147]
	v_lshlrev_b64 v[2:3], 11, v[4:5]
	v_lshl_add_u64 v[18:19], v[0:1], 0, v[2:3]
	flat_load_dwordx4 v[22:25], v[18:19]
	v_add_co_u32_e32 v0, vcc, s49, v18
	v_mul_lo_u32 v20, v16, s3
	s_nop 0
	v_addc_co_u32_e32 v1, vcc, 0, v19, vcc
	flat_load_dwordx4 v[8:11], v[0:1]
	v_add_co_u32_e32 v0, vcc, s48, v18
	v_add_u32_e32 v12, v26, v20
	s_nop 0
	v_addc_co_u32_e32 v1, vcc, 0, v19, vcc
	flat_load_dwordx4 v[4:7], v[0:1]
	v_add_co_u32_e32 v0, vcc, s47, v18
	ds_read_b128 v[28:31], v12
	s_nop 0
	v_addc_co_u32_e32 v1, vcc, 0, v19, vcc
	flat_load_dwordx4 v[0:3], v[0:1]
	v_ashrrev_i32_e32 v17, 31, v16
	s_waitcnt lgkmcnt(0)
	v_lshlrev_b32_e32 v32, 16, v28
	v_and_b32_e32 v33, 0xffff0000, v28
	v_lshlrev_b32_e32 v28, 16, v29
	v_and_b32_e32 v29, 0xffff0000, v29
	s_waitcnt vmcnt(0)
	v_lshlrev_b32_e32 v12, 16, v22
	v_and_b32_e32 v13, 0xffff0000, v22
	v_pk_add_f32 v[12:13], v[12:13], v[32:33]
	s_nop 0
	v_cvt_pk_bf16_f32 v22, v12, v13
	v_and_b32_e32 v13, 0xffff0000, v22
	v_lshlrev_b32_e32 v12, 16, v22
	v_mul_f32_e32 v21, v13, v13
	v_fmac_f32_e32 v21, v12, v12
	v_lshlrev_b32_e32 v12, 16, v23
	v_and_b32_e32 v13, 0xffff0000, v23
	v_pk_add_f32 v[12:13], v[12:13], v[28:29]
	v_lshlrev_b32_e32 v28, 16, v30
	v_cvt_pk_bf16_f32 v23, v12, v13
	v_and_b32_e32 v13, 0xffff0000, v23
	v_lshlrev_b32_e32 v12, 16, v23
	v_mul_f32_e32 v13, v13, v13
	v_fmac_f32_e32 v13, v12, v12
	v_add_f32_e32 v21, v21, v13
	v_lshlrev_b32_e32 v12, 16, v24
	v_and_b32_e32 v13, 0xffff0000, v24
	v_and_b32_e32 v29, 0xffff0000, v30
	v_pk_add_f32 v[12:13], v[12:13], v[28:29]
	v_lshlrev_b32_e32 v28, 16, v31
	v_cvt_pk_bf16_f32 v24, v12, v13
	v_and_b32_e32 v13, 0xffff0000, v24
	v_lshlrev_b32_e32 v12, 16, v24
	v_mul_f32_e32 v13, v13, v13
	v_fmac_f32_e32 v13, v12, v12
	v_add_f32_e32 v21, v13, v21
	v_lshlrev_b32_e32 v12, 16, v25
	v_and_b32_e32 v13, 0xffff0000, v25
	v_and_b32_e32 v29, 0xffff0000, v31
	v_pk_add_f32 v[12:13], v[12:13], v[28:29]
	s_nop 0
	v_cvt_pk_bf16_f32 v25, v12, v13
	v_and_b32_e32 v13, 0xffff0000, v25
	v_lshlrev_b32_e32 v12, 16, v25
	v_mul_f32_e32 v13, v13, v13
	v_fmac_f32_e32 v13, v12, v12
	v_add_f32_e32 v21, v13, v21
	v_lshl_add_u64 v[12:13], s[12:13], 0, v[16:17]
	v_lshlrev_b64 v[28:29], 11, v[12:13]
	v_xor_b32_e32 v17, 1, v169
	v_lshl_add_u64 v[28:29], s[10:11], 0, v[28:29]
	v_cmp_lt_i32_e32 vcc, v17, v15
	v_lshl_add_u64 v[28:29], v[28:29], 0, s[18:19]
	v_lshl_add_u64 v[28:29], v[28:29], 0, v[146:147]
	v_cndmask_b32_e32 v17, v169, v17, vcc
	v_lshlrev_b32_e32 v17, 2, v17
	flat_store_dwordx4 v[28:29], v[22:25]
	s_nop 1
	v_add_f32_dpp v86, v21, v21 quad_perm:[1,0,3,2] row_mask:0xf bank_mask:0xf
	s_nop 1
	v_add_f32_dpp v86, v86, v86 quad_perm:[2,3,0,1] row_mask:0xf bank_mask:0xf
	s_nop 1
	v_add_f32_dpp v86, v86, v86 row_half_mirror row_mask:0xf bank_mask:0xf
	s_nop 1
	v_add_f32_dpp v86, v86, v86 row_mirror row_mask:0xf bank_mask:0xf
	s_nop 1
	v_add_f32_dpp v86, v86, v86 row_bcast:15 row_mask:0xa bank_mask:0xf
	s_waitcnt lgkmcnt(0)
	v_xor_b32_e32 v22, 2, v169
	v_cmp_lt_i32_e32 vcc, v22, v15
	s_nop 1
	v_cndmask_b32_e32 v22, v169, v22, vcc
	v_lshlrev_b32_e32 v22, 2, v22
	s_waitcnt lgkmcnt(0)
	v_xor_b32_e32 v23, 4, v169
	v_cmp_lt_i32_e32 vcc, v23, v15
	s_nop 1
	v_cndmask_b32_e32 v23, v169, v23, vcc
	v_lshlrev_b32_e32 v23, 2, v23
	s_waitcnt lgkmcnt(0)
	v_xor_b32_e32 v24, 8, v169
	v_cmp_lt_i32_e32 vcc, v24, v15
	s_nop 1
	v_cndmask_b32_e32 v24, v169, v24, vcc
	v_lshlrev_b32_e32 v24, 2, v24
	s_waitcnt lgkmcnt(0)
	v_xor_b32_e32 v25, 16, v169
	v_cmp_lt_i32_e32 vcc, v25, v15
	s_nop 1
	v_cndmask_b32_e32 v15, v169, v25, vcc
	v_lshlrev_b32_e32 v25, 2, v15
	s_and_saveexec_b64 s[18:19], s[98:99]
	s_cbranch_execz .LBB0_778
	v_lshl_add_u64 v[12:13], v[12:13], 4, s[78:79]
	v_lshl_add_u64 v[12:13], s[6:7], 2, v[12:13]
	s_waitcnt lgkmcnt(0)
	v_mov_b32_e32 v15, v86
	flat_store_dword v[12:13], v15
